# v33 + K-loop back edge: counter/pointer SALU and s_cmp hoisted above the closing barrier
# speedup vs baseline: 1.0011x; 1.0011x over previous
; #define PG8_STAGE(bufoff, gbase, voff) do { _Pragma("unroll") for (int _i = 0; _i < 2; ++_i) \
;         __builtin_amdgcn_global_load_lds((const unsigned*)((const char*)(gbase) + (voff)[_i]), (PG8_LAS unsigned*)(lds + (bufoff) + ldsw + _i * 8192), 16, 0, 0); } while (0)
; #define PG8_LDA(dst, b, h) do { _Pragma("unroll") for (int m = 0; m < 4; ++m) _Pragma("unroll") for (int k = 0; k < 2; ++k) dst[m][k] = *(const PG8_LAS bf16x8*)(lds + PG8_SA(b, h) + aoff + m * 2048 + k * 1024); } while (0)
; #define PG8_WAIT_V(n) asm volatile("s_waitcnt vmcnt(" #n ")" ::: "memory")
; #define PG8_WAIT_L(n) asm volatile("s_waitcnt lgkmcnt(" #n ")" ::: "memory")
; #define PG8_BAR __builtin_amdgcn_s_barrier()
; template <class Epi, class Sched, bool ALIGN_EPI = false, bool SP2 = false, bool AGM = false  >
; __device__ __forceinline__ void gemm_phase(PG8_LAS unsigned char* lds, const Gemm g, const Sched& S, const Epi& E) {
;     ...
;         const bool has_next = S.next(ui + 1, nxt);
;         const char* nA = has_next ? (const char*)g.A + (size_t)nxt.pm * tstepA : cA; const char* nB = has_next ? (const char*)g.Bt + (size_t)nxt.pn * tstep : cB;
;         for (int t = 0; t < nt; t += 2) {
;             const bool last = (t == nt - 2);
;             const char* a1 = cA + (size_t)(t + 1) * kstepA;
;             const char* a2 = last ? nA : cA + (size_t)(t + 2) * kstepA; const char* b2 = last ? nB : cB + (size_t)(t + 2) * kstep;
;             const char* a3 = a2 + kstepA; const char* b3 = b2 + kstep;
;             if (last && has_next) S.a_ready(nxt);
;             if constexpr (SP2) {
;             PG8_LDB(B0, 0, 0); PG8_LDB(B1, 0, 1); PG8_SCHED; PG8_LDA(At, 0, 0); PG8_STAGE(PG8_SA(1, 1), a1 + hstepA, voffA);
;             PG8_WAIT_V(8); PG8_WAIT_L(0); PG8_BAR; PG8_MMA(0, 0, At, B0); PG8_MMA(0, 1, At, B1); PG8_BAR; PG8_SCHED;
;             PG8_LDA(At, 0, 1); PG8_STAGE(PG8_SB(0, 0), b2, voffB); PG8_STAGE(PG8_SB(0, 1), b2 + hstep, voffB); PG8_STAGE(PG8_SA(0, 0), a2, voffA);
;             PG8_WAIT_V(8); PG8_WAIT_L(0); PG8_BAR; PG8_MMA(1, 0, At, B0); PG8_MMA(1, 1, At, B1); PG8_BAR; PG8_SCHED;
;     ...
; #pragma unroll
;         for (int a = 0; a < 2; ++a)
; #pragma unroll
;             for (int b = 0; b < 2; ++b)
; #pragma unroll
;                 for (int m = 0; m < 4; ++m)
; #pragma unroll
;                     for (int n = 0; n < 2; ++n) acc[a][b][m][n] = (f32x4){0.f, 0.f, 0.f, 0.f};
.LBB0_136:
	s_ashr_i32 s15, s14, 31
	s_lshl_b64 s[16:17], s[14:15], 19
	s_add_u32 s16, s46, s16
	s_addc_u32 s17, s47, s17
	s_and_b64 s[18:19], s[0:1], exec
	s_cselect_b32 s15, s17, s23
	s_cselect_b32 s21, s16, s22
	s_ashr_i32 s13, s12, 31
	s_lshl_b64 s[18:19], s[12:13], 19
	s_add_u32 s18, s3, s18
	s_addc_u32 s19, s28, s19
	s_and_b64 s[26:27], s[0:1], exec
	s_cselect_b32 s13, s19, s25
	s_cselect_b32 s45, s18, s24
	s_add_u32 s22, s22, 0x40080
	s_addc_u32 s23, s23, 0
	s_add_u32 s53, s24, 0x100
	s_addc_u32 s54, s25, 0
	s_mov_b32 s55, -2
	ds_read_b128 v[150:153], v160
	ds_read_b128 v[164:167], v160 offset:1024
	ds_read_b128 v[168:171], v160 offset:2048
	ds_read_b128 v[172:175], v160 offset:3072
	ds_read_b128 v[176:179], v161
	ds_read_b128 v[180:183], v161 offset:1024
	ds_read_b128 v[184:187], v161 offset:2048
	ds_read_b128 v[188:191], v161 offset:3072
	s_add_u32 s24, s22, 0xfffc0080
	s_addc_u32 s25, s23, -1
	s_cmp_eq_u32 s55, 12
	s_cselect_b32 s27, s15, s25
	s_cselect_b32 s26, s21, s24
	s_cselect_b32 s25, s13, s54
	s_cselect_b32 s24, s45, s53
	v_lshl_add_u64 v[224:225], s[22:23], 0, v[142:143]
	s_add_i32 m0, s33, 0xc000
	ds_read_b128 v[192:195], v162
	ds_read_b128 v[196:199], v162 offset:1024
	ds_read_b128 v[200:203], v162 offset:2048
	ds_read_b128 v[204:207], v162 offset:3072
	ds_read_b128 v[208:211], v162 offset:4096
	ds_read_b128 v[212:215], v162 offset:5120
	ds_read_b128 v[216:219], v162 offset:6144
	ds_read_b128 v[220:223], v162 offset:7168
	global_load_lds_dwordx4 v[224:225], off
	v_lshl_add_u64 v[224:225], s[22:23], 0, v[144:145]
	s_add_i32 m0, s33, 0xe000
	s_nop 0
	global_load_lds_dwordx4 v[224:225], off
	s_waitcnt vmcnt(8)
	s_waitcnt lgkmcnt(0)
	s_barrier
	s_setprio 1
	s_waitcnt lgkmcnt(0)
	v_mfma_f32_16x16x32_bf16 v[126:129], v[150:153], v[192:195], 0
	v_mfma_f32_16x16x32_bf16 v[122:125], v[168:171], v[192:195], 0
	v_mfma_f32_16x16x32_bf16 v[114:117], v[150:153], v[200:203], 0
	v_mfma_f32_16x16x32_bf16 v[106:109], v[168:171], v[200:203], 0
	v_mfma_f32_16x16x32_bf16 v[102:105], v[150:153], v[208:211], 0
	v_mfma_f32_16x16x32_bf16 v[94:97], v[168:171], v[208:211], 0
	v_mfma_f32_16x16x32_bf16 v[86:89], v[150:153], v[216:219], 0
	v_mfma_f32_16x16x32_bf16 v[78:81], v[168:171], v[216:219], 0
	v_mfma_f32_16x16x32_bf16 v[126:129], v[164:167], v[196:199], v[126:129]
	v_mfma_f32_16x16x32_bf16 v[122:125], v[172:175], v[196:199], v[122:125]
	v_mfma_f32_16x16x32_bf16 v[114:117], v[164:167], v[204:207], v[114:117]
	v_mfma_f32_16x16x32_bf16 v[106:109], v[172:175], v[204:207], v[106:109]
	v_mfma_f32_16x16x32_bf16 v[102:105], v[164:167], v[212:215], v[102:105]
	v_mfma_f32_16x16x32_bf16 v[94:97], v[172:175], v[212:215], v[94:97]
	v_mfma_f32_16x16x32_bf16 v[86:89], v[164:167], v[220:223], v[86:89]
	v_mfma_f32_16x16x32_bf16 v[78:81], v[172:175], v[220:223], v[78:81]
	s_setprio 0
	s_setprio 1
	v_mfma_f32_16x16x32_bf16 v[118:121], v[176:179], v[192:195], 0
	v_mfma_f32_16x16x32_bf16 v[110:113], v[184:187], v[192:195], 0
	v_mfma_f32_16x16x32_bf16 v[98:101], v[176:179], v[200:203], 0
	v_mfma_f32_16x16x32_bf16 v[90:93], v[184:187], v[200:203], 0
	v_mfma_f32_16x16x32_bf16 v[82:85], v[176:179], v[208:211], 0
	v_mfma_f32_16x16x32_bf16 v[74:77], v[184:187], v[208:211], 0
	v_mfma_f32_16x16x32_bf16 v[70:73], v[176:179], v[216:219], 0
	v_mfma_f32_16x16x32_bf16 v[66:69], v[184:187], v[216:219], 0
	v_mfma_f32_16x16x32_bf16 v[118:121], v[180:183], v[196:199], v[118:121]
	v_mfma_f32_16x16x32_bf16 v[110:113], v[188:191], v[196:199], v[110:113]
	v_mfma_f32_16x16x32_bf16 v[98:101], v[180:183], v[204:207], v[98:101]
	v_mfma_f32_16x16x32_bf16 v[90:93], v[188:191], v[204:207], v[90:93]
	v_mfma_f32_16x16x32_bf16 v[82:85], v[180:183], v[212:215], v[82:85]
	v_mfma_f32_16x16x32_bf16 v[74:77], v[188:191], v[212:215], v[74:77]
	v_mfma_f32_16x16x32_bf16 v[70:73], v[180:183], v[220:223], v[70:73]
	v_mfma_f32_16x16x32_bf16 v[66:69], v[188:191], v[220:223], v[66:69]
	s_setprio 0
	s_barrier
	s_add_i32 s58, s41, s29
	v_lshl_add_u64 v[224:225], s[24:25], 0, v[134:135]
	s_mov_b32 m0, s58
	ds_read_b128 v[192:195], v162 offset:16384
	ds_read_b128 v[196:199], v162 offset:17408
	ds_read_b128 v[200:203], v162 offset:18432
	ds_read_b128 v[204:207], v162 offset:19456
	ds_read_b128 v[208:211], v162 offset:20480
	ds_read_b128 v[212:215], v162 offset:21504
	ds_read_b128 v[216:219], v162 offset:22528
	ds_read_b128 v[220:223], v162 offset:23552
	global_load_lds_dwordx4 v[224:225], off
	s_add_i32 m0, s58, 0x2000
	s_add_u32 s58, s24, 0x40000
	v_lshl_add_u64 v[226:227], s[24:25], 0, v[130:131]
	s_addc_u32 s59, s25, 0
	s_add_i32 s60, s42, s29
	global_load_lds_dwordx4 v[226:227], off
	v_lshl_add_u64 v[228:229], s[58:59], 0, v[134:135]
	s_mov_b32 m0, s60
	v_lshl_add_u64 v[230:231], s[26:27], 0, v[132:133]
	global_load_lds_dwordx4 v[228:229], off
	v_lshl_add_u64 v[228:229], s[58:59], 0, v[130:131]
	s_add_i32 m0, s60, 0x2000
	s_nop 0
	global_load_lds_dwordx4 v[228:229], off
	v_lshl_add_u64 v[228:229], s[26:27], 0, v[136:137]
	s_mov_b32 m0, s33
	s_nop 0
	global_load_lds_dwordx4 v[228:229], off
	s_mov_b32 m0, s34
	s_nop 0
	global_load_lds_dwordx4 v[230:231], off
	s_waitcnt vmcnt(8)
	s_waitcnt lgkmcnt(0)
	s_barrier
; #define PG8_STAGE(bufoff, gbase, voff) do { _Pragma("unroll") for (int _i = 0; _i < 2; ++_i) \
;         __builtin_amdgcn_global_load_lds((const unsigned*)((const char*)(gbase) + (voff)[_i]), (PG8_LAS unsigned*)(lds + (bufoff) + ldsw + _i * 8192), 16, 0, 0); } while (0)
; #define PG8_LDA(dst, b, h) do { _Pragma("unroll") for (int m = 0; m < 4; ++m) _Pragma("unroll") for (int k = 0; k < 2; ++k) dst[m][k] = *(const PG8_LAS bf16x8*)(lds + PG8_SA(b, h) + aoff + m * 2048 + k * 1024); } while (0)
; #define PG8_LDB(dst, b, h) do { _Pragma("unroll") for (int n = 0; n < 2; ++n) _Pragma("unroll") for (int k = 0; k < 2; ++k) dst[n][k] = *(const PG8_LAS bf16x8*)(lds + PG8_SB(b, h) + boff + n * 2048 + k * 1024); } while (0)
; #define PG8_MMA(ai, bj, At, Bt) do { __builtin_amdgcn_s_setprio(1); _Pragma("unroll") for (int m = 0; m < 4; ++m) _Pragma("unroll") for (int n = 0; n < 2; ++n) _Pragma("unroll") for (int k = 0; k < 2; ++k) \
;         acc[ai][bj][m][n] = __builtin_amdgcn_mfma_f32_16x16x32_bf16(Bt[n][k], At[m][k], acc[ai][bj][m][n], 0, 0, 0); __builtin_amdgcn_s_setprio(0); } while (0)
; #define PG8_WAIT_V(n) asm volatile("s_waitcnt vmcnt(" #n ")" ::: "memory")
; #define PG8_WAIT_L(n) asm volatile("s_waitcnt lgkmcnt(" #n ")" ::: "memory")
; #define PG8_BAR __builtin_amdgcn_s_barrier()
; #define PG8_SCHED __builtin_amdgcn_sched_barrier(0)
; template <class Epi, class Sched, bool ALIGN_EPI = false, bool SP2 = false, bool AGM = false  >
; __device__ __forceinline__ void gemm_phase(PG8_LAS unsigned char* lds, const Gemm g, const Sched& S, const Epi& E) {
;     ...
;             PG8_WAIT_V(8); PG8_WAIT_L(0); PG8_BAR; PG8_MMA(1, 0, At, B0); PG8_MMA(1, 1, At, B1); PG8_BAR; PG8_SCHED;
;             PG8_LDB(B0, 1, 0); PG8_LDB(B1, 1, 1); PG8_SCHED; PG8_LDA(At, 1, 0); PG8_STAGE(PG8_SA(0, 1), a2 + hstepA, voffA);
;             PG8_WAIT_V(8); PG8_WAIT_L(0); PG8_BAR; PG8_MMA(0, 0, At, B0); PG8_MMA(0, 1, At, B1); PG8_BAR; PG8_SCHED;
	s_setprio 1
	s_waitcnt lgkmcnt(0)
	v_mfma_f32_16x16x32_bf16 v[62:65], v[150:153], v[192:195], 0
	v_mfma_f32_16x16x32_bf16 v[58:61], v[168:171], v[192:195], 0
	v_mfma_f32_16x16x32_bf16 v[54:57], v[150:153], v[200:203], 0
	v_mfma_f32_16x16x32_bf16 v[46:49], v[168:171], v[200:203], 0
	v_mfma_f32_16x16x32_bf16 v[38:41], v[150:153], v[208:211], 0
	v_mfma_f32_16x16x32_bf16 v[30:33], v[168:171], v[208:211], 0
	v_mfma_f32_16x16x32_bf16 v[22:25], v[150:153], v[216:219], 0
	v_mfma_f32_16x16x32_bf16 v[14:17], v[168:171], v[216:219], 0
	v_mfma_f32_16x16x32_bf16 v[62:65], v[164:167], v[196:199], v[62:65]
	v_mfma_f32_16x16x32_bf16 v[58:61], v[172:175], v[196:199], v[58:61]
	v_mfma_f32_16x16x32_bf16 v[54:57], v[164:167], v[204:207], v[54:57]
	v_mfma_f32_16x16x32_bf16 v[46:49], v[172:175], v[204:207], v[46:49]
	v_mfma_f32_16x16x32_bf16 v[38:41], v[164:167], v[212:215], v[38:41]
	v_mfma_f32_16x16x32_bf16 v[30:33], v[172:175], v[212:215], v[30:33]
	v_mfma_f32_16x16x32_bf16 v[22:25], v[164:167], v[220:223], v[22:25]
	v_mfma_f32_16x16x32_bf16 v[14:17], v[172:175], v[220:223], v[14:17]
	s_setprio 0
	s_setprio 1
	v_mfma_f32_16x16x32_bf16 v[50:53], v[176:179], v[192:195], 0
	v_mfma_f32_16x16x32_bf16 v[42:45], v[184:187], v[192:195], 0
	v_mfma_f32_16x16x32_bf16 v[34:37], v[176:179], v[200:203], 0
	v_mfma_f32_16x16x32_bf16 v[26:29], v[184:187], v[200:203], 0
	v_mfma_f32_16x16x32_bf16 v[18:21], v[176:179], v[208:211], 0
	v_mfma_f32_16x16x32_bf16 v[10:13], v[184:187], v[208:211], 0
	v_mfma_f32_16x16x32_bf16 v[6:9], v[176:179], v[216:219], 0
	v_mfma_f32_16x16x32_bf16 v[2:5], v[184:187], v[216:219], 0
	v_mfma_f32_16x16x32_bf16 v[50:53], v[180:183], v[196:199], v[50:53]
	v_mfma_f32_16x16x32_bf16 v[42:45], v[188:191], v[196:199], v[42:45]
	v_mfma_f32_16x16x32_bf16 v[34:37], v[180:183], v[204:207], v[34:37]
	v_mfma_f32_16x16x32_bf16 v[26:29], v[188:191], v[204:207], v[26:29]
	v_mfma_f32_16x16x32_bf16 v[18:21], v[180:183], v[212:215], v[18:21]
	v_mfma_f32_16x16x32_bf16 v[10:13], v[188:191], v[212:215], v[10:13]
	v_mfma_f32_16x16x32_bf16 v[6:9], v[180:183], v[220:223], v[6:9]
	v_mfma_f32_16x16x32_bf16 v[2:5], v[188:191], v[220:223], v[2:5]
	s_setprio 0
	s_barrier
	s_add_i32 s58, 0, 0x18000
	v_add_u32_e32 v138, s58, v157
	s_add_i32 s59, 0, 0x1c000
	ds_read_b128 v[150:153], v138
	ds_read_b128 v[164:167], v138 offset:1024
	ds_read_b128 v[168:171], v138 offset:2048
	ds_read_b128 v[172:175], v138 offset:3072
	v_add_u32_e32 v138, s59, v157
	ds_read_b128 v[176:179], v138
	ds_read_b128 v[180:183], v138 offset:1024
	ds_read_b128 v[184:187], v138 offset:2048
	ds_read_b128 v[188:191], v138 offset:3072
	s_add_u32 s26, s26, 0x40000
	s_addc_u32 s27, s27, 0
	s_mov_b32 m0, s35
	v_lshl_add_u64 v[232:233], s[26:27], 0, v[136:137]
	ds_read_b128 v[192:195], v162 offset:32768
	ds_read_b128 v[196:199], v162 offset:33792
	ds_read_b128 v[200:203], v162 offset:34816
	ds_read_b128 v[204:207], v162 offset:35840
	ds_read_b128 v[208:211], v162 offset:36864
	ds_read_b128 v[212:215], v162 offset:37888
	ds_read_b128 v[216:219], v162 offset:38912
	ds_read_b128 v[220:223], v162 offset:39936
	global_load_lds_dwordx4 v[232:233], off
	v_lshl_add_u64 v[232:233], s[26:27], 0, v[132:133]
	s_mov_b32 m0, s36
	s_nop 0
	global_load_lds_dwordx4 v[232:233], off
	s_waitcnt vmcnt(8)
	s_waitcnt lgkmcnt(0)
	s_barrier
	s_setprio 1
	s_waitcnt lgkmcnt(0)
	v_mfma_f32_16x16x32_bf16 v[126:129], v[150:153], v[192:195], v[126:129]
	v_mfma_f32_16x16x32_bf16 v[122:125], v[168:171], v[192:195], v[122:125]
	v_mfma_f32_16x16x32_bf16 v[114:117], v[150:153], v[200:203], v[114:117]
	v_mfma_f32_16x16x32_bf16 v[106:109], v[168:171], v[200:203], v[106:109]
	v_mfma_f32_16x16x32_bf16 v[102:105], v[150:153], v[208:211], v[102:105]
	v_mfma_f32_16x16x32_bf16 v[94:97], v[168:171], v[208:211], v[94:97]
	v_mfma_f32_16x16x32_bf16 v[86:89], v[150:153], v[216:219], v[86:89]
	v_mfma_f32_16x16x32_bf16 v[78:81], v[168:171], v[216:219], v[78:81]
	v_mfma_f32_16x16x32_bf16 v[126:129], v[164:167], v[196:199], v[126:129]
	v_mfma_f32_16x16x32_bf16 v[122:125], v[172:175], v[196:199], v[122:125]
	v_mfma_f32_16x16x32_bf16 v[114:117], v[164:167], v[204:207], v[114:117]
	v_mfma_f32_16x16x32_bf16 v[106:109], v[172:175], v[204:207], v[106:109]
	v_mfma_f32_16x16x32_bf16 v[102:105], v[164:167], v[212:215], v[102:105]
	v_mfma_f32_16x16x32_bf16 v[94:97], v[172:175], v[212:215], v[94:97]
	v_mfma_f32_16x16x32_bf16 v[86:89], v[164:167], v[220:223], v[86:89]
	v_mfma_f32_16x16x32_bf16 v[78:81], v[172:175], v[220:223], v[78:81]
	s_setprio 0
	s_setprio 1
	v_mfma_f32_16x16x32_bf16 v[118:121], v[176:179], v[192:195], v[118:121]
	v_mfma_f32_16x16x32_bf16 v[110:113], v[184:187], v[192:195], v[110:113]
	v_mfma_f32_16x16x32_bf16 v[98:101], v[176:179], v[200:203], v[98:101]
	v_mfma_f32_16x16x32_bf16 v[90:93], v[184:187], v[200:203], v[90:93]
	v_mfma_f32_16x16x32_bf16 v[82:85], v[176:179], v[208:211], v[82:85]
	v_mfma_f32_16x16x32_bf16 v[74:77], v[184:187], v[208:211], v[74:77]
	v_mfma_f32_16x16x32_bf16 v[70:73], v[176:179], v[216:219], v[70:73]
	v_mfma_f32_16x16x32_bf16 v[66:69], v[184:187], v[216:219], v[66:69]
	v_mfma_f32_16x16x32_bf16 v[118:121], v[180:183], v[196:199], v[118:121]
	v_mfma_f32_16x16x32_bf16 v[110:113], v[188:191], v[196:199], v[110:113]
	v_mfma_f32_16x16x32_bf16 v[98:101], v[180:183], v[204:207], v[98:101]
	v_mfma_f32_16x16x32_bf16 v[90:93], v[188:191], v[204:207], v[90:93]
	v_mfma_f32_16x16x32_bf16 v[82:85], v[180:183], v[212:215], v[82:85]
	v_mfma_f32_16x16x32_bf16 v[74:77], v[188:191], v[212:215], v[74:77]
	v_mfma_f32_16x16x32_bf16 v[70:73], v[180:183], v[220:223], v[70:73]
	v_mfma_f32_16x16x32_bf16 v[66:69], v[188:191], v[220:223], v[66:69]
	s_setprio 0
	s_barrier
; #define PG8_STAGE(bufoff, gbase, voff) do { _Pragma("unroll") for (int _i = 0; _i < 2; ++_i) \
;         __builtin_amdgcn_global_load_lds((const unsigned*)((const char*)(gbase) + (voff)[_i]), (PG8_LAS unsigned*)(lds + (bufoff) + ldsw + _i * 8192), 16, 0, 0); } while (0)
; #define PG8_LDA(dst, b, h) do { _Pragma("unroll") for (int m = 0; m < 4; ++m) _Pragma("unroll") for (int k = 0; k < 2; ++k) dst[m][k] = *(const PG8_LAS bf16x8*)(lds + PG8_SA(b, h) + aoff + m * 2048 + k * 1024); } while (0)
; #define PG8_LDB(dst, b, h) do { _Pragma("unroll") for (int n = 0; n < 2; ++n) _Pragma("unroll") for (int k = 0; k < 2; ++k) dst[n][k] = *(const PG8_LAS bf16x8*)(lds + PG8_SB(b, h) + boff + n * 2048 + k * 1024); } while (0)
; #define PG8_MMA(ai, bj, At, Bt) do { __builtin_amdgcn_s_setprio(1); _Pragma("unroll") for (int m = 0; m < 4; ++m) _Pragma("unroll") for (int n = 0; n < 2; ++n) _Pragma("unroll") for (int k = 0; k < 2; ++k) \
;         acc[ai][bj][m][n] = __builtin_amdgcn_mfma_f32_16x16x32_bf16(Bt[n][k], At[m][k], acc[ai][bj][m][n], 0, 0, 0); __builtin_amdgcn_s_setprio(0); } while (0)
; #define PG8_WAIT_V(n) asm volatile("s_waitcnt vmcnt(" #n ")" ::: "memory")
; #define PG8_BAR __builtin_amdgcn_s_barrier()
; template <class Epi, class Sched, bool ALIGN_EPI = false, bool SP2 = false, bool AGM = false  >
; __device__ __forceinline__ void gemm_phase(PG8_LAS unsigned char* lds, const Gemm g, const Sched& S, const Epi& E) {
;     ...
;         for (int t = 0; t < nt; t += 2) {
;             const bool last = (t == nt - 2);
;             const char* a1 = cA + (size_t)(t + 1) * kstepA;
;             const char* a2 = last ? nA : cA + (size_t)(t + 2) * kstepA; const char* b2 = last ? nB : cB + (size_t)(t + 2) * kstep;
;             const char* a3 = a2 + kstepA; const char* b3 = b2 + kstep;
;             if (last && has_next) S.a_ready(nxt);
;             if constexpr (SP2) {
;             PG8_LDB(B0, 0, 0); PG8_LDB(B1, 0, 1); PG8_SCHED; PG8_LDA(At, 0, 0); PG8_STAGE(PG8_SA(1, 1), a1 + hstepA, voffA);
;             PG8_WAIT_V(8); PG8_WAIT_L(0); PG8_BAR; PG8_MMA(0, 0, At, B0); PG8_MMA(0, 1, At, B1); PG8_BAR; PG8_SCHED;
;     ...
;             PG8_LDA(At, 1, 1); PG8_STAGE(PG8_SB(1, 0), b3, voffB); PG8_STAGE(PG8_SB(1, 1), b3 + hstep, voffB); PG8_STAGE(PG8_SA(1, 0), a3, voffA);
;             PG8_WAIT_V(8); PG8_WAIT_L(0); PG8_BAR; PG8_MMA(1, 0, At, B0); PG8_MMA(1, 1, At, B1); PG8_BAR; PG8_SCHED;
	s_add_i32 s26, s58, s29
	v_lshl_add_u64 v[224:225], v[224:225], 0, s[10:11]
	s_mov_b32 m0, s26
	ds_read_b128 v[192:195], v162 offset:49152
	ds_read_b128 v[196:199], v162 offset:50176
	ds_read_b128 v[200:203], v162 offset:51200
	ds_read_b128 v[204:207], v162 offset:52224
	ds_read_b128 v[208:211], v162 offset:53248
	ds_read_b128 v[212:215], v162 offset:54272
	ds_read_b128 v[216:219], v162 offset:55296
	ds_read_b128 v[220:223], v162 offset:56320
	global_load_lds_dwordx4 v[224:225], off
	s_add_i32 m0, s26, 0x2000
	s_add_u32 s24, s24, 0x40080
	v_lshl_add_u64 v[224:225], v[226:227], 0, s[10:11]
	s_addc_u32 s25, s25, 0
	s_add_i32 s26, s59, s29
	global_load_lds_dwordx4 v[224:225], off
	v_lshl_add_u64 v[224:225], s[24:25], 0, v[134:135]
	s_mov_b32 m0, s26
	s_nop 0
	global_load_lds_dwordx4 v[224:225], off
	v_lshl_add_u64 v[224:225], s[24:25], 0, v[130:131]
	s_add_i32 m0, s26, 0x2000
	s_nop 0
	global_load_lds_dwordx4 v[224:225], off
	v_lshl_add_u64 v[224:225], v[228:229], 0, s[10:11]
	s_mov_b32 m0, s38
	s_nop 0
	global_load_lds_dwordx4 v[224:225], off
	v_lshl_add_u64 v[224:225], v[230:231], 0, s[10:11]
	s_mov_b32 m0, s39
	s_nop 0
	global_load_lds_dwordx4 v[224:225], off
	s_waitcnt vmcnt(8)
	s_waitcnt lgkmcnt(0)
	s_barrier
	s_setprio 1
	s_waitcnt lgkmcnt(0)
	v_mfma_f32_16x16x32_bf16 v[62:65], v[150:153], v[192:195], v[62:65]
	v_mfma_f32_16x16x32_bf16 v[58:61], v[168:171], v[192:195], v[58:61]
	v_mfma_f32_16x16x32_bf16 v[54:57], v[150:153], v[200:203], v[54:57]
	v_mfma_f32_16x16x32_bf16 v[46:49], v[168:171], v[200:203], v[46:49]
	v_mfma_f32_16x16x32_bf16 v[38:41], v[150:153], v[208:211], v[38:41]
	v_mfma_f32_16x16x32_bf16 v[30:33], v[168:171], v[208:211], v[30:33]
	v_mfma_f32_16x16x32_bf16 v[22:25], v[150:153], v[216:219], v[22:25]
	v_mfma_f32_16x16x32_bf16 v[14:17], v[168:171], v[216:219], v[14:17]
	v_mfma_f32_16x16x32_bf16 v[62:65], v[164:167], v[196:199], v[62:65]
	v_mfma_f32_16x16x32_bf16 v[58:61], v[172:175], v[196:199], v[58:61]
	v_mfma_f32_16x16x32_bf16 v[54:57], v[164:167], v[204:207], v[54:57]
	v_mfma_f32_16x16x32_bf16 v[46:49], v[172:175], v[204:207], v[46:49]
	v_mfma_f32_16x16x32_bf16 v[38:41], v[164:167], v[212:215], v[38:41]
	v_mfma_f32_16x16x32_bf16 v[30:33], v[172:175], v[212:215], v[30:33]
	v_mfma_f32_16x16x32_bf16 v[22:25], v[164:167], v[220:223], v[22:25]
	v_mfma_f32_16x16x32_bf16 v[14:17], v[172:175], v[220:223], v[14:17]
	s_setprio 0
	s_setprio 1
	v_mfma_f32_16x16x32_bf16 v[50:53], v[176:179], v[192:195], v[50:53]
	v_mfma_f32_16x16x32_bf16 v[42:45], v[184:187], v[192:195], v[42:45]
	v_mfma_f32_16x16x32_bf16 v[34:37], v[176:179], v[200:203], v[34:37]
	v_mfma_f32_16x16x32_bf16 v[26:29], v[184:187], v[200:203], v[26:29]
	v_mfma_f32_16x16x32_bf16 v[18:21], v[176:179], v[208:211], v[18:21]
	v_mfma_f32_16x16x32_bf16 v[10:13], v[184:187], v[208:211], v[10:13]
	v_mfma_f32_16x16x32_bf16 v[6:9], v[176:179], v[216:219], v[6:9]
	v_mfma_f32_16x16x32_bf16 v[2:5], v[184:187], v[216:219], v[2:5]
	v_mfma_f32_16x16x32_bf16 v[50:53], v[180:183], v[196:199], v[50:53]
	v_mfma_f32_16x16x32_bf16 v[42:45], v[188:191], v[196:199], v[42:45]
	v_mfma_f32_16x16x32_bf16 v[34:37], v[180:183], v[204:207], v[34:37]
	v_mfma_f32_16x16x32_bf16 v[26:29], v[188:191], v[204:207], v[26:29]
	v_mfma_f32_16x16x32_bf16 v[18:21], v[180:183], v[212:215], v[18:21]
	v_mfma_f32_16x16x32_bf16 v[10:13], v[188:191], v[212:215], v[10:13]
	v_mfma_f32_16x16x32_bf16 v[6:9], v[180:183], v[220:223], v[6:9]
	v_mfma_f32_16x16x32_bf16 v[2:5], v[188:191], v[220:223], v[2:5]
	s_add_i32 s55, s55, 2
	s_add_u32 s22, s22, 0x100
	s_addc_u32 s23, s23, 0
	s_add_u32 s53, s53, 0x100
	s_addc_u32 s54, s54, 0
	s_cmp_gt_u32 s55, 13
	s_setprio 0
	s_barrier
	s_cbranch_scc1 .Lpeel_done_p1
	.p2align	6
.LBB0_137:
	ds_read_b128 v[150:153], v160
	ds_read_b128 v[164:167], v160 offset:1024
	ds_read_b128 v[168:171], v160 offset:2048
	ds_read_b128 v[172:175], v160 offset:3072
	ds_read_b128 v[176:179], v161
	ds_read_b128 v[180:183], v161 offset:1024
	ds_read_b128 v[184:187], v161 offset:2048
	ds_read_b128 v[188:191], v161 offset:3072
	s_add_u32 s24, s22, 0xfffc0080
	s_addc_u32 s25, s23, -1
	s_cmp_eq_u32 s55, 12
	s_cselect_b32 s27, s15, s25
	s_cselect_b32 s26, s21, s24
	s_cselect_b32 s25, s13, s54
	s_cselect_b32 s24, s45, s53
	v_lshl_add_u64 v[224:225], s[22:23], 0, v[142:143]
	s_add_i32 m0, s33, 0xc000
	ds_read_b128 v[192:195], v162
	ds_read_b128 v[196:199], v162 offset:1024
	ds_read_b128 v[200:203], v162 offset:2048
	ds_read_b128 v[204:207], v162 offset:3072
	ds_read_b128 v[208:211], v162 offset:4096
	ds_read_b128 v[212:215], v162 offset:5120
	ds_read_b128 v[216:219], v162 offset:6144
	ds_read_b128 v[220:223], v162 offset:7168
	global_load_lds_dwordx4 v[224:225], off
	v_lshl_add_u64 v[224:225], s[22:23], 0, v[144:145]
	s_add_i32 m0, s33, 0xe000
	s_nop 0
	global_load_lds_dwordx4 v[224:225], off
	s_waitcnt vmcnt(8)
	s_waitcnt lgkmcnt(0)
	s_barrier
; #define PG8_STAGE(bufoff, gbase, voff) do { _Pragma("unroll") for (int _i = 0; _i < 2; ++_i) \
;         __builtin_amdgcn_global_load_lds((const unsigned*)((const char*)(gbase) + (voff)[_i]), (PG8_LAS unsigned*)(lds + (bufoff) + ldsw + _i * 8192), 16, 0, 0); } while (0)
; #define PG8_LDA(dst, b, h) do { _Pragma("unroll") for (int m = 0; m < 4; ++m) _Pragma("unroll") for (int k = 0; k < 2; ++k) dst[m][k] = *(const PG8_LAS bf16x8*)(lds + PG8_SA(b, h) + aoff + m * 2048 + k * 1024); } while (0)
; #define PG8_MMA(ai, bj, At, Bt) do { __builtin_amdgcn_s_setprio(1); _Pragma("unroll") for (int m = 0; m < 4; ++m) _Pragma("unroll") for (int n = 0; n < 2; ++n) _Pragma("unroll") for (int k = 0; k < 2; ++k) \
;         acc[ai][bj][m][n] = __builtin_amdgcn_mfma_f32_16x16x32_bf16(Bt[n][k], At[m][k], acc[ai][bj][m][n], 0, 0, 0); __builtin_amdgcn_s_setprio(0); } while (0)
; #define PG8_WAIT_V(n) asm volatile("s_waitcnt vmcnt(" #n ")" ::: "memory")
; #define PG8_WAIT_L(n) asm volatile("s_waitcnt lgkmcnt(" #n ")" ::: "memory")
; #define PG8_BAR __builtin_amdgcn_s_barrier()
; #define PG8_SCHED __builtin_amdgcn_sched_barrier(0)
; template <class Epi, class Sched, bool ALIGN_EPI = false, bool SP2 = false, bool AGM = false  >
; __device__ __forceinline__ void gemm_phase(PG8_LAS unsigned char* lds, const Gemm g, const Sched& S, const Epi& E) {
;     ...
;             PG8_WAIT_V(8); PG8_WAIT_L(0); PG8_BAR; PG8_MMA(0, 0, At, B0); PG8_MMA(0, 1, At, B1); PG8_BAR; PG8_SCHED;
;             PG8_LDA(At, 0, 1); PG8_STAGE(PG8_SB(0, 0), b2, voffB); PG8_STAGE(PG8_SB(0, 1), b2 + hstep, voffB); PG8_STAGE(PG8_SA(0, 0), a2, voffA);
;             PG8_WAIT_V(8); PG8_WAIT_L(0); PG8_BAR; PG8_MMA(1, 0, At, B0); PG8_MMA(1, 1, At, B1); PG8_BAR; PG8_SCHED;
	s_setprio 1
	s_waitcnt lgkmcnt(0)
	v_mfma_f32_16x16x32_bf16 v[126:129], v[150:153], v[192:195], v[126:129]
	v_mfma_f32_16x16x32_bf16 v[122:125], v[168:171], v[192:195], v[122:125]
	v_mfma_f32_16x16x32_bf16 v[114:117], v[150:153], v[200:203], v[114:117]
	v_mfma_f32_16x16x32_bf16 v[106:109], v[168:171], v[200:203], v[106:109]
	v_mfma_f32_16x16x32_bf16 v[102:105], v[150:153], v[208:211], v[102:105]
	v_mfma_f32_16x16x32_bf16 v[94:97], v[168:171], v[208:211], v[94:97]
	v_mfma_f32_16x16x32_bf16 v[86:89], v[150:153], v[216:219], v[86:89]
	v_mfma_f32_16x16x32_bf16 v[78:81], v[168:171], v[216:219], v[78:81]
	v_mfma_f32_16x16x32_bf16 v[126:129], v[164:167], v[196:199], v[126:129]
	v_mfma_f32_16x16x32_bf16 v[122:125], v[172:175], v[196:199], v[122:125]
	v_mfma_f32_16x16x32_bf16 v[114:117], v[164:167], v[204:207], v[114:117]
	v_mfma_f32_16x16x32_bf16 v[106:109], v[172:175], v[204:207], v[106:109]
	v_mfma_f32_16x16x32_bf16 v[102:105], v[164:167], v[212:215], v[102:105]
	v_mfma_f32_16x16x32_bf16 v[94:97], v[172:175], v[212:215], v[94:97]
	v_mfma_f32_16x16x32_bf16 v[86:89], v[164:167], v[220:223], v[86:89]
	v_mfma_f32_16x16x32_bf16 v[78:81], v[172:175], v[220:223], v[78:81]
	s_setprio 0
	s_setprio 1
	v_mfma_f32_16x16x32_bf16 v[118:121], v[176:179], v[192:195], v[118:121]
	v_mfma_f32_16x16x32_bf16 v[110:113], v[184:187], v[192:195], v[110:113]
	v_mfma_f32_16x16x32_bf16 v[98:101], v[176:179], v[200:203], v[98:101]
	v_mfma_f32_16x16x32_bf16 v[90:93], v[184:187], v[200:203], v[90:93]
	v_mfma_f32_16x16x32_bf16 v[82:85], v[176:179], v[208:211], v[82:85]
	v_mfma_f32_16x16x32_bf16 v[74:77], v[184:187], v[208:211], v[74:77]
	v_mfma_f32_16x16x32_bf16 v[70:73], v[176:179], v[216:219], v[70:73]
	v_mfma_f32_16x16x32_bf16 v[66:69], v[184:187], v[216:219], v[66:69]
	v_mfma_f32_16x16x32_bf16 v[118:121], v[180:183], v[196:199], v[118:121]
	v_mfma_f32_16x16x32_bf16 v[110:113], v[188:191], v[196:199], v[110:113]
	v_mfma_f32_16x16x32_bf16 v[98:101], v[180:183], v[204:207], v[98:101]
	v_mfma_f32_16x16x32_bf16 v[90:93], v[188:191], v[204:207], v[90:93]
	v_mfma_f32_16x16x32_bf16 v[82:85], v[180:183], v[212:215], v[82:85]
	v_mfma_f32_16x16x32_bf16 v[74:77], v[188:191], v[212:215], v[74:77]
	v_mfma_f32_16x16x32_bf16 v[70:73], v[180:183], v[220:223], v[70:73]
	v_mfma_f32_16x16x32_bf16 v[66:69], v[188:191], v[220:223], v[66:69]
	s_setprio 0
	s_barrier
	s_add_i32 s58, s41, s29
	v_lshl_add_u64 v[224:225], s[24:25], 0, v[134:135]
	s_mov_b32 m0, s58
	ds_read_b128 v[192:195], v162 offset:16384
	ds_read_b128 v[196:199], v162 offset:17408
	ds_read_b128 v[200:203], v162 offset:18432
	ds_read_b128 v[204:207], v162 offset:19456
	ds_read_b128 v[208:211], v162 offset:20480
	ds_read_b128 v[212:215], v162 offset:21504
	ds_read_b128 v[216:219], v162 offset:22528
	ds_read_b128 v[220:223], v162 offset:23552
	global_load_lds_dwordx4 v[224:225], off
	s_add_i32 m0, s58, 0x2000
	s_add_u32 s58, s24, 0x40000
	v_lshl_add_u64 v[226:227], s[24:25], 0, v[130:131]
	s_addc_u32 s59, s25, 0
	s_add_i32 s60, s42, s29
	global_load_lds_dwordx4 v[226:227], off
	v_lshl_add_u64 v[228:229], s[58:59], 0, v[134:135]
	s_mov_b32 m0, s60
	v_lshl_add_u64 v[230:231], s[26:27], 0, v[132:133]
	global_load_lds_dwordx4 v[228:229], off
	v_lshl_add_u64 v[228:229], s[58:59], 0, v[130:131]
	s_add_i32 m0, s60, 0x2000
	s_nop 0
	global_load_lds_dwordx4 v[228:229], off
	v_lshl_add_u64 v[228:229], s[26:27], 0, v[136:137]
	s_mov_b32 m0, s33
	s_nop 0
	global_load_lds_dwordx4 v[228:229], off
	s_mov_b32 m0, s34
	s_nop 0
	global_load_lds_dwordx4 v[230:231], off
	s_waitcnt vmcnt(8)
	s_waitcnt lgkmcnt(0)
	s_barrier
	s_setprio 1
	s_waitcnt lgkmcnt(0)
	v_mfma_f32_16x16x32_bf16 v[62:65], v[150:153], v[192:195], v[62:65]
	v_mfma_f32_16x16x32_bf16 v[58:61], v[168:171], v[192:195], v[58:61]
	v_mfma_f32_16x16x32_bf16 v[54:57], v[150:153], v[200:203], v[54:57]
	v_mfma_f32_16x16x32_bf16 v[46:49], v[168:171], v[200:203], v[46:49]
	v_mfma_f32_16x16x32_bf16 v[38:41], v[150:153], v[208:211], v[38:41]
	v_mfma_f32_16x16x32_bf16 v[30:33], v[168:171], v[208:211], v[30:33]
	v_mfma_f32_16x16x32_bf16 v[22:25], v[150:153], v[216:219], v[22:25]
	v_mfma_f32_16x16x32_bf16 v[14:17], v[168:171], v[216:219], v[14:17]
	v_mfma_f32_16x16x32_bf16 v[62:65], v[164:167], v[196:199], v[62:65]
	v_mfma_f32_16x16x32_bf16 v[58:61], v[172:175], v[196:199], v[58:61]
	v_mfma_f32_16x16x32_bf16 v[54:57], v[164:167], v[204:207], v[54:57]
	v_mfma_f32_16x16x32_bf16 v[46:49], v[172:175], v[204:207], v[46:49]
	v_mfma_f32_16x16x32_bf16 v[38:41], v[164:167], v[212:215], v[38:41]
	v_mfma_f32_16x16x32_bf16 v[30:33], v[172:175], v[212:215], v[30:33]
	v_mfma_f32_16x16x32_bf16 v[22:25], v[164:167], v[220:223], v[22:25]
	v_mfma_f32_16x16x32_bf16 v[14:17], v[172:175], v[220:223], v[14:17]
	s_setprio 0
	s_setprio 1
	v_mfma_f32_16x16x32_bf16 v[50:53], v[176:179], v[192:195], v[50:53]
	v_mfma_f32_16x16x32_bf16 v[42:45], v[184:187], v[192:195], v[42:45]
	v_mfma_f32_16x16x32_bf16 v[34:37], v[176:179], v[200:203], v[34:37]
	v_mfma_f32_16x16x32_bf16 v[26:29], v[184:187], v[200:203], v[26:29]
	v_mfma_f32_16x16x32_bf16 v[18:21], v[176:179], v[208:211], v[18:21]
	v_mfma_f32_16x16x32_bf16 v[10:13], v[184:187], v[208:211], v[10:13]
	v_mfma_f32_16x16x32_bf16 v[6:9], v[176:179], v[216:219], v[6:9]
	v_mfma_f32_16x16x32_bf16 v[2:5], v[184:187], v[216:219], v[2:5]
	v_mfma_f32_16x16x32_bf16 v[50:53], v[180:183], v[196:199], v[50:53]
	v_mfma_f32_16x16x32_bf16 v[42:45], v[188:191], v[196:199], v[42:45]
	v_mfma_f32_16x16x32_bf16 v[34:37], v[180:183], v[204:207], v[34:37]
	v_mfma_f32_16x16x32_bf16 v[26:29], v[188:191], v[204:207], v[26:29]
	v_mfma_f32_16x16x32_bf16 v[18:21], v[180:183], v[212:215], v[18:21]
	v_mfma_f32_16x16x32_bf16 v[10:13], v[188:191], v[212:215], v[10:13]
	v_mfma_f32_16x16x32_bf16 v[6:9], v[180:183], v[220:223], v[6:9]
	v_mfma_f32_16x16x32_bf16 v[2:5], v[188:191], v[220:223], v[2:5]
	s_setprio 0
	s_barrier
; #define PG8_STAGE(bufoff, gbase, voff) do { _Pragma("unroll") for (int _i = 0; _i < 2; ++_i) \
;         __builtin_amdgcn_global_load_lds((const unsigned*)((const char*)(gbase) + (voff)[_i]), (PG8_LAS unsigned*)(lds + (bufoff) + ldsw + _i * 8192), 16, 0, 0); } while (0)
; #define PG8_LDA(dst, b, h) do { _Pragma("unroll") for (int m = 0; m < 4; ++m) _Pragma("unroll") for (int k = 0; k < 2; ++k) dst[m][k] = *(const PG8_LAS bf16x8*)(lds + PG8_SA(b, h) + aoff + m * 2048 + k * 1024); } while (0)
; #define PG8_LDB(dst, b, h) do { _Pragma("unroll") for (int n = 0; n < 2; ++n) _Pragma("unroll") for (int k = 0; k < 2; ++k) dst[n][k] = *(const PG8_LAS bf16x8*)(lds + PG8_SB(b, h) + boff + n * 2048 + k * 1024); } while (0)
; #define PG8_MMA(ai, bj, At, Bt) do { __builtin_amdgcn_s_setprio(1); _Pragma("unroll") for (int m = 0; m < 4; ++m) _Pragma("unroll") for (int n = 0; n < 2; ++n) _Pragma("unroll") for (int k = 0; k < 2; ++k) \
;         acc[ai][bj][m][n] = __builtin_amdgcn_mfma_f32_16x16x32_bf16(Bt[n][k], At[m][k], acc[ai][bj][m][n], 0, 0, 0); __builtin_amdgcn_s_setprio(0); } while (0)
; #define PG8_WAIT_V(n) asm volatile("s_waitcnt vmcnt(" #n ")" ::: "memory")
; #define PG8_WAIT_L(n) asm volatile("s_waitcnt lgkmcnt(" #n ")" ::: "memory")
; #define PG8_BAR __builtin_amdgcn_s_barrier()
; #define PG8_SCHED __builtin_amdgcn_sched_barrier(0)
; template <class Epi, class Sched, bool ALIGN_EPI = false, bool SP2 = false, bool AGM = false  >
; __device__ __forceinline__ void gemm_phase(PG8_LAS unsigned char* lds, const Gemm g, const Sched& S, const Epi& E) {
;     ...
;             PG8_LDB(B0, 1, 0); PG8_LDB(B1, 1, 1); PG8_SCHED; PG8_LDA(At, 1, 0); PG8_STAGE(PG8_SA(0, 1), a2 + hstepA, voffA);
;             PG8_WAIT_V(8); PG8_WAIT_L(0); PG8_BAR; PG8_MMA(0, 0, At, B0); PG8_MMA(0, 1, At, B1); PG8_BAR; PG8_SCHED;
	s_add_i32 s58, 0, 0x18000
	v_add_u32_e32 v138, s58, v157
	s_add_i32 s59, 0, 0x1c000
	ds_read_b128 v[150:153], v138
	ds_read_b128 v[164:167], v138 offset:1024
	ds_read_b128 v[168:171], v138 offset:2048
	ds_read_b128 v[172:175], v138 offset:3072
	v_add_u32_e32 v138, s59, v157
	ds_read_b128 v[176:179], v138
	ds_read_b128 v[180:183], v138 offset:1024
	ds_read_b128 v[184:187], v138 offset:2048
	ds_read_b128 v[188:191], v138 offset:3072
	s_add_u32 s26, s26, 0x40000
	s_addc_u32 s27, s27, 0
	s_mov_b32 m0, s35
	v_lshl_add_u64 v[232:233], s[26:27], 0, v[136:137]
	ds_read_b128 v[192:195], v162 offset:32768
	ds_read_b128 v[196:199], v162 offset:33792
	ds_read_b128 v[200:203], v162 offset:34816
	ds_read_b128 v[204:207], v162 offset:35840
	ds_read_b128 v[208:211], v162 offset:36864
	ds_read_b128 v[212:215], v162 offset:37888
	ds_read_b128 v[216:219], v162 offset:38912
	ds_read_b128 v[220:223], v162 offset:39936
	global_load_lds_dwordx4 v[232:233], off
	v_lshl_add_u64 v[232:233], s[26:27], 0, v[132:133]
	s_mov_b32 m0, s36
	s_nop 0
	global_load_lds_dwordx4 v[232:233], off
	s_waitcnt vmcnt(8)
	s_waitcnt lgkmcnt(0)
	s_barrier
	s_setprio 1
	s_waitcnt lgkmcnt(0)
	v_mfma_f32_16x16x32_bf16 v[126:129], v[150:153], v[192:195], v[126:129]
	v_mfma_f32_16x16x32_bf16 v[122:125], v[168:171], v[192:195], v[122:125]
	v_mfma_f32_16x16x32_bf16 v[114:117], v[150:153], v[200:203], v[114:117]
	v_mfma_f32_16x16x32_bf16 v[106:109], v[168:171], v[200:203], v[106:109]
	v_mfma_f32_16x16x32_bf16 v[102:105], v[150:153], v[208:211], v[102:105]
	v_mfma_f32_16x16x32_bf16 v[94:97], v[168:171], v[208:211], v[94:97]
	v_mfma_f32_16x16x32_bf16 v[86:89], v[150:153], v[216:219], v[86:89]
	v_mfma_f32_16x16x32_bf16 v[78:81], v[168:171], v[216:219], v[78:81]
	v_mfma_f32_16x16x32_bf16 v[126:129], v[164:167], v[196:199], v[126:129]
	v_mfma_f32_16x16x32_bf16 v[122:125], v[172:175], v[196:199], v[122:125]
	v_mfma_f32_16x16x32_bf16 v[114:117], v[164:167], v[204:207], v[114:117]
	v_mfma_f32_16x16x32_bf16 v[106:109], v[172:175], v[204:207], v[106:109]
	v_mfma_f32_16x16x32_bf16 v[102:105], v[164:167], v[212:215], v[102:105]
	v_mfma_f32_16x16x32_bf16 v[94:97], v[172:175], v[212:215], v[94:97]
	v_mfma_f32_16x16x32_bf16 v[86:89], v[164:167], v[220:223], v[86:89]
	v_mfma_f32_16x16x32_bf16 v[78:81], v[172:175], v[220:223], v[78:81]
	s_setprio 0
	s_setprio 1
	v_mfma_f32_16x16x32_bf16 v[118:121], v[176:179], v[192:195], v[118:121]
	v_mfma_f32_16x16x32_bf16 v[110:113], v[184:187], v[192:195], v[110:113]
	v_mfma_f32_16x16x32_bf16 v[98:101], v[176:179], v[200:203], v[98:101]
	v_mfma_f32_16x16x32_bf16 v[90:93], v[184:187], v[200:203], v[90:93]
	v_mfma_f32_16x16x32_bf16 v[82:85], v[176:179], v[208:211], v[82:85]
	v_mfma_f32_16x16x32_bf16 v[74:77], v[184:187], v[208:211], v[74:77]
	v_mfma_f32_16x16x32_bf16 v[70:73], v[176:179], v[216:219], v[70:73]
	v_mfma_f32_16x16x32_bf16 v[66:69], v[184:187], v[216:219], v[66:69]
	v_mfma_f32_16x16x32_bf16 v[118:121], v[180:183], v[196:199], v[118:121]
	v_mfma_f32_16x16x32_bf16 v[110:113], v[188:191], v[196:199], v[110:113]
	v_mfma_f32_16x16x32_bf16 v[98:101], v[180:183], v[204:207], v[98:101]
	v_mfma_f32_16x16x32_bf16 v[90:93], v[188:191], v[204:207], v[90:93]
	v_mfma_f32_16x16x32_bf16 v[82:85], v[180:183], v[212:215], v[82:85]
	v_mfma_f32_16x16x32_bf16 v[74:77], v[188:191], v[212:215], v[74:77]
	v_mfma_f32_16x16x32_bf16 v[70:73], v[180:183], v[220:223], v[70:73]
	v_mfma_f32_16x16x32_bf16 v[66:69], v[188:191], v[220:223], v[66:69]
	s_setprio 0
	s_barrier
; #define PG8_STAGE(bufoff, gbase, voff) do { _Pragma("unroll") for (int _i = 0; _i < 2; ++_i) \
;         __builtin_amdgcn_global_load_lds((const unsigned*)((const char*)(gbase) + (voff)[_i]), (PG8_LAS unsigned*)(lds + (bufoff) + ldsw + _i * 8192), 16, 0, 0); } while (0)
; #define PG8_LDA(dst, b, h) do { _Pragma("unroll") for (int m = 0; m < 4; ++m) _Pragma("unroll") for (int k = 0; k < 2; ++k) dst[m][k] = *(const PG8_LAS bf16x8*)(lds + PG8_SA(b, h) + aoff + m * 2048 + k * 1024); } while (0)
; #define PG8_MMA(ai, bj, At, Bt) do { __builtin_amdgcn_s_setprio(1); _Pragma("unroll") for (int m = 0; m < 4; ++m) _Pragma("unroll") for (int n = 0; n < 2; ++n) _Pragma("unroll") for (int k = 0; k < 2; ++k) \
;         acc[ai][bj][m][n] = __builtin_amdgcn_mfma_f32_16x16x32_bf16(Bt[n][k], At[m][k], acc[ai][bj][m][n], 0, 0, 0); __builtin_amdgcn_s_setprio(0); } while (0)
; #define PG8_WAIT_V(n) asm volatile("s_waitcnt vmcnt(" #n ")" ::: "memory")
; #define PG8_WAIT_L(n) asm volatile("s_waitcnt lgkmcnt(" #n ")" ::: "memory")
; #define PG8_BAR __builtin_amdgcn_s_barrier()
; #define PG8_SCHED __builtin_amdgcn_sched_barrier(0)
; template <class Epi, class Sched, bool ALIGN_EPI = false, bool SP2 = false, bool AGM = false  >
; __device__ __forceinline__ void gemm_phase(PG8_LAS unsigned char* lds, const Gemm g, const Sched& S, const Epi& E) {
;     ...
;         for (int t = 0; t < nt; t += 2) {
;     ...
;             PG8_LDA(At, 1, 1); PG8_STAGE(PG8_SB(1, 0), b3, voffB); PG8_STAGE(PG8_SB(1, 1), b3 + hstep, voffB); PG8_STAGE(PG8_SA(1, 0), a3, voffA);
;             PG8_WAIT_V(8); PG8_WAIT_L(0); PG8_BAR; PG8_MMA(1, 0, At, B0); PG8_MMA(1, 1, At, B1); PG8_BAR; PG8_SCHED;
	s_add_i32 s26, s58, s29
	v_lshl_add_u64 v[224:225], v[224:225], 0, s[10:11]
	s_mov_b32 m0, s26
	ds_read_b128 v[192:195], v162 offset:49152
	ds_read_b128 v[196:199], v162 offset:50176
	ds_read_b128 v[200:203], v162 offset:51200
	ds_read_b128 v[204:207], v162 offset:52224
	ds_read_b128 v[208:211], v162 offset:53248
	ds_read_b128 v[212:215], v162 offset:54272
	ds_read_b128 v[216:219], v162 offset:55296
	ds_read_b128 v[220:223], v162 offset:56320
	global_load_lds_dwordx4 v[224:225], off
	s_add_i32 m0, s26, 0x2000
	s_add_u32 s24, s24, 0x40080
	v_lshl_add_u64 v[224:225], v[226:227], 0, s[10:11]
	s_addc_u32 s25, s25, 0
	s_add_i32 s26, s59, s29
	global_load_lds_dwordx4 v[224:225], off
	v_lshl_add_u64 v[224:225], s[24:25], 0, v[134:135]
	s_mov_b32 m0, s26
	s_nop 0
	global_load_lds_dwordx4 v[224:225], off
	v_lshl_add_u64 v[224:225], s[24:25], 0, v[130:131]
	s_add_i32 m0, s26, 0x2000
	s_nop 0
	global_load_lds_dwordx4 v[224:225], off
	v_lshl_add_u64 v[224:225], v[228:229], 0, s[10:11]
	s_mov_b32 m0, s38
	s_nop 0
	global_load_lds_dwordx4 v[224:225], off
	v_lshl_add_u64 v[224:225], v[230:231], 0, s[10:11]
	s_mov_b32 m0, s39
	s_nop 0
	global_load_lds_dwordx4 v[224:225], off
	s_waitcnt vmcnt(8)
	s_waitcnt lgkmcnt(0)
	s_barrier
	s_setprio 1
	s_waitcnt lgkmcnt(0)
	v_mfma_f32_16x16x32_bf16 v[62:65], v[150:153], v[192:195], v[62:65]
	v_mfma_f32_16x16x32_bf16 v[58:61], v[168:171], v[192:195], v[58:61]
	v_mfma_f32_16x16x32_bf16 v[54:57], v[150:153], v[200:203], v[54:57]
	v_mfma_f32_16x16x32_bf16 v[46:49], v[168:171], v[200:203], v[46:49]
	v_mfma_f32_16x16x32_bf16 v[38:41], v[150:153], v[208:211], v[38:41]
	v_mfma_f32_16x16x32_bf16 v[30:33], v[168:171], v[208:211], v[30:33]
	v_mfma_f32_16x16x32_bf16 v[22:25], v[150:153], v[216:219], v[22:25]
	v_mfma_f32_16x16x32_bf16 v[14:17], v[168:171], v[216:219], v[14:17]
	v_mfma_f32_16x16x32_bf16 v[62:65], v[164:167], v[196:199], v[62:65]
	v_mfma_f32_16x16x32_bf16 v[58:61], v[172:175], v[196:199], v[58:61]
	v_mfma_f32_16x16x32_bf16 v[54:57], v[164:167], v[204:207], v[54:57]
	v_mfma_f32_16x16x32_bf16 v[46:49], v[172:175], v[204:207], v[46:49]
	v_mfma_f32_16x16x32_bf16 v[38:41], v[164:167], v[212:215], v[38:41]
	v_mfma_f32_16x16x32_bf16 v[30:33], v[172:175], v[212:215], v[30:33]
	v_mfma_f32_16x16x32_bf16 v[22:25], v[164:167], v[220:223], v[22:25]
	v_mfma_f32_16x16x32_bf16 v[14:17], v[172:175], v[220:223], v[14:17]
	s_setprio 0
	s_setprio 1
	v_mfma_f32_16x16x32_bf16 v[50:53], v[176:179], v[192:195], v[50:53]
	v_mfma_f32_16x16x32_bf16 v[42:45], v[184:187], v[192:195], v[42:45]
	v_mfma_f32_16x16x32_bf16 v[34:37], v[176:179], v[200:203], v[34:37]
	v_mfma_f32_16x16x32_bf16 v[26:29], v[184:187], v[200:203], v[26:29]
	v_mfma_f32_16x16x32_bf16 v[18:21], v[176:179], v[208:211], v[18:21]
	v_mfma_f32_16x16x32_bf16 v[10:13], v[184:187], v[208:211], v[10:13]
	v_mfma_f32_16x16x32_bf16 v[6:9], v[176:179], v[216:219], v[6:9]
	v_mfma_f32_16x16x32_bf16 v[2:5], v[184:187], v[216:219], v[2:5]
	v_mfma_f32_16x16x32_bf16 v[50:53], v[180:183], v[196:199], v[50:53]
	v_mfma_f32_16x16x32_bf16 v[42:45], v[188:191], v[196:199], v[42:45]
	v_mfma_f32_16x16x32_bf16 v[34:37], v[180:183], v[204:207], v[34:37]
	v_mfma_f32_16x16x32_bf16 v[26:29], v[188:191], v[204:207], v[26:29]
	v_mfma_f32_16x16x32_bf16 v[18:21], v[180:183], v[212:215], v[18:21]
	v_mfma_f32_16x16x32_bf16 v[10:13], v[188:191], v[212:215], v[10:13]
	v_mfma_f32_16x16x32_bf16 v[6:9], v[180:183], v[220:223], v[6:9]
	v_mfma_f32_16x16x32_bf16 v[2:5], v[188:191], v[220:223], v[2:5]
	s_add_i32 s55, s55, 2
	s_add_u32 s22, s22, 0x100
	s_addc_u32 s23, s23, 0
	s_add_u32 s53, s53, 0x100
	s_addc_u32 s54, s54, 0
	s_cmp_gt_u32 s55, 13
	s_setprio 0
	s_barrier
	s_cbranch_scc0 .LBB0_137

; #define PG8_STAGE(bufoff, gbase, voff) do { _Pragma("unroll") for (int _i = 0; _i < 2; ++_i) \
;         __builtin_amdgcn_global_load_lds((const unsigned*)((const char*)(gbase) + (voff)[_i]), (PG8_LAS unsigned*)(lds + (bufoff) + ldsw + _i * 8192), 16, 0, 0); } while (0)
; #define PG8_LDA(dst, b, h) do { _Pragma("unroll") for (int m = 0; m < 4; ++m) _Pragma("unroll") for (int k = 0; k < 2; ++k) dst[m][k] = *(const PG8_LAS bf16x8*)(lds + PG8_SA(b, h) + aoff + m * 2048 + k * 1024); } while (0)
; #define PG8_LDB(dst, b, h) do { _Pragma("unroll") for (int n = 0; n < 2; ++n) _Pragma("unroll") for (int k = 0; k < 2; ++k) dst[n][k] = *(const PG8_LAS bf16x8*)(lds + PG8_SB(b, h) + boff + n * 2048 + k * 1024); } while (0)
; #define PG8_MMA(ai, bj, At, Bt) do { __builtin_amdgcn_s_setprio(1); _Pragma("unroll") for (int m = 0; m < 4; ++m) _Pragma("unroll") for (int n = 0; n < 2; ++n) _Pragma("unroll") for (int k = 0; k < 2; ++k) \
;         acc[ai][bj][m][n] = __builtin_amdgcn_mfma_f32_16x16x32_bf16(Bt[n][k], At[m][k], acc[ai][bj][m][n], 0, 0, 0); __builtin_amdgcn_s_setprio(0); } while (0)
; #define PG8_WAIT_V(n) asm volatile("s_waitcnt vmcnt(" #n ")" ::: "memory")
; #define PG8_WAIT_L(n) asm volatile("s_waitcnt lgkmcnt(" #n ")" ::: "memory")
; template <class Epi, class Sched, bool ALIGN_EPI = false, bool SP2 = false, bool AGM = false  >
; __device__ __forceinline__ void gemm_phase(PG8_LAS unsigned char* lds, const Gemm g, const Sched& S, const Epi& E) {
;     ...
;             const bool last = (t == nt - 2);
;             const char* a1 = cA + (size_t)(t + 1) * kstepA;
;             const char* a2 = last ? nA : cA + (size_t)(t + 2) * kstepA; const char* b2 = last ? nB : cB + (size_t)(t + 2) * kstep;
;             const char* a3 = a2 + kstepA; const char* b3 = b2 + kstep;
;             if (last && has_next) S.a_ready(nxt);
;             if constexpr (SP2) {
;             PG8_LDB(B0, 0, 0); PG8_LDB(B1, 0, 1); PG8_SCHED; PG8_LDA(At, 0, 0); PG8_STAGE(PG8_SA(1, 1), a1 + hstepA, voffA);
;             PG8_WAIT_V(8); PG8_WAIT_L(0); PG8_BAR; PG8_MMA(0, 0, At, B0); PG8_MMA(0, 1, At, B1); PG8_BAR; PG8_SCHED;
;             PG8_LDA(At, 0, 1); PG8_STAGE(PG8_SB(0, 0), b2, voffB); PG8_STAGE(PG8_SB(0, 1), b2 + hstep, voffB); PG8_STAGE(PG8_SA(0, 0), a2, voffA);
;             PG8_WAIT_V(8); PG8_WAIT_L(0); PG8_BAR; PG8_MMA(1, 0, At, B0); PG8_MMA(1, 1, At, B1); PG8_BAR; PG8_SCHED;
.LBB0_677:
	ds_read_b128 v[150:153], v157
	ds_read_b128 v[164:167], v157 offset:1024
	ds_read_b128 v[168:171], v157 offset:2048
	ds_read_b128 v[172:175], v157 offset:3072
	ds_read_b128 v[176:179], v158
	ds_read_b128 v[180:183], v158 offset:1024
	ds_read_b128 v[184:187], v158 offset:2048
	ds_read_b128 v[188:191], v158 offset:3072
	s_add_u32 s26, s24, 0x440000
	s_addc_u32 s27, s25, 0
	s_cmp_eq_u32 s70, 4
	s_cselect_b32 s34, s62, s26
	s_cselect_b32 s35, s19, s27
	s_cselect_b32 s30, s63, s68
	s_cselect_b32 s31, s17, s69
	s_add_u32 s28, s34, 0x220000
	s_addc_u32 s29, s35, 0
	v_lshl_add_u64 v[224:225], s[24:25], 0, v[142:143]
	s_add_i32 m0, s5, 0xc000
	ds_read_b128 v[192:195], v159
	ds_read_b128 v[196:199], v159 offset:1024
	ds_read_b128 v[200:203], v159 offset:2048
	ds_read_b128 v[204:207], v159 offset:3072
	ds_read_b128 v[208:211], v159 offset:4096
	ds_read_b128 v[212:215], v159 offset:5120
	ds_read_b128 v[216:219], v159 offset:6144
	ds_read_b128 v[220:223], v159 offset:7168
	global_load_lds_dwordx4 v[224:225], off
	v_lshl_add_u64 v[224:225], s[24:25], 0, v[144:145]
	s_add_i32 m0, s5, 0xe000
	s_nop 0
	global_load_lds_dwordx4 v[224:225], off
	s_waitcnt vmcnt(8)
	s_waitcnt lgkmcnt(0)
	s_barrier
	s_setprio 1
	s_waitcnt lgkmcnt(0)
	v_mfma_f32_16x16x32_bf16 v[126:129], v[150:153], v[192:195], v[126:129]
	v_mfma_f32_16x16x32_bf16 v[122:125], v[168:171], v[192:195], v[122:125]
	v_mfma_f32_16x16x32_bf16 v[110:113], v[150:153], v[200:203], v[110:113]
	v_mfma_f32_16x16x32_bf16 v[106:109], v[168:171], v[200:203], v[106:109]
	v_mfma_f32_16x16x32_bf16 v[94:97], v[150:153], v[208:211], v[94:97]
	v_mfma_f32_16x16x32_bf16 v[90:93], v[168:171], v[208:211], v[90:93]
	v_mfma_f32_16x16x32_bf16 v[78:81], v[150:153], v[216:219], v[78:81]
	v_mfma_f32_16x16x32_bf16 v[74:77], v[168:171], v[216:219], v[74:77]
	v_mfma_f32_16x16x32_bf16 v[126:129], v[164:167], v[196:199], v[126:129]
	v_mfma_f32_16x16x32_bf16 v[122:125], v[172:175], v[196:199], v[122:125]
	v_mfma_f32_16x16x32_bf16 v[110:113], v[164:167], v[204:207], v[110:113]
	v_mfma_f32_16x16x32_bf16 v[106:109], v[172:175], v[204:207], v[106:109]
	v_mfma_f32_16x16x32_bf16 v[94:97], v[164:167], v[212:215], v[94:97]
	v_mfma_f32_16x16x32_bf16 v[90:93], v[172:175], v[212:215], v[90:93]
	v_mfma_f32_16x16x32_bf16 v[78:81], v[164:167], v[220:223], v[78:81]
	v_mfma_f32_16x16x32_bf16 v[74:77], v[172:175], v[220:223], v[74:77]
	s_setprio 0
	s_setprio 1
	v_mfma_f32_16x16x32_bf16 v[118:121], v[176:179], v[192:195], v[118:121]
	v_mfma_f32_16x16x32_bf16 v[114:117], v[184:187], v[192:195], v[114:117]
	v_mfma_f32_16x16x32_bf16 v[102:105], v[176:179], v[200:203], v[102:105]
	v_mfma_f32_16x16x32_bf16 v[98:101], v[184:187], v[200:203], v[98:101]
	v_mfma_f32_16x16x32_bf16 v[86:89], v[176:179], v[208:211], v[86:89]
	v_mfma_f32_16x16x32_bf16 v[82:85], v[184:187], v[208:211], v[82:85]
	v_mfma_f32_16x16x32_bf16 v[70:73], v[176:179], v[216:219], v[70:73]
	v_mfma_f32_16x16x32_bf16 v[66:69], v[184:187], v[216:219], v[66:69]
	v_mfma_f32_16x16x32_bf16 v[118:121], v[180:183], v[196:199], v[118:121]
	v_mfma_f32_16x16x32_bf16 v[114:117], v[188:191], v[196:199], v[114:117]
	v_mfma_f32_16x16x32_bf16 v[102:105], v[180:183], v[204:207], v[102:105]
	v_mfma_f32_16x16x32_bf16 v[98:101], v[188:191], v[204:207], v[98:101]
	v_mfma_f32_16x16x32_bf16 v[86:89], v[180:183], v[212:215], v[86:89]
	v_mfma_f32_16x16x32_bf16 v[82:85], v[188:191], v[212:215], v[82:85]
	v_mfma_f32_16x16x32_bf16 v[70:73], v[180:183], v[220:223], v[70:73]
	v_mfma_f32_16x16x32_bf16 v[66:69], v[188:191], v[220:223], v[66:69]
	s_setprio 0
	s_barrier
	s_add_i32 s24, s54, s37
	v_lshl_add_u64 v[224:225], s[30:31], 0, v[134:135]
	s_mov_b32 m0, s24
	ds_read_b128 v[192:195], v159 offset:16384
	ds_read_b128 v[196:199], v159 offset:17408
	ds_read_b128 v[200:203], v159 offset:18432
	ds_read_b128 v[204:207], v159 offset:19456
	ds_read_b128 v[208:211], v159 offset:20480
	ds_read_b128 v[212:215], v159 offset:21504
	ds_read_b128 v[216:219], v159 offset:22528
	ds_read_b128 v[220:223], v159 offset:23552
	global_load_lds_dwordx4 v[224:225], off
	s_add_i32 m0, s24, 0x2000
	s_add_u32 s24, s30, 0x20000
	v_lshl_add_u64 v[226:227], s[30:31], 0, v[130:131]
	s_addc_u32 s25, s31, 0
	s_add_i32 s71, s55, s37
	global_load_lds_dwordx4 v[226:227], off
	v_lshl_add_u64 v[228:229], s[24:25], 0, v[134:135]
	s_mov_b32 m0, s71
	s_nop 0
	global_load_lds_dwordx4 v[228:229], off
	v_lshl_add_u64 v[228:229], s[24:25], 0, v[130:131]
	s_add_i32 m0, s71, 0x2000
	s_nop 0
	global_load_lds_dwordx4 v[228:229], off
	v_lshl_add_u64 v[228:229], s[34:35], 0, v[136:137]
	s_mov_b32 m0, s5
	s_nop 0
	global_load_lds_dwordx4 v[228:229], off
	v_lshl_add_u64 v[228:229], s[34:35], 0, v[132:133]
	s_mov_b32 m0, s39
	s_nop 0
	global_load_lds_dwordx4 v[228:229], off
	s_waitcnt vmcnt(8)
	s_waitcnt lgkmcnt(0)
	s_barrier
; #define PG8_STAGE(bufoff, gbase, voff) do { _Pragma("unroll") for (int _i = 0; _i < 2; ++_i) \
;         __builtin_amdgcn_global_load_lds((const unsigned*)((const char*)(gbase) + (voff)[_i]), (PG8_LAS unsigned*)(lds + (bufoff) + ldsw + _i * 8192), 16, 0, 0); } while (0)
; #define PG8_LDA(dst, b, h) do { _Pragma("unroll") for (int m = 0; m < 4; ++m) _Pragma("unroll") for (int k = 0; k < 2; ++k) dst[m][k] = *(const PG8_LAS bf16x8*)(lds + PG8_SA(b, h) + aoff + m * 2048 + k * 1024); } while (0)
; #define PG8_LDB(dst, b, h) do { _Pragma("unroll") for (int n = 0; n < 2; ++n) _Pragma("unroll") for (int k = 0; k < 2; ++k) dst[n][k] = *(const PG8_LAS bf16x8*)(lds + PG8_SB(b, h) + boff + n * 2048 + k * 1024); } while (0)
; #define PG8_MMA(ai, bj, At, Bt) do { __builtin_amdgcn_s_setprio(1); _Pragma("unroll") for (int m = 0; m < 4; ++m) _Pragma("unroll") for (int n = 0; n < 2; ++n) _Pragma("unroll") for (int k = 0; k < 2; ++k) \
;         acc[ai][bj][m][n] = __builtin_amdgcn_mfma_f32_16x16x32_bf16(Bt[n][k], At[m][k], acc[ai][bj][m][n], 0, 0, 0); __builtin_amdgcn_s_setprio(0); } while (0)
; #define PG8_WAIT_V(n) asm volatile("s_waitcnt vmcnt(" #n ")" ::: "memory")
; #define PG8_WAIT_L(n) asm volatile("s_waitcnt lgkmcnt(" #n ")" ::: "memory")
; #define PG8_BAR __builtin_amdgcn_s_barrier()
; #define PG8_SCHED __builtin_amdgcn_sched_barrier(0)
; template <class Epi, class Sched, bool ALIGN_EPI = false, bool SP2 = false, bool AGM = false  >
; __device__ __forceinline__ void gemm_phase(PG8_LAS unsigned char* lds, const Gemm g, const Sched& S, const Epi& E) {
;     ...
;             PG8_WAIT_V(8); PG8_WAIT_L(0); PG8_BAR; PG8_MMA(1, 0, At, B0); PG8_MMA(1, 1, At, B1); PG8_BAR; PG8_SCHED;
;             PG8_LDB(B0, 1, 0); PG8_LDB(B1, 1, 1); PG8_SCHED; PG8_LDA(At, 1, 0); PG8_STAGE(PG8_SA(0, 1), a2 + hstepA, voffA);
;             PG8_WAIT_V(8); PG8_WAIT_L(0); PG8_BAR; PG8_MMA(0, 0, At, B0); PG8_MMA(0, 1, At, B1); PG8_BAR; PG8_SCHED;
	s_setprio 1
	s_waitcnt lgkmcnt(0)
	v_mfma_f32_16x16x32_bf16 v[62:65], v[150:153], v[192:195], v[62:65]
	v_mfma_f32_16x16x32_bf16 v[58:61], v[168:171], v[192:195], v[58:61]
	v_mfma_f32_16x16x32_bf16 v[46:49], v[150:153], v[200:203], v[46:49]
	v_mfma_f32_16x16x32_bf16 v[42:45], v[168:171], v[200:203], v[42:45]
	v_mfma_f32_16x16x32_bf16 v[30:33], v[150:153], v[208:211], v[30:33]
	v_mfma_f32_16x16x32_bf16 v[26:29], v[168:171], v[208:211], v[26:29]
	v_mfma_f32_16x16x32_bf16 v[14:17], v[150:153], v[216:219], v[14:17]
	v_mfma_f32_16x16x32_bf16 v[10:13], v[168:171], v[216:219], v[10:13]
	v_mfma_f32_16x16x32_bf16 v[62:65], v[164:167], v[196:199], v[62:65]
	v_mfma_f32_16x16x32_bf16 v[58:61], v[172:175], v[196:199], v[58:61]
	v_mfma_f32_16x16x32_bf16 v[46:49], v[164:167], v[204:207], v[46:49]
	v_mfma_f32_16x16x32_bf16 v[42:45], v[172:175], v[204:207], v[42:45]
	v_mfma_f32_16x16x32_bf16 v[30:33], v[164:167], v[212:215], v[30:33]
	v_mfma_f32_16x16x32_bf16 v[26:29], v[172:175], v[212:215], v[26:29]
	v_mfma_f32_16x16x32_bf16 v[14:17], v[164:167], v[220:223], v[14:17]
	v_mfma_f32_16x16x32_bf16 v[10:13], v[172:175], v[220:223], v[10:13]
	s_setprio 0
	s_setprio 1
	v_mfma_f32_16x16x32_bf16 v[54:57], v[176:179], v[192:195], v[54:57]
	v_mfma_f32_16x16x32_bf16 v[50:53], v[184:187], v[192:195], v[50:53]
	v_mfma_f32_16x16x32_bf16 v[38:41], v[176:179], v[200:203], v[38:41]
	v_mfma_f32_16x16x32_bf16 v[34:37], v[184:187], v[200:203], v[34:37]
	v_mfma_f32_16x16x32_bf16 v[22:25], v[176:179], v[208:211], v[22:25]
	v_mfma_f32_16x16x32_bf16 v[18:21], v[184:187], v[208:211], v[18:21]
	v_mfma_f32_16x16x32_bf16 v[6:9], v[176:179], v[216:219], v[6:9]
	v_mfma_f32_16x16x32_bf16 v[2:5], v[184:187], v[216:219], v[2:5]
	v_mfma_f32_16x16x32_bf16 v[54:57], v[180:183], v[196:199], v[54:57]
	v_mfma_f32_16x16x32_bf16 v[50:53], v[188:191], v[196:199], v[50:53]
	v_mfma_f32_16x16x32_bf16 v[38:41], v[180:183], v[204:207], v[38:41]
	v_mfma_f32_16x16x32_bf16 v[34:37], v[188:191], v[204:207], v[34:37]
	v_mfma_f32_16x16x32_bf16 v[22:25], v[180:183], v[212:215], v[22:25]
	v_mfma_f32_16x16x32_bf16 v[18:21], v[188:191], v[212:215], v[18:21]
	v_mfma_f32_16x16x32_bf16 v[6:9], v[180:183], v[220:223], v[6:9]
	v_mfma_f32_16x16x32_bf16 v[2:5], v[188:191], v[220:223], v[2:5]
	s_setprio 0
	s_barrier
	s_add_i32 s71, 0, 0x18000
	v_add_u32_e32 v163, s71, v155
	s_add_i32 s72, 0, 0x1c000
	ds_read_b128 v[150:153], v163
	ds_read_b128 v[164:167], v163 offset:1024
	ds_read_b128 v[168:171], v163 offset:2048
	ds_read_b128 v[172:175], v163 offset:3072
	v_add_u32_e32 v163, s72, v155
	ds_read_b128 v[176:179], v163
	ds_read_b128 v[180:183], v163 offset:1024
	ds_read_b128 v[184:187], v163 offset:2048
	ds_read_b128 v[188:191], v163 offset:3072
	s_add_u32 s24, s34, 0x1000
	s_addc_u32 s25, s35, 0
	s_mov_b32 m0, s40
	v_lshl_add_u64 v[228:229], s[24:25], 0, v[136:137]
	ds_read_b128 v[192:195], v159 offset:32768
	ds_read_b128 v[196:199], v159 offset:33792
	ds_read_b128 v[200:203], v159 offset:34816
	ds_read_b128 v[204:207], v159 offset:35840
	ds_read_b128 v[208:211], v159 offset:36864
	ds_read_b128 v[212:215], v159 offset:37888
	ds_read_b128 v[216:219], v159 offset:38912
	ds_read_b128 v[220:223], v159 offset:39936
	global_load_lds_dwordx4 v[228:229], off
	v_lshl_add_u64 v[228:229], s[24:25], 0, v[132:133]
	s_mov_b32 m0, s41
	s_nop 0
	global_load_lds_dwordx4 v[228:229], off
	s_waitcnt vmcnt(8)
	s_waitcnt lgkmcnt(0)
	s_barrier
	s_setprio 1
	s_waitcnt lgkmcnt(0)
	v_mfma_f32_16x16x32_bf16 v[126:129], v[150:153], v[192:195], v[126:129]
	v_mfma_f32_16x16x32_bf16 v[122:125], v[168:171], v[192:195], v[122:125]
	v_mfma_f32_16x16x32_bf16 v[110:113], v[150:153], v[200:203], v[110:113]
	v_mfma_f32_16x16x32_bf16 v[106:109], v[168:171], v[200:203], v[106:109]
	v_mfma_f32_16x16x32_bf16 v[94:97], v[150:153], v[208:211], v[94:97]
	v_mfma_f32_16x16x32_bf16 v[90:93], v[168:171], v[208:211], v[90:93]
	v_mfma_f32_16x16x32_bf16 v[78:81], v[150:153], v[216:219], v[78:81]
	v_mfma_f32_16x16x32_bf16 v[74:77], v[168:171], v[216:219], v[74:77]
	v_mfma_f32_16x16x32_bf16 v[126:129], v[164:167], v[196:199], v[126:129]
	v_mfma_f32_16x16x32_bf16 v[122:125], v[172:175], v[196:199], v[122:125]
	v_mfma_f32_16x16x32_bf16 v[110:113], v[164:167], v[204:207], v[110:113]
	v_mfma_f32_16x16x32_bf16 v[106:109], v[172:175], v[204:207], v[106:109]
	v_mfma_f32_16x16x32_bf16 v[94:97], v[164:167], v[212:215], v[94:97]
	v_mfma_f32_16x16x32_bf16 v[90:93], v[172:175], v[212:215], v[90:93]
	v_mfma_f32_16x16x32_bf16 v[78:81], v[164:167], v[220:223], v[78:81]
	v_mfma_f32_16x16x32_bf16 v[74:77], v[172:175], v[220:223], v[74:77]
	s_setprio 0
	s_setprio 1
	v_mfma_f32_16x16x32_bf16 v[118:121], v[176:179], v[192:195], v[118:121]
	v_mfma_f32_16x16x32_bf16 v[114:117], v[184:187], v[192:195], v[114:117]
	v_mfma_f32_16x16x32_bf16 v[102:105], v[176:179], v[200:203], v[102:105]
	v_mfma_f32_16x16x32_bf16 v[98:101], v[184:187], v[200:203], v[98:101]
	v_mfma_f32_16x16x32_bf16 v[86:89], v[176:179], v[208:211], v[86:89]
	v_mfma_f32_16x16x32_bf16 v[82:85], v[184:187], v[208:211], v[82:85]
	v_mfma_f32_16x16x32_bf16 v[70:73], v[176:179], v[216:219], v[70:73]
	v_mfma_f32_16x16x32_bf16 v[66:69], v[184:187], v[216:219], v[66:69]
	v_mfma_f32_16x16x32_bf16 v[118:121], v[180:183], v[196:199], v[118:121]
	v_mfma_f32_16x16x32_bf16 v[114:117], v[188:191], v[196:199], v[114:117]
	v_mfma_f32_16x16x32_bf16 v[102:105], v[180:183], v[204:207], v[102:105]
	v_mfma_f32_16x16x32_bf16 v[98:101], v[188:191], v[204:207], v[98:101]
	v_mfma_f32_16x16x32_bf16 v[86:89], v[180:183], v[212:215], v[86:89]
	v_mfma_f32_16x16x32_bf16 v[82:85], v[188:191], v[212:215], v[82:85]
	v_mfma_f32_16x16x32_bf16 v[70:73], v[180:183], v[220:223], v[70:73]
	v_mfma_f32_16x16x32_bf16 v[66:69], v[188:191], v[220:223], v[66:69]
	s_setprio 0
	s_barrier
; #define PG8_STAGE(bufoff, gbase, voff) do { _Pragma("unroll") for (int _i = 0; _i < 2; ++_i) \
;         __builtin_amdgcn_global_load_lds((const unsigned*)((const char*)(gbase) + (voff)[_i]), (PG8_LAS unsigned*)(lds + (bufoff) + ldsw + _i * 8192), 16, 0, 0); } while (0)
; #define PG8_LDA(dst, b, h) do { _Pragma("unroll") for (int m = 0; m < 4; ++m) _Pragma("unroll") for (int k = 0; k < 2; ++k) dst[m][k] = *(const PG8_LAS bf16x8*)(lds + PG8_SA(b, h) + aoff + m * 2048 + k * 1024); } while (0)
; #define PG8_MMA(ai, bj, At, Bt) do { __builtin_amdgcn_s_setprio(1); _Pragma("unroll") for (int m = 0; m < 4; ++m) _Pragma("unroll") for (int n = 0; n < 2; ++n) _Pragma("unroll") for (int k = 0; k < 2; ++k) \
;         acc[ai][bj][m][n] = __builtin_amdgcn_mfma_f32_16x16x32_bf16(Bt[n][k], At[m][k], acc[ai][bj][m][n], 0, 0, 0); __builtin_amdgcn_s_setprio(0); } while (0)
; #define PG8_WAIT_V(n) asm volatile("s_waitcnt vmcnt(" #n ")" ::: "memory")
; #define PG8_WAIT_L(n) asm volatile("s_waitcnt lgkmcnt(" #n ")" ::: "memory")
; #define PG8_BAR __builtin_amdgcn_s_barrier()
; #define PG8_SCHED __builtin_amdgcn_sched_barrier(0)
; template <class Epi, class Sched, bool ALIGN_EPI = false, bool SP2 = false, bool AGM = false  >
; __device__ __forceinline__ void gemm_phase(PG8_LAS unsigned char* lds, const Gemm g, const Sched& S, const Epi& E) {
;     ...
;             PG8_LDA(At, 1, 1); PG8_STAGE(PG8_SB(1, 0), b3, voffB); PG8_STAGE(PG8_SB(1, 1), b3 + hstep, voffB); PG8_STAGE(PG8_SA(1, 0), a3, voffA);
;             PG8_WAIT_V(8); PG8_WAIT_L(0); PG8_BAR; PG8_MMA(1, 0, At, B0); PG8_MMA(1, 1, At, B1); PG8_BAR; PG8_SCHED;
;     ...
;         if constexpr (ALIGN_EPI) { if (wr == 0) PG8_BAR; }
	s_add_i32 s24, s71, s37
	v_lshl_add_u64 v[224:225], v[224:225], 0, s[12:13]
	s_mov_b32 m0, s24
	ds_read_b128 v[192:195], v159 offset:49152
	ds_read_b128 v[196:199], v159 offset:50176
	ds_read_b128 v[200:203], v159 offset:51200
	ds_read_b128 v[204:207], v159 offset:52224
	ds_read_b128 v[208:211], v159 offset:53248
	ds_read_b128 v[212:215], v159 offset:54272
	ds_read_b128 v[216:219], v159 offset:55296
	ds_read_b128 v[220:223], v159 offset:56320
	global_load_lds_dwordx4 v[224:225], off
	s_add_i32 m0, s24, 0x2000
	s_add_u32 s24, s30, 0x20080
	v_lshl_add_u64 v[224:225], v[226:227], 0, s[12:13]
	s_addc_u32 s25, s31, 0
	s_add_i32 s30, s72, s37
	global_load_lds_dwordx4 v[224:225], off
	v_lshl_add_u64 v[224:225], s[24:25], 0, v[134:135]
	s_mov_b32 m0, s30
	s_nop 0
	global_load_lds_dwordx4 v[224:225], off
	v_lshl_add_u64 v[224:225], s[24:25], 0, v[130:131]
	s_add_i32 m0, s30, 0x2000
	s_nop 0
	global_load_lds_dwordx4 v[224:225], off
	v_lshl_add_u64 v[224:225], s[28:29], 0, v[136:137]
	s_mov_b32 m0, s44
	s_nop 0
	global_load_lds_dwordx4 v[224:225], off
	v_lshl_add_u64 v[224:225], s[28:29], 0, v[132:133]
	s_mov_b32 m0, s45
	s_nop 0
	global_load_lds_dwordx4 v[224:225], off
	s_waitcnt vmcnt(8)
	s_waitcnt lgkmcnt(0)
	s_barrier
	s_setprio 1
	s_waitcnt lgkmcnt(0)
	v_mfma_f32_16x16x32_bf16 v[62:65], v[150:153], v[192:195], v[62:65]
	v_mfma_f32_16x16x32_bf16 v[58:61], v[168:171], v[192:195], v[58:61]
	v_mfma_f32_16x16x32_bf16 v[46:49], v[150:153], v[200:203], v[46:49]
	v_mfma_f32_16x16x32_bf16 v[42:45], v[168:171], v[200:203], v[42:45]
	v_mfma_f32_16x16x32_bf16 v[30:33], v[150:153], v[208:211], v[30:33]
	v_mfma_f32_16x16x32_bf16 v[26:29], v[168:171], v[208:211], v[26:29]
	v_mfma_f32_16x16x32_bf16 v[14:17], v[150:153], v[216:219], v[14:17]
	v_mfma_f32_16x16x32_bf16 v[10:13], v[168:171], v[216:219], v[10:13]
	v_mfma_f32_16x16x32_bf16 v[62:65], v[164:167], v[196:199], v[62:65]
	v_mfma_f32_16x16x32_bf16 v[58:61], v[172:175], v[196:199], v[58:61]
	v_mfma_f32_16x16x32_bf16 v[46:49], v[164:167], v[204:207], v[46:49]
	v_mfma_f32_16x16x32_bf16 v[42:45], v[172:175], v[204:207], v[42:45]
	v_mfma_f32_16x16x32_bf16 v[30:33], v[164:167], v[212:215], v[30:33]
	v_mfma_f32_16x16x32_bf16 v[26:29], v[172:175], v[212:215], v[26:29]
	v_mfma_f32_16x16x32_bf16 v[14:17], v[164:167], v[220:223], v[14:17]
	v_mfma_f32_16x16x32_bf16 v[10:13], v[172:175], v[220:223], v[10:13]
	s_setprio 0
	s_setprio 1
	v_mfma_f32_16x16x32_bf16 v[54:57], v[176:179], v[192:195], v[54:57]
	v_mfma_f32_16x16x32_bf16 v[50:53], v[184:187], v[192:195], v[50:53]
	v_mfma_f32_16x16x32_bf16 v[38:41], v[176:179], v[200:203], v[38:41]
	v_mfma_f32_16x16x32_bf16 v[34:37], v[184:187], v[200:203], v[34:37]
	v_mfma_f32_16x16x32_bf16 v[22:25], v[176:179], v[208:211], v[22:25]
	v_mfma_f32_16x16x32_bf16 v[18:21], v[184:187], v[208:211], v[18:21]
	v_mfma_f32_16x16x32_bf16 v[6:9], v[176:179], v[216:219], v[6:9]
	v_mfma_f32_16x16x32_bf16 v[2:5], v[184:187], v[216:219], v[2:5]
	v_mfma_f32_16x16x32_bf16 v[54:57], v[180:183], v[196:199], v[54:57]
	v_mfma_f32_16x16x32_bf16 v[50:53], v[188:191], v[196:199], v[50:53]
	v_mfma_f32_16x16x32_bf16 v[38:41], v[180:183], v[204:207], v[38:41]
	v_mfma_f32_16x16x32_bf16 v[34:37], v[188:191], v[204:207], v[34:37]
	v_mfma_f32_16x16x32_bf16 v[22:25], v[180:183], v[212:215], v[22:25]
	v_mfma_f32_16x16x32_bf16 v[18:21], v[188:191], v[212:215], v[18:21]
	v_mfma_f32_16x16x32_bf16 v[6:9], v[180:183], v[220:223], v[6:9]
	v_mfma_f32_16x16x32_bf16 v[2:5], v[188:191], v[220:223], v[2:5]
	s_add_i32 s70, s70, 2
	s_add_u32 s68, s68, 0x100
	s_addc_u32 s69, s69, 0
	s_cmp_gt_u32 s70, 5
	s_mov_b64 s[24:25], s[26:27]
	s_setprio 0
	s_barrier
	s_cbranch_scc0 .LBB0_677
	s_and_b64 vcc, exec, s[14:15]
	s_cbranch_vccz .LBB0_680
	s_barrier

; #define PG8_STAGE(bufoff, gbase, voff) do { _Pragma("unroll") for (int _i = 0; _i < 2; ++_i) \
;         __builtin_amdgcn_global_load_lds((const unsigned*)((const char*)(gbase) + (voff)[_i]), (PG8_LAS unsigned*)(lds + (bufoff) + ldsw + _i * 8192), 16, 0, 0); } while (0)
; #define PG8_LDA(dst, b, h) do { _Pragma("unroll") for (int m = 0; m < 4; ++m) _Pragma("unroll") for (int k = 0; k < 2; ++k) dst[m][k] = *(const PG8_LAS bf16x8*)(lds + PG8_SA(b, h) + aoff + m * 2048 + k * 1024); } while (0)
; #define PG8_LDB(dst, b, h) do { _Pragma("unroll") for (int n = 0; n < 2; ++n) _Pragma("unroll") for (int k = 0; k < 2; ++k) dst[n][k] = *(const PG8_LAS bf16x8*)(lds + PG8_SB(b, h) + boff + n * 2048 + k * 1024); } while (0)
; #define PG8_MMA(ai, bj, At, Bt) do { __builtin_amdgcn_s_setprio(1); _Pragma("unroll") for (int m = 0; m < 4; ++m) _Pragma("unroll") for (int n = 0; n < 2; ++n) _Pragma("unroll") for (int k = 0; k < 2; ++k) \
;         acc[ai][bj][m][n] = __builtin_amdgcn_mfma_f32_16x16x32_bf16(Bt[n][k], At[m][k], acc[ai][bj][m][n], 0, 0, 0); __builtin_amdgcn_s_setprio(0); } while (0)
; #define PG8_WAIT_V(n) asm volatile("s_waitcnt vmcnt(" #n ")" ::: "memory")
; #define PG8_WAIT_L(n) asm volatile("s_waitcnt lgkmcnt(" #n ")" ::: "memory")
; template <class Epi, class Sched, bool ALIGN_EPI = false, bool SP2 = false, bool AGM = false  >
; __device__ __forceinline__ void gemm_phase(PG8_LAS unsigned char* lds, const Gemm g, const Sched& S, const Epi& E) {
;     ...
;             const bool last = (t == nt - 2);
;             const char* a1 = cA + (size_t)(t + 1) * kstepA;
;             const char* a2 = last ? nA : cA + (size_t)(t + 2) * kstepA; const char* b2 = last ? nB : cB + (size_t)(t + 2) * kstep;
;             const char* a3 = a2 + kstepA; const char* b3 = b2 + kstep;
;             if (last && has_next) S.a_ready(nxt);
;             if constexpr (SP2) {
;             PG8_LDB(B0, 0, 0); PG8_LDB(B1, 0, 1); PG8_SCHED; PG8_LDA(At, 0, 0); PG8_STAGE(PG8_SA(1, 1), a1 + hstepA, voffA);
;             PG8_WAIT_V(8); PG8_WAIT_L(0); PG8_BAR; PG8_MMA(0, 0, At, B0); PG8_MMA(0, 1, At, B1); PG8_BAR; PG8_SCHED;
;             PG8_LDA(At, 0, 1); PG8_STAGE(PG8_SB(0, 0), b2, voffB); PG8_STAGE(PG8_SB(0, 1), b2 + hstep, voffB); PG8_STAGE(PG8_SA(0, 0), a2, voffA);
;             PG8_WAIT_V(8); PG8_WAIT_L(0); PG8_BAR; PG8_MMA(1, 0, At, B0); PG8_MMA(1, 1, At, B1); PG8_BAR; PG8_SCHED;
.LBB0_783:
	ds_read_b128 v[130:133], v186
	ds_read_b128 v[134:137], v186 offset:1024
	ds_read_b128 v[138:141], v186 offset:2048
	ds_read_b128 v[142:145], v186 offset:3072
	ds_read_b128 v[146:149], v187
	ds_read_b128 v[150:153], v187 offset:1024
	ds_read_b128 v[178:181], v187 offset:2048
	ds_read_b128 v[194:197], v187 offset:3072
	s_add_u32 s40, s38, 0xfffc0080
	s_addc_u32 s41, s39, -1
	s_cmp_eq_u32 s75, 12
	s_cselect_b32 s43, s5, s41
	s_cselect_b32 s42, s31, s40
	s_cselect_b32 s41, s29, s74
	s_cselect_b32 s40, s33, s62
	v_lshl_add_u64 v[182:183], s[38:39], 0, v[170:171]
	s_add_i32 m0, s44, 0xc000
	ds_read_b128 v[198:201], v188
	ds_read_b128 v[202:205], v188 offset:1024
	ds_read_b128 v[206:209], v188 offset:2048
	ds_read_b128 v[210:213], v188 offset:3072
	ds_read_b128 v[214:217], v188 offset:4096
	ds_read_b128 v[218:221], v188 offset:5120
	ds_read_b128 v[222:225], v188 offset:6144
	ds_read_b128 v[226:229], v188 offset:7168
	global_load_lds_dwordx4 v[182:183], off
	v_lshl_add_u64 v[182:183], s[38:39], 0, v[172:173]
	s_add_i32 m0, s44, 0xe000
	s_nop 0
	global_load_lds_dwordx4 v[182:183], off
	s_waitcnt vmcnt(8)
	s_waitcnt lgkmcnt(0)
	s_barrier
	s_setprio 1
	s_waitcnt lgkmcnt(0)
	v_mfma_f32_16x16x32_bf16 v[126:129], v[130:133], v[198:201], v[126:129]
	v_mfma_f32_16x16x32_bf16 v[122:125], v[138:141], v[198:201], v[122:125]
	v_mfma_f32_16x16x32_bf16 v[110:113], v[130:133], v[206:209], v[110:113]
	v_mfma_f32_16x16x32_bf16 v[106:109], v[138:141], v[206:209], v[106:109]
	v_mfma_f32_16x16x32_bf16 v[94:97], v[130:133], v[214:217], v[94:97]
	v_mfma_f32_16x16x32_bf16 v[90:93], v[138:141], v[214:217], v[90:93]
	v_mfma_f32_16x16x32_bf16 v[78:81], v[130:133], v[222:225], v[78:81]
	v_mfma_f32_16x16x32_bf16 v[74:77], v[138:141], v[222:225], v[74:77]
	v_mfma_f32_16x16x32_bf16 v[126:129], v[134:137], v[202:205], v[126:129]
	v_mfma_f32_16x16x32_bf16 v[122:125], v[142:145], v[202:205], v[122:125]
	v_mfma_f32_16x16x32_bf16 v[110:113], v[134:137], v[210:213], v[110:113]
	v_mfma_f32_16x16x32_bf16 v[106:109], v[142:145], v[210:213], v[106:109]
	v_mfma_f32_16x16x32_bf16 v[94:97], v[134:137], v[218:221], v[94:97]
	v_mfma_f32_16x16x32_bf16 v[90:93], v[142:145], v[218:221], v[90:93]
	v_mfma_f32_16x16x32_bf16 v[78:81], v[134:137], v[226:229], v[78:81]
	v_mfma_f32_16x16x32_bf16 v[74:77], v[142:145], v[226:229], v[74:77]
	s_setprio 0
	s_setprio 1
	v_mfma_f32_16x16x32_bf16 v[118:121], v[146:149], v[198:201], v[118:121]
	v_mfma_f32_16x16x32_bf16 v[114:117], v[178:181], v[198:201], v[114:117]
	v_mfma_f32_16x16x32_bf16 v[102:105], v[146:149], v[206:209], v[102:105]
	v_mfma_f32_16x16x32_bf16 v[98:101], v[178:181], v[206:209], v[98:101]
	v_mfma_f32_16x16x32_bf16 v[86:89], v[146:149], v[214:217], v[86:89]
	v_mfma_f32_16x16x32_bf16 v[82:85], v[178:181], v[214:217], v[82:85]
	v_mfma_f32_16x16x32_bf16 v[70:73], v[146:149], v[222:225], v[70:73]
	v_mfma_f32_16x16x32_bf16 v[66:69], v[178:181], v[222:225], v[66:69]
	v_mfma_f32_16x16x32_bf16 v[118:121], v[150:153], v[202:205], v[118:121]
	v_mfma_f32_16x16x32_bf16 v[114:117], v[194:197], v[202:205], v[114:117]
	v_mfma_f32_16x16x32_bf16 v[102:105], v[150:153], v[210:213], v[102:105]
	v_mfma_f32_16x16x32_bf16 v[98:101], v[194:197], v[210:213], v[98:101]
	v_mfma_f32_16x16x32_bf16 v[86:89], v[150:153], v[218:221], v[86:89]
	v_mfma_f32_16x16x32_bf16 v[82:85], v[194:197], v[218:221], v[82:85]
	v_mfma_f32_16x16x32_bf16 v[70:73], v[150:153], v[226:229], v[70:73]
	v_mfma_f32_16x16x32_bf16 v[66:69], v[194:197], v[226:229], v[66:69]
	s_setprio 0
	s_barrier
	s_add_i32 s76, s71, s3
	v_lshl_add_u64 v[182:183], s[40:41], 0, v[158:159]
	s_mov_b32 m0, s76
	ds_read_b128 v[198:201], v188 offset:16384
	ds_read_b128 v[202:205], v188 offset:17408
	ds_read_b128 v[206:209], v188 offset:18432
	ds_read_b128 v[210:213], v188 offset:19456
	ds_read_b128 v[214:217], v188 offset:20480
	ds_read_b128 v[218:221], v188 offset:21504
	ds_read_b128 v[222:225], v188 offset:22528
	ds_read_b128 v[226:229], v188 offset:23552
	global_load_lds_dwordx4 v[182:183], off
	s_add_i32 m0, s76, 0x2000
	s_add_u32 s76, s40, 0x40000
	v_lshl_add_u64 v[230:231], s[40:41], 0, v[162:163]
	s_addc_u32 s77, s41, 0
	s_add_i32 s78, s72, s3
	global_load_lds_dwordx4 v[230:231], off
	v_lshl_add_u64 v[232:233], s[76:77], 0, v[158:159]
	s_mov_b32 m0, s78
	v_lshl_add_u64 v[234:235], s[42:43], 0, v[160:161]
	global_load_lds_dwordx4 v[232:233], off
	v_lshl_add_u64 v[232:233], s[76:77], 0, v[162:163]
	s_add_i32 m0, s78, 0x2000
	s_nop 0
	global_load_lds_dwordx4 v[232:233], off
	v_lshl_add_u64 v[232:233], s[42:43], 0, v[156:157]
	s_mov_b32 m0, s44
	s_nop 0
	global_load_lds_dwordx4 v[232:233], off
	s_mov_b32 m0, s45
	s_nop 0
	global_load_lds_dwordx4 v[234:235], off
	s_waitcnt vmcnt(8)
	s_waitcnt lgkmcnt(0)
	s_barrier
; #define PG8_STAGE(bufoff, gbase, voff) do { _Pragma("unroll") for (int _i = 0; _i < 2; ++_i) \
;         __builtin_amdgcn_global_load_lds((const unsigned*)((const char*)(gbase) + (voff)[_i]), (PG8_LAS unsigned*)(lds + (bufoff) + ldsw + _i * 8192), 16, 0, 0); } while (0)
; #define PG8_LDA(dst, b, h) do { _Pragma("unroll") for (int m = 0; m < 4; ++m) _Pragma("unroll") for (int k = 0; k < 2; ++k) dst[m][k] = *(const PG8_LAS bf16x8*)(lds + PG8_SA(b, h) + aoff + m * 2048 + k * 1024); } while (0)
; #define PG8_LDB(dst, b, h) do { _Pragma("unroll") for (int n = 0; n < 2; ++n) _Pragma("unroll") for (int k = 0; k < 2; ++k) dst[n][k] = *(const PG8_LAS bf16x8*)(lds + PG8_SB(b, h) + boff + n * 2048 + k * 1024); } while (0)
; #define PG8_MMA(ai, bj, At, Bt) do { __builtin_amdgcn_s_setprio(1); _Pragma("unroll") for (int m = 0; m < 4; ++m) _Pragma("unroll") for (int n = 0; n < 2; ++n) _Pragma("unroll") for (int k = 0; k < 2; ++k) \
;         acc[ai][bj][m][n] = __builtin_amdgcn_mfma_f32_16x16x32_bf16(Bt[n][k], At[m][k], acc[ai][bj][m][n], 0, 0, 0); __builtin_amdgcn_s_setprio(0); } while (0)
; #define PG8_WAIT_V(n) asm volatile("s_waitcnt vmcnt(" #n ")" ::: "memory")
; #define PG8_WAIT_L(n) asm volatile("s_waitcnt lgkmcnt(" #n ")" ::: "memory")
; #define PG8_BAR __builtin_amdgcn_s_barrier()
; #define PG8_SCHED __builtin_amdgcn_sched_barrier(0)
; template <class Epi, class Sched, bool ALIGN_EPI = false, bool SP2 = false, bool AGM = false  >
; __device__ __forceinline__ void gemm_phase(PG8_LAS unsigned char* lds, const Gemm g, const Sched& S, const Epi& E) {
;     ...
;             PG8_WAIT_V(8); PG8_WAIT_L(0); PG8_BAR; PG8_MMA(1, 0, At, B0); PG8_MMA(1, 1, At, B1); PG8_BAR; PG8_SCHED;
;             PG8_LDB(B0, 1, 0); PG8_LDB(B1, 1, 1); PG8_SCHED; PG8_LDA(At, 1, 0); PG8_STAGE(PG8_SA(0, 1), a2 + hstepA, voffA);
;             PG8_WAIT_V(8); PG8_WAIT_L(0); PG8_BAR; PG8_MMA(0, 0, At, B0); PG8_MMA(0, 1, At, B1); PG8_BAR; PG8_SCHED;
	s_setprio 1
	s_waitcnt lgkmcnt(0)
	v_mfma_f32_16x16x32_bf16 v[62:65], v[130:133], v[198:201], v[62:65]
	v_mfma_f32_16x16x32_bf16 v[58:61], v[138:141], v[198:201], v[58:61]
	v_mfma_f32_16x16x32_bf16 v[46:49], v[130:133], v[206:209], v[46:49]
	v_mfma_f32_16x16x32_bf16 v[42:45], v[138:141], v[206:209], v[42:45]
	v_mfma_f32_16x16x32_bf16 v[30:33], v[130:133], v[214:217], v[30:33]
	v_mfma_f32_16x16x32_bf16 v[26:29], v[138:141], v[214:217], v[26:29]
	v_mfma_f32_16x16x32_bf16 v[14:17], v[130:133], v[222:225], v[14:17]
	v_mfma_f32_16x16x32_bf16 v[10:13], v[138:141], v[222:225], v[10:13]
	v_mfma_f32_16x16x32_bf16 v[62:65], v[134:137], v[202:205], v[62:65]
	v_mfma_f32_16x16x32_bf16 v[58:61], v[142:145], v[202:205], v[58:61]
	v_mfma_f32_16x16x32_bf16 v[46:49], v[134:137], v[210:213], v[46:49]
	v_mfma_f32_16x16x32_bf16 v[42:45], v[142:145], v[210:213], v[42:45]
	v_mfma_f32_16x16x32_bf16 v[30:33], v[134:137], v[218:221], v[30:33]
	v_mfma_f32_16x16x32_bf16 v[26:29], v[142:145], v[218:221], v[26:29]
	v_mfma_f32_16x16x32_bf16 v[14:17], v[134:137], v[226:229], v[14:17]
	v_mfma_f32_16x16x32_bf16 v[10:13], v[142:145], v[226:229], v[10:13]
	s_setprio 0
	s_setprio 1
	v_mfma_f32_16x16x32_bf16 v[54:57], v[146:149], v[198:201], v[54:57]
	v_mfma_f32_16x16x32_bf16 v[50:53], v[178:181], v[198:201], v[50:53]
	v_mfma_f32_16x16x32_bf16 v[38:41], v[146:149], v[206:209], v[38:41]
	v_mfma_f32_16x16x32_bf16 v[34:37], v[178:181], v[206:209], v[34:37]
	v_mfma_f32_16x16x32_bf16 v[22:25], v[146:149], v[214:217], v[22:25]
	v_mfma_f32_16x16x32_bf16 v[18:21], v[178:181], v[214:217], v[18:21]
	v_mfma_f32_16x16x32_bf16 v[6:9], v[146:149], v[222:225], v[6:9]
	v_mfma_f32_16x16x32_bf16 v[2:5], v[178:181], v[222:225], v[2:5]
	v_mfma_f32_16x16x32_bf16 v[54:57], v[150:153], v[202:205], v[54:57]
	v_mfma_f32_16x16x32_bf16 v[50:53], v[194:197], v[202:205], v[50:53]
	v_mfma_f32_16x16x32_bf16 v[38:41], v[150:153], v[210:213], v[38:41]
	v_mfma_f32_16x16x32_bf16 v[34:37], v[194:197], v[210:213], v[34:37]
	v_mfma_f32_16x16x32_bf16 v[22:25], v[150:153], v[218:221], v[22:25]
	v_mfma_f32_16x16x32_bf16 v[18:21], v[194:197], v[218:221], v[18:21]
	v_mfma_f32_16x16x32_bf16 v[6:9], v[150:153], v[226:229], v[6:9]
	v_mfma_f32_16x16x32_bf16 v[2:5], v[194:197], v[226:229], v[2:5]
	s_setprio 0
	s_barrier
	s_add_i32 s76, 0, 0x18000
	s_add_i32 s77, 0, 0x1c000
	v_add_u32_e32 v142, s76, v184
	v_add_u32_e32 v164, s77, v184
	ds_read_b128 v[130:133], v142
	ds_read_b128 v[134:137], v142 offset:1024
	ds_read_b128 v[138:141], v142 offset:2048
	ds_read_b128 v[142:145], v142 offset:3072
	ds_read_b128 v[146:149], v164
	ds_read_b128 v[150:153], v164 offset:1024
	ds_read_b128 v[178:181], v164 offset:2048
	ds_read_b128 v[194:197], v164 offset:3072
	s_add_u32 s42, s42, 0x40000
	s_addc_u32 s43, s43, 0
	s_mov_b32 m0, s53
	v_lshl_add_u64 v[236:237], s[42:43], 0, v[156:157]
	ds_read_b128 v[198:201], v188 offset:32768
	ds_read_b128 v[202:205], v188 offset:33792
	ds_read_b128 v[206:209], v188 offset:34816
	ds_read_b128 v[210:213], v188 offset:35840
	ds_read_b128 v[214:217], v188 offset:36864
	ds_read_b128 v[218:221], v188 offset:37888
	ds_read_b128 v[222:225], v188 offset:38912
	ds_read_b128 v[226:229], v188 offset:39936
	global_load_lds_dwordx4 v[236:237], off
	v_lshl_add_u64 v[236:237], s[42:43], 0, v[160:161]
	s_mov_b32 m0, s54
	s_nop 0
	global_load_lds_dwordx4 v[236:237], off
	s_waitcnt vmcnt(8)
	s_waitcnt lgkmcnt(0)
	s_barrier
	s_setprio 1
	s_waitcnt lgkmcnt(0)
	v_mfma_f32_16x16x32_bf16 v[126:129], v[130:133], v[198:201], v[126:129]
	v_mfma_f32_16x16x32_bf16 v[122:125], v[138:141], v[198:201], v[122:125]
	v_mfma_f32_16x16x32_bf16 v[110:113], v[130:133], v[206:209], v[110:113]
	v_mfma_f32_16x16x32_bf16 v[106:109], v[138:141], v[206:209], v[106:109]
	v_mfma_f32_16x16x32_bf16 v[94:97], v[130:133], v[214:217], v[94:97]
	v_mfma_f32_16x16x32_bf16 v[90:93], v[138:141], v[214:217], v[90:93]
	v_mfma_f32_16x16x32_bf16 v[78:81], v[130:133], v[222:225], v[78:81]
	v_mfma_f32_16x16x32_bf16 v[74:77], v[138:141], v[222:225], v[74:77]
	v_mfma_f32_16x16x32_bf16 v[126:129], v[134:137], v[202:205], v[126:129]
	v_mfma_f32_16x16x32_bf16 v[122:125], v[142:145], v[202:205], v[122:125]
	v_mfma_f32_16x16x32_bf16 v[110:113], v[134:137], v[210:213], v[110:113]
	v_mfma_f32_16x16x32_bf16 v[106:109], v[142:145], v[210:213], v[106:109]
	v_mfma_f32_16x16x32_bf16 v[94:97], v[134:137], v[218:221], v[94:97]
	v_mfma_f32_16x16x32_bf16 v[90:93], v[142:145], v[218:221], v[90:93]
	v_mfma_f32_16x16x32_bf16 v[78:81], v[134:137], v[226:229], v[78:81]
	v_mfma_f32_16x16x32_bf16 v[74:77], v[142:145], v[226:229], v[74:77]
	s_setprio 0
	s_setprio 1
	v_mfma_f32_16x16x32_bf16 v[118:121], v[146:149], v[198:201], v[118:121]
	v_mfma_f32_16x16x32_bf16 v[114:117], v[178:181], v[198:201], v[114:117]
	v_mfma_f32_16x16x32_bf16 v[102:105], v[146:149], v[206:209], v[102:105]
	v_mfma_f32_16x16x32_bf16 v[98:101], v[178:181], v[206:209], v[98:101]
	v_mfma_f32_16x16x32_bf16 v[86:89], v[146:149], v[214:217], v[86:89]
	v_mfma_f32_16x16x32_bf16 v[82:85], v[178:181], v[214:217], v[82:85]
	v_mfma_f32_16x16x32_bf16 v[70:73], v[146:149], v[222:225], v[70:73]
	v_mfma_f32_16x16x32_bf16 v[66:69], v[178:181], v[222:225], v[66:69]
	v_mfma_f32_16x16x32_bf16 v[118:121], v[150:153], v[202:205], v[118:121]
	v_mfma_f32_16x16x32_bf16 v[114:117], v[194:197], v[202:205], v[114:117]
	v_mfma_f32_16x16x32_bf16 v[102:105], v[150:153], v[210:213], v[102:105]
	v_mfma_f32_16x16x32_bf16 v[98:101], v[194:197], v[210:213], v[98:101]
	v_mfma_f32_16x16x32_bf16 v[86:89], v[150:153], v[218:221], v[86:89]
	v_mfma_f32_16x16x32_bf16 v[82:85], v[194:197], v[218:221], v[82:85]
	v_mfma_f32_16x16x32_bf16 v[70:73], v[150:153], v[226:229], v[70:73]
	v_mfma_f32_16x16x32_bf16 v[66:69], v[194:197], v[226:229], v[66:69]
	s_setprio 0
	s_barrier
; #define PG8_STAGE(bufoff, gbase, voff) do { _Pragma("unroll") for (int _i = 0; _i < 2; ++_i) \
;         __builtin_amdgcn_global_load_lds((const unsigned*)((const char*)(gbase) + (voff)[_i]), (PG8_LAS unsigned*)(lds + (bufoff) + ldsw + _i * 8192), 16, 0, 0); } while (0)
; #define PG8_LDA(dst, b, h) do { _Pragma("unroll") for (int m = 0; m < 4; ++m) _Pragma("unroll") for (int k = 0; k < 2; ++k) dst[m][k] = *(const PG8_LAS bf16x8*)(lds + PG8_SA(b, h) + aoff + m * 2048 + k * 1024); } while (0)
; #define PG8_MMA(ai, bj, At, Bt) do { __builtin_amdgcn_s_setprio(1); _Pragma("unroll") for (int m = 0; m < 4; ++m) _Pragma("unroll") for (int n = 0; n < 2; ++n) _Pragma("unroll") for (int k = 0; k < 2; ++k) \
;         acc[ai][bj][m][n] = __builtin_amdgcn_mfma_f32_16x16x32_bf16(Bt[n][k], At[m][k], acc[ai][bj][m][n], 0, 0, 0); __builtin_amdgcn_s_setprio(0); } while (0)
; #define PG8_WAIT_V(n) asm volatile("s_waitcnt vmcnt(" #n ")" ::: "memory")
; #define PG8_WAIT_L(n) asm volatile("s_waitcnt lgkmcnt(" #n ")" ::: "memory")
; #define PG8_BAR __builtin_amdgcn_s_barrier()
; #define PG8_SCHED __builtin_amdgcn_sched_barrier(0)
; template <class Epi, class Sched, bool ALIGN_EPI = false, bool SP2 = false, bool AGM = false  >
; __device__ __forceinline__ void gemm_phase(PG8_LAS unsigned char* lds, const Gemm g, const Sched& S, const Epi& E) {
;     ...
;             PG8_LDA(At, 1, 1); PG8_STAGE(PG8_SB(1, 0), b3, voffB); PG8_STAGE(PG8_SB(1, 1), b3 + hstep, voffB); PG8_STAGE(PG8_SA(1, 0), a3, voffA);
;             PG8_WAIT_V(8); PG8_WAIT_L(0); PG8_BAR; PG8_MMA(1, 0, At, B0); PG8_MMA(1, 1, At, B1); PG8_BAR; PG8_SCHED;
;     ...
;         if constexpr (ALIGN_EPI) { if (wr == 0) PG8_BAR; }
	s_add_i32 s42, s76, s3
	v_lshl_add_u64 v[182:183], v[182:183], 0, s[24:25]
	s_mov_b32 m0, s42
	ds_read_b128 v[198:201], v188 offset:49152
	ds_read_b128 v[202:205], v188 offset:50176
	ds_read_b128 v[206:209], v188 offset:51200
	ds_read_b128 v[210:213], v188 offset:52224
	ds_read_b128 v[214:217], v188 offset:53248
	ds_read_b128 v[218:221], v188 offset:54272
	ds_read_b128 v[222:225], v188 offset:55296
	ds_read_b128 v[226:229], v188 offset:56320
	global_load_lds_dwordx4 v[182:183], off
	s_add_i32 m0, s42, 0x2000
	s_add_u32 s40, s40, 0x40080
	v_lshl_add_u64 v[182:183], v[230:231], 0, s[24:25]
	s_addc_u32 s41, s41, 0
	s_add_i32 s42, s77, s3
	global_load_lds_dwordx4 v[182:183], off
	v_lshl_add_u64 v[182:183], s[40:41], 0, v[158:159]
	s_mov_b32 m0, s42
	s_nop 0
	global_load_lds_dwordx4 v[182:183], off
	v_lshl_add_u64 v[182:183], s[40:41], 0, v[162:163]
	s_add_i32 m0, s42, 0x2000
	s_nop 0
	global_load_lds_dwordx4 v[182:183], off
	v_lshl_add_u64 v[182:183], v[232:233], 0, s[24:25]
	s_mov_b32 m0, s60
	s_nop 0
	global_load_lds_dwordx4 v[182:183], off
	v_lshl_add_u64 v[182:183], v[234:235], 0, s[24:25]
	s_mov_b32 m0, s61
	s_nop 0
	global_load_lds_dwordx4 v[182:183], off
	s_waitcnt vmcnt(8)
	s_waitcnt lgkmcnt(0)
	s_barrier
	s_setprio 1
	s_waitcnt lgkmcnt(0)
	v_mfma_f32_16x16x32_bf16 v[62:65], v[130:133], v[198:201], v[62:65]
	v_mfma_f32_16x16x32_bf16 v[58:61], v[138:141], v[198:201], v[58:61]
	v_mfma_f32_16x16x32_bf16 v[46:49], v[130:133], v[206:209], v[46:49]
	v_mfma_f32_16x16x32_bf16 v[42:45], v[138:141], v[206:209], v[42:45]
	v_mfma_f32_16x16x32_bf16 v[30:33], v[130:133], v[214:217], v[30:33]
	v_mfma_f32_16x16x32_bf16 v[26:29], v[138:141], v[214:217], v[26:29]
	v_mfma_f32_16x16x32_bf16 v[14:17], v[130:133], v[222:225], v[14:17]
	v_mfma_f32_16x16x32_bf16 v[10:13], v[138:141], v[222:225], v[10:13]
	v_mfma_f32_16x16x32_bf16 v[62:65], v[134:137], v[202:205], v[62:65]
	v_mfma_f32_16x16x32_bf16 v[58:61], v[142:145], v[202:205], v[58:61]
	v_mfma_f32_16x16x32_bf16 v[46:49], v[134:137], v[210:213], v[46:49]
	v_mfma_f32_16x16x32_bf16 v[42:45], v[142:145], v[210:213], v[42:45]
	v_mfma_f32_16x16x32_bf16 v[30:33], v[134:137], v[218:221], v[30:33]
	v_mfma_f32_16x16x32_bf16 v[26:29], v[142:145], v[218:221], v[26:29]
	v_mfma_f32_16x16x32_bf16 v[14:17], v[134:137], v[226:229], v[14:17]
	v_mfma_f32_16x16x32_bf16 v[10:13], v[142:145], v[226:229], v[10:13]
	s_setprio 0
	s_setprio 1
	v_mfma_f32_16x16x32_bf16 v[54:57], v[146:149], v[198:201], v[54:57]
	v_mfma_f32_16x16x32_bf16 v[50:53], v[178:181], v[198:201], v[50:53]
	v_mfma_f32_16x16x32_bf16 v[38:41], v[146:149], v[206:209], v[38:41]
	v_mfma_f32_16x16x32_bf16 v[34:37], v[178:181], v[206:209], v[34:37]
	v_mfma_f32_16x16x32_bf16 v[22:25], v[146:149], v[214:217], v[22:25]
	v_mfma_f32_16x16x32_bf16 v[18:21], v[178:181], v[214:217], v[18:21]
	v_mfma_f32_16x16x32_bf16 v[6:9], v[146:149], v[222:225], v[6:9]
	v_mfma_f32_16x16x32_bf16 v[2:5], v[178:181], v[222:225], v[2:5]
	v_mfma_f32_16x16x32_bf16 v[54:57], v[150:153], v[202:205], v[54:57]
	v_mfma_f32_16x16x32_bf16 v[50:53], v[194:197], v[202:205], v[50:53]
	v_mfma_f32_16x16x32_bf16 v[38:41], v[150:153], v[210:213], v[38:41]
	v_mfma_f32_16x16x32_bf16 v[34:37], v[194:197], v[210:213], v[34:37]
	v_mfma_f32_16x16x32_bf16 v[22:25], v[150:153], v[218:221], v[22:25]
	v_mfma_f32_16x16x32_bf16 v[18:21], v[194:197], v[218:221], v[18:21]
	v_mfma_f32_16x16x32_bf16 v[6:9], v[150:153], v[226:229], v[6:9]
	v_mfma_f32_16x16x32_bf16 v[2:5], v[194:197], v[226:229], v[2:5]
	s_add_i32 s75, s75, 2
	s_add_u32 s38, s38, 0x100
	s_addc_u32 s39, s39, 0
	s_add_u32 s62, s62, 0x100
	s_addc_u32 s74, s74, 0
	s_cmp_gt_u32 s75, 13
	s_setprio 0
	s_barrier
	s_cbranch_scc0 .LBB0_783
	s_and_b64 vcc, exec, s[26:27]
	s_cbranch_vccz .LBB0_786
	s_barrier

; #define PG8_STAGE(bufoff, gbase, voff) do { _Pragma("unroll") for (int _i = 0; _i < 2; ++_i) \
;         __builtin_amdgcn_global_load_lds((const unsigned*)((const char*)(gbase) + (voff)[_i]), (PG8_LAS unsigned*)(lds + (bufoff) + ldsw + _i * 8192), 16, 0, 0); } while (0)
; #define PG8_LDA(dst, b, h) do { _Pragma("unroll") for (int m = 0; m < 4; ++m) _Pragma("unroll") for (int k = 0; k < 2; ++k) dst[m][k] = *(const PG8_LAS bf16x8*)(lds + PG8_SA(b, h) + aoff + m * 2048 + k * 1024); } while (0)
; #define PG8_WAIT_V(n) asm volatile("s_waitcnt vmcnt(" #n ")" ::: "memory")
; #define PG8_WAIT_L(n) asm volatile("s_waitcnt lgkmcnt(" #n ")" ::: "memory")
; #define PG8_BAR __builtin_amdgcn_s_barrier()
; template <class Epi, class Sched, bool ALIGN_EPI = false, bool SP2 = false, bool AGM = false  >
; __device__ __forceinline__ void gemm_phase(PG8_LAS unsigned char* lds, const Gemm g, const Sched& S, const Epi& E) {
;     ...
;         const bool has_next = S.next(ui + 1, nxt);
;         const char* nA = has_next ? (const char*)g.A + (size_t)nxt.pm * tstepA : cA; const char* nB = has_next ? (const char*)g.Bt + (size_t)nxt.pn * tstep : cB;
;         for (int t = 0; t < nt; t += 2) {
;             const bool last = (t == nt - 2);
;             const char* a1 = cA + (size_t)(t + 1) * kstepA;
;             const char* a2 = last ? nA : cA + (size_t)(t + 2) * kstepA; const char* b2 = last ? nB : cB + (size_t)(t + 2) * kstep;
;             const char* a3 = a2 + kstepA; const char* b3 = b2 + kstep;
;             if (last && has_next) S.a_ready(nxt);
;             if constexpr (SP2) {
;             PG8_LDB(B0, 0, 0); PG8_LDB(B1, 0, 1); PG8_SCHED; PG8_LDA(At, 0, 0); PG8_STAGE(PG8_SA(1, 1), a1 + hstepA, voffA);
;             PG8_WAIT_V(8); PG8_WAIT_L(0); PG8_BAR; PG8_MMA(0, 0, At, B0); PG8_MMA(0, 1, At, B1); PG8_BAR; PG8_SCHED;
;             PG8_LDA(At, 0, 1); PG8_STAGE(PG8_SB(0, 0), b2, voffB); PG8_STAGE(PG8_SB(0, 1), b2 + hstep, voffB); PG8_STAGE(PG8_SA(0, 0), a2, voffA);
;             PG8_WAIT_V(8); PG8_WAIT_L(0); PG8_BAR; PG8_MMA(1, 0, At, B0); PG8_MMA(1, 1, At, B1); PG8_BAR; PG8_SCHED;
;     ...
; #pragma unroll
;         for (int a = 0; a < 2; ++a)
; #pragma unroll
;             for (int b = 0; b < 2; ++b)
; #pragma unroll
;                 for (int m = 0; m < 4; ++m)
; #pragma unroll
;                     for (int n = 0; n < 2; ++n) acc[a][b][m][n] = (f32x4){0.f, 0.f, 0.f, 0.f};
.LBB0_876:
	s_ashr_i32 s23, s22, 31
	s_lshl_b64 s[24:25], s[22:23], 19
	s_add_u32 s24, s46, s24
	s_addc_u32 s25, s47, s25
	s_and_b64 s[26:27], s[0:1], exec
	s_cselect_b32 s23, s25, s29
	s_cselect_b32 s64, s24, s28
	s_ashr_i32 s21, s20, 31
	s_lshl_b64 s[26:27], s[20:21], 19
	s_add_u32 s26, s10, s26
	s_addc_u32 s27, s11, s27
	s_and_b64 s[34:35], s[0:1], exec
	s_cselect_b32 s21, s27, s31
	s_cselect_b32 s65, s26, s30
	s_add_u32 s28, s28, 0x40080
	s_addc_u32 s29, s29, 0
	s_add_u32 s66, s30, 0x100
	s_addc_u32 s67, s31, 0
	s_mov_b32 s68, -2
	s_waitcnt vmcnt(0)
	s_waitcnt lgkmcnt(0)
	ds_read_b128 v[148:151], v156
	ds_read_b128 v[164:167], v156 offset:1024
	ds_read_b128 v[168:171], v156 offset:2048
	ds_read_b128 v[172:175], v156 offset:3072
	ds_read_b128 v[176:179], v157
	ds_read_b128 v[180:183], v157 offset:1024
	ds_read_b128 v[184:187], v157 offset:2048
	ds_read_b128 v[188:191], v157 offset:3072
	s_add_u32 s30, s28, 0xfffc0080
	s_addc_u32 s31, s29, -1
	s_cmp_eq_u32 s68, 12
	s_cselect_b32 s35, s23, s31
	s_cselect_b32 s34, s64, s30
	s_cselect_b32 s31, s21, s67
	s_cselect_b32 s30, s65, s66
	v_lshl_add_u64 v[224:225], s[28:29], 0, v[140:141]
	s_add_i32 m0, s37, 0xc000
	ds_read_b128 v[192:195], v158
	ds_read_b128 v[196:199], v158 offset:1024
	ds_read_b128 v[200:203], v158 offset:2048
	ds_read_b128 v[204:207], v158 offset:3072
	ds_read_b128 v[208:211], v158 offset:4096
	ds_read_b128 v[212:215], v158 offset:5120
	ds_read_b128 v[216:219], v158 offset:6144
	ds_read_b128 v[220:223], v158 offset:7168
	global_load_lds_dwordx4 v[224:225], off
	v_lshl_add_u64 v[224:225], s[28:29], 0, v[142:143]
	s_add_i32 m0, s37, 0xe000
	s_nop 0
	global_load_lds_dwordx4 v[224:225], off
	s_waitcnt vmcnt(8)
	s_waitcnt lgkmcnt(0)
	s_barrier
	s_setprio 1
	s_waitcnt lgkmcnt(0)
	v_mfma_f32_16x16x32_bf16 v[126:129], v[148:151], v[192:195], 0
	v_mfma_f32_16x16x32_bf16 v[122:125], v[168:171], v[192:195], 0
	v_mfma_f32_16x16x32_bf16 v[110:113], v[148:151], v[200:203], 0
	v_mfma_f32_16x16x32_bf16 v[106:109], v[168:171], v[200:203], 0
	v_mfma_f32_16x16x32_bf16 v[94:97], v[148:151], v[208:211], 0
	v_mfma_f32_16x16x32_bf16 v[90:93], v[168:171], v[208:211], 0
	v_mfma_f32_16x16x32_bf16 v[78:81], v[148:151], v[216:219], 0
	v_mfma_f32_16x16x32_bf16 v[74:77], v[168:171], v[216:219], 0
	v_mfma_f32_16x16x32_bf16 v[126:129], v[164:167], v[196:199], v[126:129]
	v_mfma_f32_16x16x32_bf16 v[122:125], v[172:175], v[196:199], v[122:125]
	v_mfma_f32_16x16x32_bf16 v[110:113], v[164:167], v[204:207], v[110:113]
	v_mfma_f32_16x16x32_bf16 v[106:109], v[172:175], v[204:207], v[106:109]
	v_mfma_f32_16x16x32_bf16 v[94:97], v[164:167], v[212:215], v[94:97]
	v_mfma_f32_16x16x32_bf16 v[90:93], v[172:175], v[212:215], v[90:93]
	v_mfma_f32_16x16x32_bf16 v[78:81], v[164:167], v[220:223], v[78:81]
	v_mfma_f32_16x16x32_bf16 v[74:77], v[172:175], v[220:223], v[74:77]
	s_setprio 0
	s_setprio 1
	v_mfma_f32_16x16x32_bf16 v[118:121], v[176:179], v[192:195], 0
	v_mfma_f32_16x16x32_bf16 v[114:117], v[184:187], v[192:195], 0
	v_mfma_f32_16x16x32_bf16 v[102:105], v[176:179], v[200:203], 0
	v_mfma_f32_16x16x32_bf16 v[98:101], v[184:187], v[200:203], 0
	v_mfma_f32_16x16x32_bf16 v[86:89], v[176:179], v[208:211], 0
	v_mfma_f32_16x16x32_bf16 v[82:85], v[184:187], v[208:211], 0
	v_mfma_f32_16x16x32_bf16 v[70:73], v[176:179], v[216:219], 0
	v_mfma_f32_16x16x32_bf16 v[66:69], v[184:187], v[216:219], 0
	v_mfma_f32_16x16x32_bf16 v[118:121], v[180:183], v[196:199], v[118:121]
	v_mfma_f32_16x16x32_bf16 v[114:117], v[188:191], v[196:199], v[114:117]
	v_mfma_f32_16x16x32_bf16 v[102:105], v[180:183], v[204:207], v[102:105]
	v_mfma_f32_16x16x32_bf16 v[98:101], v[188:191], v[204:207], v[98:101]
	v_mfma_f32_16x16x32_bf16 v[86:89], v[180:183], v[212:215], v[86:89]
	v_mfma_f32_16x16x32_bf16 v[82:85], v[188:191], v[212:215], v[82:85]
	v_mfma_f32_16x16x32_bf16 v[70:73], v[180:183], v[220:223], v[70:73]
	v_mfma_f32_16x16x32_bf16 v[66:69], v[188:191], v[220:223], v[66:69]
	s_setprio 0
	s_barrier
	s_add_i32 s69, s53, s3
	v_lshl_add_u64 v[224:225], s[30:31], 0, v[134:135]
	s_mov_b32 m0, s69
	ds_read_b128 v[192:195], v158 offset:16384
	ds_read_b128 v[196:199], v158 offset:17408
	ds_read_b128 v[200:203], v158 offset:18432
	ds_read_b128 v[204:207], v158 offset:19456
	ds_read_b128 v[208:211], v158 offset:20480
	ds_read_b128 v[212:215], v158 offset:21504
	ds_read_b128 v[216:219], v158 offset:22528
	ds_read_b128 v[220:223], v158 offset:23552
	global_load_lds_dwordx4 v[224:225], off
	s_add_i32 m0, s69, 0x2000
	s_add_u32 s70, s30, 0x40000
	v_lshl_add_u64 v[226:227], s[30:31], 0, v[130:131]
	s_addc_u32 s71, s31, 0
	s_add_i32 s69, s54, s3
	global_load_lds_dwordx4 v[226:227], off
	v_lshl_add_u64 v[228:229], s[70:71], 0, v[134:135]
	s_mov_b32 m0, s69
	v_lshl_add_u64 v[230:231], s[34:35], 0, v[132:133]
	global_load_lds_dwordx4 v[228:229], off
	v_lshl_add_u64 v[228:229], s[70:71], 0, v[130:131]
	s_add_i32 m0, s69, 0x2000
	s_nop 0
	global_load_lds_dwordx4 v[228:229], off
	v_lshl_add_u64 v[228:229], s[34:35], 0, v[136:137]
	s_mov_b32 m0, s37
	s_nop 0
	global_load_lds_dwordx4 v[228:229], off
	s_mov_b32 m0, s38
	s_nop 0
	global_load_lds_dwordx4 v[230:231], off
	s_waitcnt vmcnt(8)
	s_waitcnt lgkmcnt(0)
	s_barrier
; #define PG8_STAGE(bufoff, gbase, voff) do { _Pragma("unroll") for (int _i = 0; _i < 2; ++_i) \
;         __builtin_amdgcn_global_load_lds((const unsigned*)((const char*)(gbase) + (voff)[_i]), (PG8_LAS unsigned*)(lds + (bufoff) + ldsw + _i * 8192), 16, 0, 0); } while (0)
; #define PG8_LDA(dst, b, h) do { _Pragma("unroll") for (int m = 0; m < 4; ++m) _Pragma("unroll") for (int k = 0; k < 2; ++k) dst[m][k] = *(const PG8_LAS bf16x8*)(lds + PG8_SA(b, h) + aoff + m * 2048 + k * 1024); } while (0)
; #define PG8_LDB(dst, b, h) do { _Pragma("unroll") for (int n = 0; n < 2; ++n) _Pragma("unroll") for (int k = 0; k < 2; ++k) dst[n][k] = *(const PG8_LAS bf16x8*)(lds + PG8_SB(b, h) + boff + n * 2048 + k * 1024); } while (0)
; #define PG8_MMA(ai, bj, At, Bt) do { __builtin_amdgcn_s_setprio(1); _Pragma("unroll") for (int m = 0; m < 4; ++m) _Pragma("unroll") for (int n = 0; n < 2; ++n) _Pragma("unroll") for (int k = 0; k < 2; ++k) \
;         acc[ai][bj][m][n] = __builtin_amdgcn_mfma_f32_16x16x32_bf16(Bt[n][k], At[m][k], acc[ai][bj][m][n], 0, 0, 0); __builtin_amdgcn_s_setprio(0); } while (0)
; #define PG8_WAIT_V(n) asm volatile("s_waitcnt vmcnt(" #n ")" ::: "memory")
; #define PG8_WAIT_L(n) asm volatile("s_waitcnt lgkmcnt(" #n ")" ::: "memory")
; #define PG8_BAR __builtin_amdgcn_s_barrier()
; #define PG8_SCHED __builtin_amdgcn_sched_barrier(0)
; template <class Epi, class Sched, bool ALIGN_EPI = false, bool SP2 = false, bool AGM = false  >
; __device__ __forceinline__ void gemm_phase(PG8_LAS unsigned char* lds, const Gemm g, const Sched& S, const Epi& E) {
;     ...
;             PG8_WAIT_V(8); PG8_WAIT_L(0); PG8_BAR; PG8_MMA(1, 0, At, B0); PG8_MMA(1, 1, At, B1); PG8_BAR; PG8_SCHED;
;             PG8_LDB(B0, 1, 0); PG8_LDB(B1, 1, 1); PG8_SCHED; PG8_LDA(At, 1, 0); PG8_STAGE(PG8_SA(0, 1), a2 + hstepA, voffA);
;             PG8_WAIT_V(8); PG8_WAIT_L(0); PG8_BAR; PG8_MMA(0, 0, At, B0); PG8_MMA(0, 1, At, B1); PG8_BAR; PG8_SCHED;
	s_setprio 1
	s_waitcnt lgkmcnt(0)
	v_mfma_f32_16x16x32_bf16 v[62:65], v[148:151], v[192:195], 0
	v_mfma_f32_16x16x32_bf16 v[58:61], v[168:171], v[192:195], 0
	v_mfma_f32_16x16x32_bf16 v[46:49], v[148:151], v[200:203], 0
	v_mfma_f32_16x16x32_bf16 v[42:45], v[168:171], v[200:203], 0
	v_mfma_f32_16x16x32_bf16 v[30:33], v[148:151], v[208:211], 0
	v_mfma_f32_16x16x32_bf16 v[26:29], v[168:171], v[208:211], 0
	v_mfma_f32_16x16x32_bf16 v[14:17], v[148:151], v[216:219], 0
	v_mfma_f32_16x16x32_bf16 v[10:13], v[168:171], v[216:219], 0
	v_mfma_f32_16x16x32_bf16 v[62:65], v[164:167], v[196:199], v[62:65]
	v_mfma_f32_16x16x32_bf16 v[58:61], v[172:175], v[196:199], v[58:61]
	v_mfma_f32_16x16x32_bf16 v[46:49], v[164:167], v[204:207], v[46:49]
	v_mfma_f32_16x16x32_bf16 v[42:45], v[172:175], v[204:207], v[42:45]
	v_mfma_f32_16x16x32_bf16 v[30:33], v[164:167], v[212:215], v[30:33]
	v_mfma_f32_16x16x32_bf16 v[26:29], v[172:175], v[212:215], v[26:29]
	v_mfma_f32_16x16x32_bf16 v[14:17], v[164:167], v[220:223], v[14:17]
	v_mfma_f32_16x16x32_bf16 v[10:13], v[172:175], v[220:223], v[10:13]
	s_setprio 0
	s_setprio 1
	v_mfma_f32_16x16x32_bf16 v[54:57], v[176:179], v[192:195], 0
	v_mfma_f32_16x16x32_bf16 v[50:53], v[184:187], v[192:195], 0
	v_mfma_f32_16x16x32_bf16 v[38:41], v[176:179], v[200:203], 0
	v_mfma_f32_16x16x32_bf16 v[34:37], v[184:187], v[200:203], 0
	v_mfma_f32_16x16x32_bf16 v[22:25], v[176:179], v[208:211], 0
	v_mfma_f32_16x16x32_bf16 v[18:21], v[184:187], v[208:211], 0
	v_mfma_f32_16x16x32_bf16 v[6:9], v[176:179], v[216:219], 0
	v_mfma_f32_16x16x32_bf16 v[2:5], v[184:187], v[216:219], 0
	v_mfma_f32_16x16x32_bf16 v[54:57], v[180:183], v[196:199], v[54:57]
	v_mfma_f32_16x16x32_bf16 v[50:53], v[188:191], v[196:199], v[50:53]
	v_mfma_f32_16x16x32_bf16 v[38:41], v[180:183], v[204:207], v[38:41]
	v_mfma_f32_16x16x32_bf16 v[34:37], v[188:191], v[204:207], v[34:37]
	v_mfma_f32_16x16x32_bf16 v[22:25], v[180:183], v[212:215], v[22:25]
	v_mfma_f32_16x16x32_bf16 v[18:21], v[188:191], v[212:215], v[18:21]
	v_mfma_f32_16x16x32_bf16 v[6:9], v[180:183], v[220:223], v[6:9]
	v_mfma_f32_16x16x32_bf16 v[2:5], v[188:191], v[220:223], v[2:5]
	s_setprio 0
	s_barrier
	s_add_i32 s69, 0, 0x18000
	s_add_i32 s70, 0, 0x1c000
	v_add_u32_e32 v172, s69, v155
	v_add_u32_e32 v188, s70, v155
	ds_read_b128 v[148:151], v172
	ds_read_b128 v[164:167], v172 offset:1024
	ds_read_b128 v[168:171], v172 offset:2048
	ds_read_b128 v[172:175], v172 offset:3072
	ds_read_b128 v[176:179], v188
	ds_read_b128 v[180:183], v188 offset:1024
	ds_read_b128 v[184:187], v188 offset:2048
	ds_read_b128 v[188:191], v188 offset:3072
	s_add_u32 s34, s34, 0x40000
	s_addc_u32 s35, s35, 0
	s_mov_b32 m0, s39
	v_lshl_add_u64 v[232:233], s[34:35], 0, v[136:137]
	ds_read_b128 v[192:195], v158 offset:32768
	ds_read_b128 v[196:199], v158 offset:33792
	ds_read_b128 v[200:203], v158 offset:34816
	ds_read_b128 v[204:207], v158 offset:35840
	ds_read_b128 v[208:211], v158 offset:36864
	ds_read_b128 v[212:215], v158 offset:37888
	ds_read_b128 v[216:219], v158 offset:38912
	ds_read_b128 v[220:223], v158 offset:39936
	global_load_lds_dwordx4 v[232:233], off
	v_lshl_add_u64 v[232:233], s[34:35], 0, v[132:133]
	s_mov_b32 m0, s40
	s_nop 0
	global_load_lds_dwordx4 v[232:233], off
	s_waitcnt vmcnt(8)
	s_waitcnt lgkmcnt(0)
	s_barrier
	s_setprio 1
	s_waitcnt lgkmcnt(0)
	v_mfma_f32_16x16x32_bf16 v[126:129], v[148:151], v[192:195], v[126:129]
	v_mfma_f32_16x16x32_bf16 v[122:125], v[168:171], v[192:195], v[122:125]
	v_mfma_f32_16x16x32_bf16 v[110:113], v[148:151], v[200:203], v[110:113]
	v_mfma_f32_16x16x32_bf16 v[106:109], v[168:171], v[200:203], v[106:109]
	v_mfma_f32_16x16x32_bf16 v[94:97], v[148:151], v[208:211], v[94:97]
	v_mfma_f32_16x16x32_bf16 v[90:93], v[168:171], v[208:211], v[90:93]
	v_mfma_f32_16x16x32_bf16 v[78:81], v[148:151], v[216:219], v[78:81]
	v_mfma_f32_16x16x32_bf16 v[74:77], v[168:171], v[216:219], v[74:77]
	v_mfma_f32_16x16x32_bf16 v[126:129], v[164:167], v[196:199], v[126:129]
	v_mfma_f32_16x16x32_bf16 v[122:125], v[172:175], v[196:199], v[122:125]
	v_mfma_f32_16x16x32_bf16 v[110:113], v[164:167], v[204:207], v[110:113]
	v_mfma_f32_16x16x32_bf16 v[106:109], v[172:175], v[204:207], v[106:109]
	v_mfma_f32_16x16x32_bf16 v[94:97], v[164:167], v[212:215], v[94:97]
	v_mfma_f32_16x16x32_bf16 v[90:93], v[172:175], v[212:215], v[90:93]
	v_mfma_f32_16x16x32_bf16 v[78:81], v[164:167], v[220:223], v[78:81]
	v_mfma_f32_16x16x32_bf16 v[74:77], v[172:175], v[220:223], v[74:77]
	s_setprio 0
	s_setprio 1
	v_mfma_f32_16x16x32_bf16 v[118:121], v[176:179], v[192:195], v[118:121]
	v_mfma_f32_16x16x32_bf16 v[114:117], v[184:187], v[192:195], v[114:117]
	v_mfma_f32_16x16x32_bf16 v[102:105], v[176:179], v[200:203], v[102:105]
	v_mfma_f32_16x16x32_bf16 v[98:101], v[184:187], v[200:203], v[98:101]
	v_mfma_f32_16x16x32_bf16 v[86:89], v[176:179], v[208:211], v[86:89]
	v_mfma_f32_16x16x32_bf16 v[82:85], v[184:187], v[208:211], v[82:85]
	v_mfma_f32_16x16x32_bf16 v[70:73], v[176:179], v[216:219], v[70:73]
	v_mfma_f32_16x16x32_bf16 v[66:69], v[184:187], v[216:219], v[66:69]
	v_mfma_f32_16x16x32_bf16 v[118:121], v[180:183], v[196:199], v[118:121]
	v_mfma_f32_16x16x32_bf16 v[114:117], v[188:191], v[196:199], v[114:117]
	v_mfma_f32_16x16x32_bf16 v[102:105], v[180:183], v[204:207], v[102:105]
	v_mfma_f32_16x16x32_bf16 v[98:101], v[188:191], v[204:207], v[98:101]
	v_mfma_f32_16x16x32_bf16 v[86:89], v[180:183], v[212:215], v[86:89]
	v_mfma_f32_16x16x32_bf16 v[82:85], v[188:191], v[212:215], v[82:85]
	v_mfma_f32_16x16x32_bf16 v[70:73], v[180:183], v[220:223], v[70:73]
	v_mfma_f32_16x16x32_bf16 v[66:69], v[188:191], v[220:223], v[66:69]
	s_setprio 0
	s_barrier
; #define PG8_STAGE(bufoff, gbase, voff) do { _Pragma("unroll") for (int _i = 0; _i < 2; ++_i) \
;         __builtin_amdgcn_global_load_lds((const unsigned*)((const char*)(gbase) + (voff)[_i]), (PG8_LAS unsigned*)(lds + (bufoff) + ldsw + _i * 8192), 16, 0, 0); } while (0)
; #define PG8_LDA(dst, b, h) do { _Pragma("unroll") for (int m = 0; m < 4; ++m) _Pragma("unroll") for (int k = 0; k < 2; ++k) dst[m][k] = *(const PG8_LAS bf16x8*)(lds + PG8_SA(b, h) + aoff + m * 2048 + k * 1024); } while (0)
; #define PG8_LDB(dst, b, h) do { _Pragma("unroll") for (int n = 0; n < 2; ++n) _Pragma("unroll") for (int k = 0; k < 2; ++k) dst[n][k] = *(const PG8_LAS bf16x8*)(lds + PG8_SB(b, h) + boff + n * 2048 + k * 1024); } while (0)
; #define PG8_MMA(ai, bj, At, Bt) do { __builtin_amdgcn_s_setprio(1); _Pragma("unroll") for (int m = 0; m < 4; ++m) _Pragma("unroll") for (int n = 0; n < 2; ++n) _Pragma("unroll") for (int k = 0; k < 2; ++k) \
;         acc[ai][bj][m][n] = __builtin_amdgcn_mfma_f32_16x16x32_bf16(Bt[n][k], At[m][k], acc[ai][bj][m][n], 0, 0, 0); __builtin_amdgcn_s_setprio(0); } while (0)
; #define PG8_WAIT_V(n) asm volatile("s_waitcnt vmcnt(" #n ")" ::: "memory")
; #define PG8_BAR __builtin_amdgcn_s_barrier()
; template <class Epi, class Sched, bool ALIGN_EPI = false, bool SP2 = false, bool AGM = false  >
; __device__ __forceinline__ void gemm_phase(PG8_LAS unsigned char* lds, const Gemm g, const Sched& S, const Epi& E) {
;     ...
;         for (int t = 0; t < nt; t += 2) {
;             const bool last = (t == nt - 2);
;             const char* a1 = cA + (size_t)(t + 1) * kstepA;
;             const char* a2 = last ? nA : cA + (size_t)(t + 2) * kstepA; const char* b2 = last ? nB : cB + (size_t)(t + 2) * kstep;
;             const char* a3 = a2 + kstepA; const char* b3 = b2 + kstep;
;             if (last && has_next) S.a_ready(nxt);
;             if constexpr (SP2) {
;             PG8_LDB(B0, 0, 0); PG8_LDB(B1, 0, 1); PG8_SCHED; PG8_LDA(At, 0, 0); PG8_STAGE(PG8_SA(1, 1), a1 + hstepA, voffA);
;             PG8_WAIT_V(8); PG8_WAIT_L(0); PG8_BAR; PG8_MMA(0, 0, At, B0); PG8_MMA(0, 1, At, B1); PG8_BAR; PG8_SCHED;
;     ...
;             PG8_LDA(At, 1, 1); PG8_STAGE(PG8_SB(1, 0), b3, voffB); PG8_STAGE(PG8_SB(1, 1), b3 + hstep, voffB); PG8_STAGE(PG8_SA(1, 0), a3, voffA);
;             PG8_WAIT_V(8); PG8_WAIT_L(0); PG8_BAR; PG8_MMA(1, 0, At, B0); PG8_MMA(1, 1, At, B1); PG8_BAR; PG8_SCHED;
	s_add_i32 s34, s69, s3
	v_lshl_add_u64 v[224:225], v[224:225], 0, s[16:17]
	s_mov_b32 m0, s34
	ds_read_b128 v[192:195], v158 offset:49152
	ds_read_b128 v[196:199], v158 offset:50176
	ds_read_b128 v[200:203], v158 offset:51200
	ds_read_b128 v[204:207], v158 offset:52224
	ds_read_b128 v[208:211], v158 offset:53248
	ds_read_b128 v[212:215], v158 offset:54272
	ds_read_b128 v[216:219], v158 offset:55296
	ds_read_b128 v[220:223], v158 offset:56320
	global_load_lds_dwordx4 v[224:225], off
	s_add_i32 m0, s34, 0x2000
	s_add_u32 s30, s30, 0x40080
	v_lshl_add_u64 v[224:225], v[226:227], 0, s[16:17]
	s_addc_u32 s31, s31, 0
	s_add_i32 s34, s70, s3
	global_load_lds_dwordx4 v[224:225], off
	v_lshl_add_u64 v[224:225], s[30:31], 0, v[134:135]
	s_mov_b32 m0, s34
	s_nop 0
	global_load_lds_dwordx4 v[224:225], off
	v_lshl_add_u64 v[224:225], s[30:31], 0, v[130:131]
	s_add_i32 m0, s34, 0x2000
	s_nop 0
	global_load_lds_dwordx4 v[224:225], off
	v_lshl_add_u64 v[224:225], v[228:229], 0, s[16:17]
	s_mov_b32 m0, s43
	s_nop 0
	global_load_lds_dwordx4 v[224:225], off
	v_lshl_add_u64 v[224:225], v[230:231], 0, s[16:17]
	s_mov_b32 m0, s44
	s_nop 0
	global_load_lds_dwordx4 v[224:225], off
	s_waitcnt vmcnt(8)
	s_waitcnt lgkmcnt(0)
	s_barrier
	s_setprio 1
	s_waitcnt lgkmcnt(0)
	v_mfma_f32_16x16x32_bf16 v[62:65], v[148:151], v[192:195], v[62:65]
	v_mfma_f32_16x16x32_bf16 v[58:61], v[168:171], v[192:195], v[58:61]
	v_mfma_f32_16x16x32_bf16 v[46:49], v[148:151], v[200:203], v[46:49]
	v_mfma_f32_16x16x32_bf16 v[42:45], v[168:171], v[200:203], v[42:45]
	v_mfma_f32_16x16x32_bf16 v[30:33], v[148:151], v[208:211], v[30:33]
	v_mfma_f32_16x16x32_bf16 v[26:29], v[168:171], v[208:211], v[26:29]
	v_mfma_f32_16x16x32_bf16 v[14:17], v[148:151], v[216:219], v[14:17]
	v_mfma_f32_16x16x32_bf16 v[10:13], v[168:171], v[216:219], v[10:13]
	v_mfma_f32_16x16x32_bf16 v[62:65], v[164:167], v[196:199], v[62:65]
	v_mfma_f32_16x16x32_bf16 v[58:61], v[172:175], v[196:199], v[58:61]
	v_mfma_f32_16x16x32_bf16 v[46:49], v[164:167], v[204:207], v[46:49]
	v_mfma_f32_16x16x32_bf16 v[42:45], v[172:175], v[204:207], v[42:45]
	v_mfma_f32_16x16x32_bf16 v[30:33], v[164:167], v[212:215], v[30:33]
	v_mfma_f32_16x16x32_bf16 v[26:29], v[172:175], v[212:215], v[26:29]
	v_mfma_f32_16x16x32_bf16 v[14:17], v[164:167], v[220:223], v[14:17]
	v_mfma_f32_16x16x32_bf16 v[10:13], v[172:175], v[220:223], v[10:13]
	s_setprio 0
	s_setprio 1
	v_mfma_f32_16x16x32_bf16 v[54:57], v[176:179], v[192:195], v[54:57]
	v_mfma_f32_16x16x32_bf16 v[50:53], v[184:187], v[192:195], v[50:53]
	v_mfma_f32_16x16x32_bf16 v[38:41], v[176:179], v[200:203], v[38:41]
	v_mfma_f32_16x16x32_bf16 v[34:37], v[184:187], v[200:203], v[34:37]
	v_mfma_f32_16x16x32_bf16 v[22:25], v[176:179], v[208:211], v[22:25]
	v_mfma_f32_16x16x32_bf16 v[18:21], v[184:187], v[208:211], v[18:21]
	v_mfma_f32_16x16x32_bf16 v[6:9], v[176:179], v[216:219], v[6:9]
	v_mfma_f32_16x16x32_bf16 v[2:5], v[184:187], v[216:219], v[2:5]
	v_mfma_f32_16x16x32_bf16 v[54:57], v[180:183], v[196:199], v[54:57]
	v_mfma_f32_16x16x32_bf16 v[50:53], v[188:191], v[196:199], v[50:53]
	v_mfma_f32_16x16x32_bf16 v[38:41], v[180:183], v[204:207], v[38:41]
	v_mfma_f32_16x16x32_bf16 v[34:37], v[188:191], v[204:207], v[34:37]
	v_mfma_f32_16x16x32_bf16 v[22:25], v[180:183], v[212:215], v[22:25]
	v_mfma_f32_16x16x32_bf16 v[18:21], v[188:191], v[212:215], v[18:21]
	v_mfma_f32_16x16x32_bf16 v[6:9], v[180:183], v[220:223], v[6:9]
	v_mfma_f32_16x16x32_bf16 v[2:5], v[188:191], v[220:223], v[2:5]
	s_add_i32 s68, s68, 2
	s_add_u32 s28, s28, 0x100
	s_addc_u32 s29, s29, 0
	s_add_u32 s66, s66, 0x100
	s_addc_u32 s67, s67, 0
	s_cmp_gt_u32 s68, 13
	s_setprio 0
	s_barrier
	s_cbranch_scc1 .Lpeel_done_p6
	.p2align	6
.LBB0_877:
	ds_read_b128 v[148:151], v156
	ds_read_b128 v[164:167], v156 offset:1024
	ds_read_b128 v[168:171], v156 offset:2048
	ds_read_b128 v[172:175], v156 offset:3072
	ds_read_b128 v[176:179], v157
	ds_read_b128 v[180:183], v157 offset:1024
	ds_read_b128 v[184:187], v157 offset:2048
	ds_read_b128 v[188:191], v157 offset:3072
	s_add_u32 s30, s28, 0xfffc0080
	s_addc_u32 s31, s29, -1
	s_cmp_eq_u32 s68, 12
	s_cselect_b32 s35, s23, s31
	s_cselect_b32 s34, s64, s30
	s_cselect_b32 s31, s21, s67
	s_cselect_b32 s30, s65, s66
	v_lshl_add_u64 v[224:225], s[28:29], 0, v[140:141]
	s_add_i32 m0, s37, 0xc000
	ds_read_b128 v[192:195], v158
	ds_read_b128 v[196:199], v158 offset:1024
	ds_read_b128 v[200:203], v158 offset:2048
	ds_read_b128 v[204:207], v158 offset:3072
	ds_read_b128 v[208:211], v158 offset:4096
	ds_read_b128 v[212:215], v158 offset:5120
	ds_read_b128 v[216:219], v158 offset:6144
	ds_read_b128 v[220:223], v158 offset:7168
	global_load_lds_dwordx4 v[224:225], off
	v_lshl_add_u64 v[224:225], s[28:29], 0, v[142:143]
	s_add_i32 m0, s37, 0xe000
	s_nop 0
	global_load_lds_dwordx4 v[224:225], off
	s_waitcnt vmcnt(8)
	s_waitcnt lgkmcnt(0)
	s_barrier
; #define PG8_STAGE(bufoff, gbase, voff) do { _Pragma("unroll") for (int _i = 0; _i < 2; ++_i) \
;         __builtin_amdgcn_global_load_lds((const unsigned*)((const char*)(gbase) + (voff)[_i]), (PG8_LAS unsigned*)(lds + (bufoff) + ldsw + _i * 8192), 16, 0, 0); } while (0)
; #define PG8_LDA(dst, b, h) do { _Pragma("unroll") for (int m = 0; m < 4; ++m) _Pragma("unroll") for (int k = 0; k < 2; ++k) dst[m][k] = *(const PG8_LAS bf16x8*)(lds + PG8_SA(b, h) + aoff + m * 2048 + k * 1024); } while (0)
; #define PG8_MMA(ai, bj, At, Bt) do { __builtin_amdgcn_s_setprio(1); _Pragma("unroll") for (int m = 0; m < 4; ++m) _Pragma("unroll") for (int n = 0; n < 2; ++n) _Pragma("unroll") for (int k = 0; k < 2; ++k) \
;         acc[ai][bj][m][n] = __builtin_amdgcn_mfma_f32_16x16x32_bf16(Bt[n][k], At[m][k], acc[ai][bj][m][n], 0, 0, 0); __builtin_amdgcn_s_setprio(0); } while (0)
; #define PG8_WAIT_V(n) asm volatile("s_waitcnt vmcnt(" #n ")" ::: "memory")
; #define PG8_WAIT_L(n) asm volatile("s_waitcnt lgkmcnt(" #n ")" ::: "memory")
; #define PG8_BAR __builtin_amdgcn_s_barrier()
; #define PG8_SCHED __builtin_amdgcn_sched_barrier(0)
; template <class Epi, class Sched, bool ALIGN_EPI = false, bool SP2 = false, bool AGM = false  >
; __device__ __forceinline__ void gemm_phase(PG8_LAS unsigned char* lds, const Gemm g, const Sched& S, const Epi& E) {
;     ...
;             PG8_WAIT_V(8); PG8_WAIT_L(0); PG8_BAR; PG8_MMA(0, 0, At, B0); PG8_MMA(0, 1, At, B1); PG8_BAR; PG8_SCHED;
;             PG8_LDA(At, 0, 1); PG8_STAGE(PG8_SB(0, 0), b2, voffB); PG8_STAGE(PG8_SB(0, 1), b2 + hstep, voffB); PG8_STAGE(PG8_SA(0, 0), a2, voffA);
;             PG8_WAIT_V(8); PG8_WAIT_L(0); PG8_BAR; PG8_MMA(1, 0, At, B0); PG8_MMA(1, 1, At, B1); PG8_BAR; PG8_SCHED;
	s_setprio 1
	s_waitcnt lgkmcnt(0)
	v_mfma_f32_16x16x32_bf16 v[126:129], v[148:151], v[192:195], v[126:129]
	v_mfma_f32_16x16x32_bf16 v[122:125], v[168:171], v[192:195], v[122:125]
	v_mfma_f32_16x16x32_bf16 v[110:113], v[148:151], v[200:203], v[110:113]
	v_mfma_f32_16x16x32_bf16 v[106:109], v[168:171], v[200:203], v[106:109]
	v_mfma_f32_16x16x32_bf16 v[94:97], v[148:151], v[208:211], v[94:97]
	v_mfma_f32_16x16x32_bf16 v[90:93], v[168:171], v[208:211], v[90:93]
	v_mfma_f32_16x16x32_bf16 v[78:81], v[148:151], v[216:219], v[78:81]
	v_mfma_f32_16x16x32_bf16 v[74:77], v[168:171], v[216:219], v[74:77]
	v_mfma_f32_16x16x32_bf16 v[126:129], v[164:167], v[196:199], v[126:129]
	v_mfma_f32_16x16x32_bf16 v[122:125], v[172:175], v[196:199], v[122:125]
	v_mfma_f32_16x16x32_bf16 v[110:113], v[164:167], v[204:207], v[110:113]
	v_mfma_f32_16x16x32_bf16 v[106:109], v[172:175], v[204:207], v[106:109]
	v_mfma_f32_16x16x32_bf16 v[94:97], v[164:167], v[212:215], v[94:97]
	v_mfma_f32_16x16x32_bf16 v[90:93], v[172:175], v[212:215], v[90:93]
	v_mfma_f32_16x16x32_bf16 v[78:81], v[164:167], v[220:223], v[78:81]
	v_mfma_f32_16x16x32_bf16 v[74:77], v[172:175], v[220:223], v[74:77]
	s_setprio 0
	s_setprio 1
	v_mfma_f32_16x16x32_bf16 v[118:121], v[176:179], v[192:195], v[118:121]
	v_mfma_f32_16x16x32_bf16 v[114:117], v[184:187], v[192:195], v[114:117]
	v_mfma_f32_16x16x32_bf16 v[102:105], v[176:179], v[200:203], v[102:105]
	v_mfma_f32_16x16x32_bf16 v[98:101], v[184:187], v[200:203], v[98:101]
	v_mfma_f32_16x16x32_bf16 v[86:89], v[176:179], v[208:211], v[86:89]
	v_mfma_f32_16x16x32_bf16 v[82:85], v[184:187], v[208:211], v[82:85]
	v_mfma_f32_16x16x32_bf16 v[70:73], v[176:179], v[216:219], v[70:73]
	v_mfma_f32_16x16x32_bf16 v[66:69], v[184:187], v[216:219], v[66:69]
	v_mfma_f32_16x16x32_bf16 v[118:121], v[180:183], v[196:199], v[118:121]
	v_mfma_f32_16x16x32_bf16 v[114:117], v[188:191], v[196:199], v[114:117]
	v_mfma_f32_16x16x32_bf16 v[102:105], v[180:183], v[204:207], v[102:105]
	v_mfma_f32_16x16x32_bf16 v[98:101], v[188:191], v[204:207], v[98:101]
	v_mfma_f32_16x16x32_bf16 v[86:89], v[180:183], v[212:215], v[86:89]
	v_mfma_f32_16x16x32_bf16 v[82:85], v[188:191], v[212:215], v[82:85]
	v_mfma_f32_16x16x32_bf16 v[70:73], v[180:183], v[220:223], v[70:73]
	v_mfma_f32_16x16x32_bf16 v[66:69], v[188:191], v[220:223], v[66:69]
	s_setprio 0
	s_barrier
	s_add_i32 s69, s53, s3
	v_lshl_add_u64 v[224:225], s[30:31], 0, v[134:135]
	s_mov_b32 m0, s69
	ds_read_b128 v[192:195], v158 offset:16384
	ds_read_b128 v[196:199], v158 offset:17408
	ds_read_b128 v[200:203], v158 offset:18432
	ds_read_b128 v[204:207], v158 offset:19456
	ds_read_b128 v[208:211], v158 offset:20480
	ds_read_b128 v[212:215], v158 offset:21504
	ds_read_b128 v[216:219], v158 offset:22528
	ds_read_b128 v[220:223], v158 offset:23552
	global_load_lds_dwordx4 v[224:225], off
	s_add_i32 m0, s69, 0x2000
	s_add_u32 s70, s30, 0x40000
	v_lshl_add_u64 v[226:227], s[30:31], 0, v[130:131]
	s_addc_u32 s71, s31, 0
	s_add_i32 s69, s54, s3
	global_load_lds_dwordx4 v[226:227], off
	v_lshl_add_u64 v[228:229], s[70:71], 0, v[134:135]
	s_mov_b32 m0, s69
	v_lshl_add_u64 v[230:231], s[34:35], 0, v[132:133]
	global_load_lds_dwordx4 v[228:229], off
	v_lshl_add_u64 v[228:229], s[70:71], 0, v[130:131]
	s_add_i32 m0, s69, 0x2000
	s_nop 0
	global_load_lds_dwordx4 v[228:229], off
	v_lshl_add_u64 v[228:229], s[34:35], 0, v[136:137]
	s_mov_b32 m0, s37
	s_nop 0
	global_load_lds_dwordx4 v[228:229], off
	s_mov_b32 m0, s38
	s_nop 0
	global_load_lds_dwordx4 v[230:231], off
	s_waitcnt vmcnt(8)
	s_waitcnt lgkmcnt(0)
	s_barrier
	s_setprio 1
	s_waitcnt lgkmcnt(0)
	v_mfma_f32_16x16x32_bf16 v[62:65], v[148:151], v[192:195], v[62:65]
	v_mfma_f32_16x16x32_bf16 v[58:61], v[168:171], v[192:195], v[58:61]
	v_mfma_f32_16x16x32_bf16 v[46:49], v[148:151], v[200:203], v[46:49]
	v_mfma_f32_16x16x32_bf16 v[42:45], v[168:171], v[200:203], v[42:45]
	v_mfma_f32_16x16x32_bf16 v[30:33], v[148:151], v[208:211], v[30:33]
	v_mfma_f32_16x16x32_bf16 v[26:29], v[168:171], v[208:211], v[26:29]
	v_mfma_f32_16x16x32_bf16 v[14:17], v[148:151], v[216:219], v[14:17]
	v_mfma_f32_16x16x32_bf16 v[10:13], v[168:171], v[216:219], v[10:13]
	v_mfma_f32_16x16x32_bf16 v[62:65], v[164:167], v[196:199], v[62:65]
	v_mfma_f32_16x16x32_bf16 v[58:61], v[172:175], v[196:199], v[58:61]
	v_mfma_f32_16x16x32_bf16 v[46:49], v[164:167], v[204:207], v[46:49]
	v_mfma_f32_16x16x32_bf16 v[42:45], v[172:175], v[204:207], v[42:45]
	v_mfma_f32_16x16x32_bf16 v[30:33], v[164:167], v[212:215], v[30:33]
	v_mfma_f32_16x16x32_bf16 v[26:29], v[172:175], v[212:215], v[26:29]
	v_mfma_f32_16x16x32_bf16 v[14:17], v[164:167], v[220:223], v[14:17]
	v_mfma_f32_16x16x32_bf16 v[10:13], v[172:175], v[220:223], v[10:13]
	s_setprio 0
	s_setprio 1
	v_mfma_f32_16x16x32_bf16 v[54:57], v[176:179], v[192:195], v[54:57]
	v_mfma_f32_16x16x32_bf16 v[50:53], v[184:187], v[192:195], v[50:53]
	v_mfma_f32_16x16x32_bf16 v[38:41], v[176:179], v[200:203], v[38:41]
	v_mfma_f32_16x16x32_bf16 v[34:37], v[184:187], v[200:203], v[34:37]
	v_mfma_f32_16x16x32_bf16 v[22:25], v[176:179], v[208:211], v[22:25]
	v_mfma_f32_16x16x32_bf16 v[18:21], v[184:187], v[208:211], v[18:21]
	v_mfma_f32_16x16x32_bf16 v[6:9], v[176:179], v[216:219], v[6:9]
	v_mfma_f32_16x16x32_bf16 v[2:5], v[184:187], v[216:219], v[2:5]
	v_mfma_f32_16x16x32_bf16 v[54:57], v[180:183], v[196:199], v[54:57]
	v_mfma_f32_16x16x32_bf16 v[50:53], v[188:191], v[196:199], v[50:53]
	v_mfma_f32_16x16x32_bf16 v[38:41], v[180:183], v[204:207], v[38:41]
	v_mfma_f32_16x16x32_bf16 v[34:37], v[188:191], v[204:207], v[34:37]
	v_mfma_f32_16x16x32_bf16 v[22:25], v[180:183], v[212:215], v[22:25]
	v_mfma_f32_16x16x32_bf16 v[18:21], v[188:191], v[212:215], v[18:21]
	v_mfma_f32_16x16x32_bf16 v[6:9], v[180:183], v[220:223], v[6:9]
	v_mfma_f32_16x16x32_bf16 v[2:5], v[188:191], v[220:223], v[2:5]
	s_setprio 0
	s_barrier
; #define PG8_STAGE(bufoff, gbase, voff) do { _Pragma("unroll") for (int _i = 0; _i < 2; ++_i) \
;         __builtin_amdgcn_global_load_lds((const unsigned*)((const char*)(gbase) + (voff)[_i]), (PG8_LAS unsigned*)(lds + (bufoff) + ldsw + _i * 8192), 16, 0, 0); } while (0)
; #define PG8_LDA(dst, b, h) do { _Pragma("unroll") for (int m = 0; m < 4; ++m) _Pragma("unroll") for (int k = 0; k < 2; ++k) dst[m][k] = *(const PG8_LAS bf16x8*)(lds + PG8_SA(b, h) + aoff + m * 2048 + k * 1024); } while (0)
; #define PG8_LDB(dst, b, h) do { _Pragma("unroll") for (int n = 0; n < 2; ++n) _Pragma("unroll") for (int k = 0; k < 2; ++k) dst[n][k] = *(const PG8_LAS bf16x8*)(lds + PG8_SB(b, h) + boff + n * 2048 + k * 1024); } while (0)
; #define PG8_MMA(ai, bj, At, Bt) do { __builtin_amdgcn_s_setprio(1); _Pragma("unroll") for (int m = 0; m < 4; ++m) _Pragma("unroll") for (int n = 0; n < 2; ++n) _Pragma("unroll") for (int k = 0; k < 2; ++k) \
;         acc[ai][bj][m][n] = __builtin_amdgcn_mfma_f32_16x16x32_bf16(Bt[n][k], At[m][k], acc[ai][bj][m][n], 0, 0, 0); __builtin_amdgcn_s_setprio(0); } while (0)
; #define PG8_WAIT_V(n) asm volatile("s_waitcnt vmcnt(" #n ")" ::: "memory")
; #define PG8_WAIT_L(n) asm volatile("s_waitcnt lgkmcnt(" #n ")" ::: "memory")
; #define PG8_BAR __builtin_amdgcn_s_barrier()
; #define PG8_SCHED __builtin_amdgcn_sched_barrier(0)
; template <class Epi, class Sched, bool ALIGN_EPI = false, bool SP2 = false, bool AGM = false  >
; __device__ __forceinline__ void gemm_phase(PG8_LAS unsigned char* lds, const Gemm g, const Sched& S, const Epi& E) {
;     ...
;             PG8_LDB(B0, 1, 0); PG8_LDB(B1, 1, 1); PG8_SCHED; PG8_LDA(At, 1, 0); PG8_STAGE(PG8_SA(0, 1), a2 + hstepA, voffA);
;             PG8_WAIT_V(8); PG8_WAIT_L(0); PG8_BAR; PG8_MMA(0, 0, At, B0); PG8_MMA(0, 1, At, B1); PG8_BAR; PG8_SCHED;
	s_add_i32 s69, 0, 0x18000
	s_add_i32 s70, 0, 0x1c000
	v_add_u32_e32 v172, s69, v155
	v_add_u32_e32 v188, s70, v155
	ds_read_b128 v[148:151], v172
	ds_read_b128 v[164:167], v172 offset:1024
	ds_read_b128 v[168:171], v172 offset:2048
	ds_read_b128 v[172:175], v172 offset:3072
	ds_read_b128 v[176:179], v188
	ds_read_b128 v[180:183], v188 offset:1024
	ds_read_b128 v[184:187], v188 offset:2048
	ds_read_b128 v[188:191], v188 offset:3072
	s_add_u32 s34, s34, 0x40000
	s_addc_u32 s35, s35, 0
	s_mov_b32 m0, s39
	v_lshl_add_u64 v[232:233], s[34:35], 0, v[136:137]
	ds_read_b128 v[192:195], v158 offset:32768
	ds_read_b128 v[196:199], v158 offset:33792
	ds_read_b128 v[200:203], v158 offset:34816
	ds_read_b128 v[204:207], v158 offset:35840
	ds_read_b128 v[208:211], v158 offset:36864
	ds_read_b128 v[212:215], v158 offset:37888
	ds_read_b128 v[216:219], v158 offset:38912
	ds_read_b128 v[220:223], v158 offset:39936
	global_load_lds_dwordx4 v[232:233], off
	v_lshl_add_u64 v[232:233], s[34:35], 0, v[132:133]
	s_mov_b32 m0, s40
	s_nop 0
	global_load_lds_dwordx4 v[232:233], off
	s_waitcnt vmcnt(8)
	s_waitcnt lgkmcnt(0)
	s_barrier
	s_setprio 1
	s_waitcnt lgkmcnt(0)
	v_mfma_f32_16x16x32_bf16 v[126:129], v[148:151], v[192:195], v[126:129]
	v_mfma_f32_16x16x32_bf16 v[122:125], v[168:171], v[192:195], v[122:125]
	v_mfma_f32_16x16x32_bf16 v[110:113], v[148:151], v[200:203], v[110:113]
	v_mfma_f32_16x16x32_bf16 v[106:109], v[168:171], v[200:203], v[106:109]
	v_mfma_f32_16x16x32_bf16 v[94:97], v[148:151], v[208:211], v[94:97]
	v_mfma_f32_16x16x32_bf16 v[90:93], v[168:171], v[208:211], v[90:93]
	v_mfma_f32_16x16x32_bf16 v[78:81], v[148:151], v[216:219], v[78:81]
	v_mfma_f32_16x16x32_bf16 v[74:77], v[168:171], v[216:219], v[74:77]
	v_mfma_f32_16x16x32_bf16 v[126:129], v[164:167], v[196:199], v[126:129]
	v_mfma_f32_16x16x32_bf16 v[122:125], v[172:175], v[196:199], v[122:125]
	v_mfma_f32_16x16x32_bf16 v[110:113], v[164:167], v[204:207], v[110:113]
	v_mfma_f32_16x16x32_bf16 v[106:109], v[172:175], v[204:207], v[106:109]
	v_mfma_f32_16x16x32_bf16 v[94:97], v[164:167], v[212:215], v[94:97]
	v_mfma_f32_16x16x32_bf16 v[90:93], v[172:175], v[212:215], v[90:93]
	v_mfma_f32_16x16x32_bf16 v[78:81], v[164:167], v[220:223], v[78:81]
	v_mfma_f32_16x16x32_bf16 v[74:77], v[172:175], v[220:223], v[74:77]
	s_setprio 0
	s_setprio 1
	v_mfma_f32_16x16x32_bf16 v[118:121], v[176:179], v[192:195], v[118:121]
	v_mfma_f32_16x16x32_bf16 v[114:117], v[184:187], v[192:195], v[114:117]
	v_mfma_f32_16x16x32_bf16 v[102:105], v[176:179], v[200:203], v[102:105]
	v_mfma_f32_16x16x32_bf16 v[98:101], v[184:187], v[200:203], v[98:101]
	v_mfma_f32_16x16x32_bf16 v[86:89], v[176:179], v[208:211], v[86:89]
	v_mfma_f32_16x16x32_bf16 v[82:85], v[184:187], v[208:211], v[82:85]
	v_mfma_f32_16x16x32_bf16 v[70:73], v[176:179], v[216:219], v[70:73]
	v_mfma_f32_16x16x32_bf16 v[66:69], v[184:187], v[216:219], v[66:69]
	v_mfma_f32_16x16x32_bf16 v[118:121], v[180:183], v[196:199], v[118:121]
	v_mfma_f32_16x16x32_bf16 v[114:117], v[188:191], v[196:199], v[114:117]
	v_mfma_f32_16x16x32_bf16 v[102:105], v[180:183], v[204:207], v[102:105]
	v_mfma_f32_16x16x32_bf16 v[98:101], v[188:191], v[204:207], v[98:101]
	v_mfma_f32_16x16x32_bf16 v[86:89], v[180:183], v[212:215], v[86:89]
	v_mfma_f32_16x16x32_bf16 v[82:85], v[188:191], v[212:215], v[82:85]
	v_mfma_f32_16x16x32_bf16 v[70:73], v[180:183], v[220:223], v[70:73]
	v_mfma_f32_16x16x32_bf16 v[66:69], v[188:191], v[220:223], v[66:69]
	s_setprio 0
	s_barrier
; #define PG8_STAGE(bufoff, gbase, voff) do { _Pragma("unroll") for (int _i = 0; _i < 2; ++_i) \
;         __builtin_amdgcn_global_load_lds((const unsigned*)((const char*)(gbase) + (voff)[_i]), (PG8_LAS unsigned*)(lds + (bufoff) + ldsw + _i * 8192), 16, 0, 0); } while (0)
; #define PG8_LDA(dst, b, h) do { _Pragma("unroll") for (int m = 0; m < 4; ++m) _Pragma("unroll") for (int k = 0; k < 2; ++k) dst[m][k] = *(const PG8_LAS bf16x8*)(lds + PG8_SA(b, h) + aoff + m * 2048 + k * 1024); } while (0)
; #define PG8_MMA(ai, bj, At, Bt) do { __builtin_amdgcn_s_setprio(1); _Pragma("unroll") for (int m = 0; m < 4; ++m) _Pragma("unroll") for (int n = 0; n < 2; ++n) _Pragma("unroll") for (int k = 0; k < 2; ++k) \
;         acc[ai][bj][m][n] = __builtin_amdgcn_mfma_f32_16x16x32_bf16(Bt[n][k], At[m][k], acc[ai][bj][m][n], 0, 0, 0); __builtin_amdgcn_s_setprio(0); } while (0)
; #define PG8_WAIT_V(n) asm volatile("s_waitcnt vmcnt(" #n ")" ::: "memory")
; #define PG8_WAIT_L(n) asm volatile("s_waitcnt lgkmcnt(" #n ")" ::: "memory")
; #define PG8_BAR __builtin_amdgcn_s_barrier()
; #define PG8_SCHED __builtin_amdgcn_sched_barrier(0)
; template <class Epi, class Sched, bool ALIGN_EPI = false, bool SP2 = false, bool AGM = false  >
; __device__ __forceinline__ void gemm_phase(PG8_LAS unsigned char* lds, const Gemm g, const Sched& S, const Epi& E) {
;     ...
;         for (int t = 0; t < nt; t += 2) {
;     ...
;             PG8_LDA(At, 1, 1); PG8_STAGE(PG8_SB(1, 0), b3, voffB); PG8_STAGE(PG8_SB(1, 1), b3 + hstep, voffB); PG8_STAGE(PG8_SA(1, 0), a3, voffA);
;             PG8_WAIT_V(8); PG8_WAIT_L(0); PG8_BAR; PG8_MMA(1, 0, At, B0); PG8_MMA(1, 1, At, B1); PG8_BAR; PG8_SCHED;
	s_add_i32 s34, s69, s3
	v_lshl_add_u64 v[224:225], v[224:225], 0, s[16:17]
	s_mov_b32 m0, s34
	ds_read_b128 v[192:195], v158 offset:49152
	ds_read_b128 v[196:199], v158 offset:50176
	ds_read_b128 v[200:203], v158 offset:51200
	ds_read_b128 v[204:207], v158 offset:52224
	ds_read_b128 v[208:211], v158 offset:53248
	ds_read_b128 v[212:215], v158 offset:54272
	ds_read_b128 v[216:219], v158 offset:55296
	ds_read_b128 v[220:223], v158 offset:56320
	global_load_lds_dwordx4 v[224:225], off
	s_add_i32 m0, s34, 0x2000
	s_add_u32 s30, s30, 0x40080
	v_lshl_add_u64 v[224:225], v[226:227], 0, s[16:17]
	s_addc_u32 s31, s31, 0
	s_add_i32 s34, s70, s3
	global_load_lds_dwordx4 v[224:225], off
	v_lshl_add_u64 v[224:225], s[30:31], 0, v[134:135]
	s_mov_b32 m0, s34
	s_nop 0
	global_load_lds_dwordx4 v[224:225], off
	v_lshl_add_u64 v[224:225], s[30:31], 0, v[130:131]
	s_add_i32 m0, s34, 0x2000
	s_nop 0
	global_load_lds_dwordx4 v[224:225], off
	v_lshl_add_u64 v[224:225], v[228:229], 0, s[16:17]
	s_mov_b32 m0, s43
	s_nop 0
	global_load_lds_dwordx4 v[224:225], off
	v_lshl_add_u64 v[224:225], v[230:231], 0, s[16:17]
	s_mov_b32 m0, s44
	s_nop 0
	global_load_lds_dwordx4 v[224:225], off
	s_waitcnt vmcnt(8)
	s_waitcnt lgkmcnt(0)
	s_barrier
	s_setprio 1
	s_waitcnt lgkmcnt(0)
	v_mfma_f32_16x16x32_bf16 v[62:65], v[148:151], v[192:195], v[62:65]
	v_mfma_f32_16x16x32_bf16 v[58:61], v[168:171], v[192:195], v[58:61]
	v_mfma_f32_16x16x32_bf16 v[46:49], v[148:151], v[200:203], v[46:49]
	v_mfma_f32_16x16x32_bf16 v[42:45], v[168:171], v[200:203], v[42:45]
	v_mfma_f32_16x16x32_bf16 v[30:33], v[148:151], v[208:211], v[30:33]
	v_mfma_f32_16x16x32_bf16 v[26:29], v[168:171], v[208:211], v[26:29]
	v_mfma_f32_16x16x32_bf16 v[14:17], v[148:151], v[216:219], v[14:17]
	v_mfma_f32_16x16x32_bf16 v[10:13], v[168:171], v[216:219], v[10:13]
	v_mfma_f32_16x16x32_bf16 v[62:65], v[164:167], v[196:199], v[62:65]
	v_mfma_f32_16x16x32_bf16 v[58:61], v[172:175], v[196:199], v[58:61]
	v_mfma_f32_16x16x32_bf16 v[46:49], v[164:167], v[204:207], v[46:49]
	v_mfma_f32_16x16x32_bf16 v[42:45], v[172:175], v[204:207], v[42:45]
	v_mfma_f32_16x16x32_bf16 v[30:33], v[164:167], v[212:215], v[30:33]
	v_mfma_f32_16x16x32_bf16 v[26:29], v[172:175], v[212:215], v[26:29]
	v_mfma_f32_16x16x32_bf16 v[14:17], v[164:167], v[220:223], v[14:17]
	v_mfma_f32_16x16x32_bf16 v[10:13], v[172:175], v[220:223], v[10:13]
	s_setprio 0
	s_setprio 1
	v_mfma_f32_16x16x32_bf16 v[54:57], v[176:179], v[192:195], v[54:57]
	v_mfma_f32_16x16x32_bf16 v[50:53], v[184:187], v[192:195], v[50:53]
	v_mfma_f32_16x16x32_bf16 v[38:41], v[176:179], v[200:203], v[38:41]
	v_mfma_f32_16x16x32_bf16 v[34:37], v[184:187], v[200:203], v[34:37]
	v_mfma_f32_16x16x32_bf16 v[22:25], v[176:179], v[208:211], v[22:25]
	v_mfma_f32_16x16x32_bf16 v[18:21], v[184:187], v[208:211], v[18:21]
	v_mfma_f32_16x16x32_bf16 v[6:9], v[176:179], v[216:219], v[6:9]
	v_mfma_f32_16x16x32_bf16 v[2:5], v[184:187], v[216:219], v[2:5]
	v_mfma_f32_16x16x32_bf16 v[54:57], v[180:183], v[196:199], v[54:57]
	v_mfma_f32_16x16x32_bf16 v[50:53], v[188:191], v[196:199], v[50:53]
	v_mfma_f32_16x16x32_bf16 v[38:41], v[180:183], v[204:207], v[38:41]
	v_mfma_f32_16x16x32_bf16 v[34:37], v[188:191], v[204:207], v[34:37]
	v_mfma_f32_16x16x32_bf16 v[22:25], v[180:183], v[212:215], v[22:25]
	v_mfma_f32_16x16x32_bf16 v[18:21], v[188:191], v[212:215], v[18:21]
	v_mfma_f32_16x16x32_bf16 v[6:9], v[180:183], v[220:223], v[6:9]
	v_mfma_f32_16x16x32_bf16 v[2:5], v[188:191], v[220:223], v[2:5]
	s_add_i32 s68, s68, 2
	s_add_u32 s28, s28, 0x100
	s_addc_u32 s29, s29, 0
	s_add_u32 s66, s66, 0x100
	s_addc_u32 s67, s67, 0
	s_cmp_gt_u32 s68, 13
	s_setprio 0
	s_barrier
	s_cbranch_scc0 .LBB0_877

; #define PG8_STAGE(bufoff, gbase, voff) do { _Pragma("unroll") for (int _i = 0; _i < 2; ++_i) \
;         __builtin_amdgcn_global_load_lds((const unsigned*)((const char*)(gbase) + (voff)[_i]), (PG8_LAS unsigned*)(lds + (bufoff) + ldsw + _i * 8192), 16, 0, 0); } while (0)
; #define PG8_LDA(dst, b, h) do { _Pragma("unroll") for (int m = 0; m < 4; ++m) _Pragma("unroll") for (int k = 0; k < 2; ++k) dst[m][k] = *(const PG8_LAS bf16x8*)(lds + PG8_SA(b, h) + aoff + m * 2048 + k * 1024); } while (0)
; #define PG8_LDB(dst, b, h) do { _Pragma("unroll") for (int n = 0; n < 2; ++n) _Pragma("unroll") for (int k = 0; k < 2; ++k) dst[n][k] = *(const PG8_LAS bf16x8*)(lds + PG8_SB(b, h) + boff + n * 2048 + k * 1024); } while (0)
; #define PG8_MMA(ai, bj, At, Bt) do { __builtin_amdgcn_s_setprio(1); _Pragma("unroll") for (int m = 0; m < 4; ++m) _Pragma("unroll") for (int n = 0; n < 2; ++n) _Pragma("unroll") for (int k = 0; k < 2; ++k) \
;         acc[ai][bj][m][n] = __builtin_amdgcn_mfma_f32_16x16x32_bf16(Bt[n][k], At[m][k], acc[ai][bj][m][n], 0, 0, 0); __builtin_amdgcn_s_setprio(0); } while (0)
; #define PG8_WAIT_V(n) asm volatile("s_waitcnt vmcnt(" #n ")" ::: "memory")
; #define PG8_WAIT_L(n) asm volatile("s_waitcnt lgkmcnt(" #n ")" ::: "memory")
; template <class Epi, class Sched, bool ALIGN_EPI = false, bool SP2 = false, bool AGM = false  >
; __device__ __forceinline__ void gemm_phase(PG8_LAS unsigned char* lds, const Gemm g, const Sched& S, const Epi& E) {
;     ...
;             const bool last = (t == nt - 2);
;             const char* a1 = cA + (size_t)(t + 1) * kstepA;
;             const char* a2 = last ? nA : cA + (size_t)(t + 2) * kstepA; const char* b2 = last ? nB : cB + (size_t)(t + 2) * kstep;
;             const char* a3 = a2 + kstepA; const char* b3 = b2 + kstep;
;             if (last && has_next) S.a_ready(nxt);
;             if constexpr (SP2) {
;             PG8_LDB(B0, 0, 0); PG8_LDB(B1, 0, 1); PG8_SCHED; PG8_LDA(At, 0, 0); PG8_STAGE(PG8_SA(1, 1), a1 + hstepA, voffA);
;             PG8_WAIT_V(8); PG8_WAIT_L(0); PG8_BAR; PG8_MMA(0, 0, At, B0); PG8_MMA(0, 1, At, B1); PG8_BAR; PG8_SCHED;
;             PG8_LDA(At, 0, 1); PG8_STAGE(PG8_SB(0, 0), b2, voffB); PG8_STAGE(PG8_SB(0, 1), b2 + hstep, voffB); PG8_STAGE(PG8_SA(0, 0), a2, voffA);
;             PG8_WAIT_V(8); PG8_WAIT_L(0); PG8_BAR; PG8_MMA(1, 0, At, B0); PG8_MMA(1, 1, At, B1); PG8_BAR; PG8_SCHED;
.LBB0_1068:
	ds_read_b128 v[150:153], v167
	ds_read_b128 v[156:159], v167 offset:1024
	ds_read_b128 v[160:163], v167 offset:2048
	ds_read_b128 v[176:179], v167 offset:3072
	ds_read_b128 v[180:183], v168
	ds_read_b128 v[184:187], v168 offset:1024
	ds_read_b128 v[188:191], v168 offset:2048
	ds_read_b128 v[192:195], v168 offset:3072
	s_add_u32 s34, s30, 0xfff50080
	s_addc_u32 s35, s31, -1
	s_cmp_eq_u32 s65, 40
	s_cselect_b32 s37, s13, s35
	s_cselect_b32 s36, s12, s34
	s_cselect_b32 s35, s29, s33
	s_cselect_b32 s34, s28, s5
	v_lshl_add_u64 v[164:165], s[30:31], 0, v[142:143]
	s_add_i32 m0, s39, 0xc000
	ds_read_b128 v[196:199], v169
	ds_read_b128 v[200:203], v169 offset:1024
	ds_read_b128 v[204:207], v169 offset:2048
	ds_read_b128 v[208:211], v169 offset:3072
	ds_read_b128 v[212:215], v169 offset:4096
	ds_read_b128 v[216:219], v169 offset:5120
	ds_read_b128 v[220:223], v169 offset:6144
	ds_read_b128 v[224:227], v169 offset:7168
	global_load_lds_dwordx4 v[164:165], off
	v_lshl_add_u64 v[164:165], s[30:31], 0, v[144:145]
	s_add_i32 m0, s39, 0xe000
	s_nop 0
	global_load_lds_dwordx4 v[164:165], off
	s_waitcnt vmcnt(8)
	s_waitcnt lgkmcnt(0)
	s_barrier
	s_setprio 1
	s_waitcnt lgkmcnt(0)
	v_mfma_f32_16x16x32_bf16 v[126:129], v[150:153], v[196:199], v[126:129]
	v_mfma_f32_16x16x32_bf16 v[122:125], v[160:163], v[196:199], v[122:125]
	v_mfma_f32_16x16x32_bf16 v[110:113], v[150:153], v[204:207], v[110:113]
	v_mfma_f32_16x16x32_bf16 v[106:109], v[160:163], v[204:207], v[106:109]
	v_mfma_f32_16x16x32_bf16 v[94:97], v[150:153], v[212:215], v[94:97]
	v_mfma_f32_16x16x32_bf16 v[90:93], v[160:163], v[212:215], v[90:93]
	v_mfma_f32_16x16x32_bf16 v[78:81], v[150:153], v[220:223], v[78:81]
	v_mfma_f32_16x16x32_bf16 v[74:77], v[160:163], v[220:223], v[74:77]
	v_mfma_f32_16x16x32_bf16 v[126:129], v[156:159], v[200:203], v[126:129]
	v_mfma_f32_16x16x32_bf16 v[122:125], v[176:179], v[200:203], v[122:125]
	v_mfma_f32_16x16x32_bf16 v[110:113], v[156:159], v[208:211], v[110:113]
	v_mfma_f32_16x16x32_bf16 v[106:109], v[176:179], v[208:211], v[106:109]
	v_mfma_f32_16x16x32_bf16 v[94:97], v[156:159], v[216:219], v[94:97]
	v_mfma_f32_16x16x32_bf16 v[90:93], v[176:179], v[216:219], v[90:93]
	v_mfma_f32_16x16x32_bf16 v[78:81], v[156:159], v[224:227], v[78:81]
	v_mfma_f32_16x16x32_bf16 v[74:77], v[176:179], v[224:227], v[74:77]
	s_setprio 0
	s_setprio 1
	v_mfma_f32_16x16x32_bf16 v[118:121], v[180:183], v[196:199], v[118:121]
	v_mfma_f32_16x16x32_bf16 v[114:117], v[188:191], v[196:199], v[114:117]
	v_mfma_f32_16x16x32_bf16 v[102:105], v[180:183], v[204:207], v[102:105]
	v_mfma_f32_16x16x32_bf16 v[98:101], v[188:191], v[204:207], v[98:101]
	v_mfma_f32_16x16x32_bf16 v[86:89], v[180:183], v[212:215], v[86:89]
	v_mfma_f32_16x16x32_bf16 v[82:85], v[188:191], v[212:215], v[82:85]
	v_mfma_f32_16x16x32_bf16 v[70:73], v[180:183], v[220:223], v[70:73]
	v_mfma_f32_16x16x32_bf16 v[66:69], v[188:191], v[220:223], v[66:69]
	v_mfma_f32_16x16x32_bf16 v[118:121], v[184:187], v[200:203], v[118:121]
	v_mfma_f32_16x16x32_bf16 v[114:117], v[192:195], v[200:203], v[114:117]
	v_mfma_f32_16x16x32_bf16 v[102:105], v[184:187], v[208:211], v[102:105]
	v_mfma_f32_16x16x32_bf16 v[98:101], v[192:195], v[208:211], v[98:101]
	v_mfma_f32_16x16x32_bf16 v[86:89], v[184:187], v[216:219], v[86:89]
	v_mfma_f32_16x16x32_bf16 v[82:85], v[192:195], v[216:219], v[82:85]
	v_mfma_f32_16x16x32_bf16 v[70:73], v[184:187], v[224:227], v[70:73]
	v_mfma_f32_16x16x32_bf16 v[66:69], v[192:195], v[224:227], v[66:69]
	s_setprio 0
	s_barrier
	s_add_i32 s66, s60, s38
	v_lshl_add_u64 v[164:165], s[34:35], 0, v[132:133]
	s_mov_b32 m0, s66
	ds_read_b128 v[196:199], v169 offset:16384
	ds_read_b128 v[200:203], v169 offset:17408
	ds_read_b128 v[204:207], v169 offset:18432
	ds_read_b128 v[208:211], v169 offset:19456
	ds_read_b128 v[212:215], v169 offset:20480
	ds_read_b128 v[216:219], v169 offset:21504
	ds_read_b128 v[220:223], v169 offset:22528
	ds_read_b128 v[224:227], v169 offset:23552
	global_load_lds_dwordx4 v[164:165], off
	s_add_i32 m0, s66, 0x2000
	s_add_u32 s66, s34, 0xb0000
	v_lshl_add_u64 v[228:229], s[34:35], 0, v[136:137]
	s_addc_u32 s67, s35, 0
	s_add_i32 s68, s61, s38
	global_load_lds_dwordx4 v[228:229], off
	v_lshl_add_u64 v[230:231], s[66:67], 0, v[132:133]
	s_mov_b32 m0, s68
	v_lshl_add_u64 v[232:233], s[36:37], 0, v[134:135]
	global_load_lds_dwordx4 v[230:231], off
	v_lshl_add_u64 v[230:231], s[66:67], 0, v[136:137]
	s_add_i32 m0, s68, 0x2000
	s_nop 0
	global_load_lds_dwordx4 v[230:231], off
	v_lshl_add_u64 v[230:231], s[36:37], 0, v[130:131]
	s_mov_b32 m0, s39
	s_nop 0
	global_load_lds_dwordx4 v[230:231], off
	s_mov_b32 m0, s40
	s_nop 0
	global_load_lds_dwordx4 v[232:233], off
	s_waitcnt vmcnt(8)
	s_waitcnt lgkmcnt(0)
	s_barrier
; #define PG8_STAGE(bufoff, gbase, voff) do { _Pragma("unroll") for (int _i = 0; _i < 2; ++_i) \
;         __builtin_amdgcn_global_load_lds((const unsigned*)((const char*)(gbase) + (voff)[_i]), (PG8_LAS unsigned*)(lds + (bufoff) + ldsw + _i * 8192), 16, 0, 0); } while (0)
; #define PG8_LDA(dst, b, h) do { _Pragma("unroll") for (int m = 0; m < 4; ++m) _Pragma("unroll") for (int k = 0; k < 2; ++k) dst[m][k] = *(const PG8_LAS bf16x8*)(lds + PG8_SA(b, h) + aoff + m * 2048 + k * 1024); } while (0)
; #define PG8_LDB(dst, b, h) do { _Pragma("unroll") for (int n = 0; n < 2; ++n) _Pragma("unroll") for (int k = 0; k < 2; ++k) dst[n][k] = *(const PG8_LAS bf16x8*)(lds + PG8_SB(b, h) + boff + n * 2048 + k * 1024); } while (0)
; #define PG8_MMA(ai, bj, At, Bt) do { __builtin_amdgcn_s_setprio(1); _Pragma("unroll") for (int m = 0; m < 4; ++m) _Pragma("unroll") for (int n = 0; n < 2; ++n) _Pragma("unroll") for (int k = 0; k < 2; ++k) \
;         acc[ai][bj][m][n] = __builtin_amdgcn_mfma_f32_16x16x32_bf16(Bt[n][k], At[m][k], acc[ai][bj][m][n], 0, 0, 0); __builtin_amdgcn_s_setprio(0); } while (0)
; #define PG8_WAIT_V(n) asm volatile("s_waitcnt vmcnt(" #n ")" ::: "memory")
; #define PG8_WAIT_L(n) asm volatile("s_waitcnt lgkmcnt(" #n ")" ::: "memory")
; #define PG8_BAR __builtin_amdgcn_s_barrier()
; #define PG8_SCHED __builtin_amdgcn_sched_barrier(0)
; template <class Epi, class Sched, bool ALIGN_EPI = false, bool SP2 = false, bool AGM = false  >
; __device__ __forceinline__ void gemm_phase(PG8_LAS unsigned char* lds, const Gemm g, const Sched& S, const Epi& E) {
;     ...
;             PG8_WAIT_V(8); PG8_WAIT_L(0); PG8_BAR; PG8_MMA(1, 0, At, B0); PG8_MMA(1, 1, At, B1); PG8_BAR; PG8_SCHED;
;             PG8_LDB(B0, 1, 0); PG8_LDB(B1, 1, 1); PG8_SCHED; PG8_LDA(At, 1, 0); PG8_STAGE(PG8_SA(0, 1), a2 + hstepA, voffA);
;             PG8_WAIT_V(8); PG8_WAIT_L(0); PG8_BAR; PG8_MMA(0, 0, At, B0); PG8_MMA(0, 1, At, B1); PG8_BAR; PG8_SCHED;
	s_setprio 1
	s_waitcnt lgkmcnt(0)
	v_mfma_f32_16x16x32_bf16 v[62:65], v[150:153], v[196:199], v[62:65]
	v_mfma_f32_16x16x32_bf16 v[58:61], v[160:163], v[196:199], v[58:61]
	v_mfma_f32_16x16x32_bf16 v[46:49], v[150:153], v[204:207], v[46:49]
	v_mfma_f32_16x16x32_bf16 v[42:45], v[160:163], v[204:207], v[42:45]
	v_mfma_f32_16x16x32_bf16 v[30:33], v[150:153], v[212:215], v[30:33]
	v_mfma_f32_16x16x32_bf16 v[26:29], v[160:163], v[212:215], v[26:29]
	v_mfma_f32_16x16x32_bf16 v[14:17], v[150:153], v[220:223], v[14:17]
	v_mfma_f32_16x16x32_bf16 v[10:13], v[160:163], v[220:223], v[10:13]
	v_mfma_f32_16x16x32_bf16 v[62:65], v[156:159], v[200:203], v[62:65]
	v_mfma_f32_16x16x32_bf16 v[58:61], v[176:179], v[200:203], v[58:61]
	v_mfma_f32_16x16x32_bf16 v[46:49], v[156:159], v[208:211], v[46:49]
	v_mfma_f32_16x16x32_bf16 v[42:45], v[176:179], v[208:211], v[42:45]
	v_mfma_f32_16x16x32_bf16 v[30:33], v[156:159], v[216:219], v[30:33]
	v_mfma_f32_16x16x32_bf16 v[26:29], v[176:179], v[216:219], v[26:29]
	v_mfma_f32_16x16x32_bf16 v[14:17], v[156:159], v[224:227], v[14:17]
	v_mfma_f32_16x16x32_bf16 v[10:13], v[176:179], v[224:227], v[10:13]
	s_setprio 0
	s_setprio 1
	v_mfma_f32_16x16x32_bf16 v[54:57], v[180:183], v[196:199], v[54:57]
	v_mfma_f32_16x16x32_bf16 v[50:53], v[188:191], v[196:199], v[50:53]
	v_mfma_f32_16x16x32_bf16 v[38:41], v[180:183], v[204:207], v[38:41]
	v_mfma_f32_16x16x32_bf16 v[34:37], v[188:191], v[204:207], v[34:37]
	v_mfma_f32_16x16x32_bf16 v[22:25], v[180:183], v[212:215], v[22:25]
	v_mfma_f32_16x16x32_bf16 v[18:21], v[188:191], v[212:215], v[18:21]
	v_mfma_f32_16x16x32_bf16 v[6:9], v[180:183], v[220:223], v[6:9]
	v_mfma_f32_16x16x32_bf16 v[2:5], v[188:191], v[220:223], v[2:5]
	v_mfma_f32_16x16x32_bf16 v[54:57], v[184:187], v[200:203], v[54:57]
	v_mfma_f32_16x16x32_bf16 v[50:53], v[192:195], v[200:203], v[50:53]
	v_mfma_f32_16x16x32_bf16 v[38:41], v[184:187], v[208:211], v[38:41]
	v_mfma_f32_16x16x32_bf16 v[34:37], v[192:195], v[208:211], v[34:37]
	v_mfma_f32_16x16x32_bf16 v[22:25], v[184:187], v[216:219], v[22:25]
	v_mfma_f32_16x16x32_bf16 v[18:21], v[192:195], v[216:219], v[18:21]
	v_mfma_f32_16x16x32_bf16 v[6:9], v[184:187], v[224:227], v[6:9]
	v_mfma_f32_16x16x32_bf16 v[2:5], v[192:195], v[224:227], v[2:5]
	s_setprio 0
	s_barrier
	s_add_i32 s66, 0, 0x18000
	s_add_i32 s67, 0, 0x1c000
	v_add_u32_e32 v176, s66, v1
	v_add_u32_e32 v192, s67, v1
	ds_read_b128 v[150:153], v176
	ds_read_b128 v[156:159], v176 offset:1024
	ds_read_b128 v[160:163], v176 offset:2048
	ds_read_b128 v[176:179], v176 offset:3072
	ds_read_b128 v[180:183], v192
	ds_read_b128 v[184:187], v192 offset:1024
	ds_read_b128 v[188:191], v192 offset:2048
	ds_read_b128 v[192:195], v192 offset:3072
	s_add_u32 s36, s36, 0xb0000
	s_addc_u32 s37, s37, 0
	s_mov_b32 m0, s41
	v_lshl_add_u64 v[234:235], s[36:37], 0, v[130:131]
	ds_read_b128 v[196:199], v169 offset:32768
	ds_read_b128 v[200:203], v169 offset:33792
	ds_read_b128 v[204:207], v169 offset:34816
	ds_read_b128 v[208:211], v169 offset:35840
	ds_read_b128 v[212:215], v169 offset:36864
	ds_read_b128 v[216:219], v169 offset:37888
	ds_read_b128 v[220:223], v169 offset:38912
	ds_read_b128 v[224:227], v169 offset:39936
	global_load_lds_dwordx4 v[234:235], off
	v_lshl_add_u64 v[234:235], s[36:37], 0, v[134:135]
	s_mov_b32 m0, s42
	s_nop 0
	global_load_lds_dwordx4 v[234:235], off
	s_waitcnt vmcnt(8)
	s_waitcnt lgkmcnt(0)
	s_barrier
	s_setprio 1
	s_waitcnt lgkmcnt(0)
	v_mfma_f32_16x16x32_bf16 v[126:129], v[150:153], v[196:199], v[126:129]
	v_mfma_f32_16x16x32_bf16 v[122:125], v[160:163], v[196:199], v[122:125]
	v_mfma_f32_16x16x32_bf16 v[110:113], v[150:153], v[204:207], v[110:113]
	v_mfma_f32_16x16x32_bf16 v[106:109], v[160:163], v[204:207], v[106:109]
	v_mfma_f32_16x16x32_bf16 v[94:97], v[150:153], v[212:215], v[94:97]
	v_mfma_f32_16x16x32_bf16 v[90:93], v[160:163], v[212:215], v[90:93]
	v_mfma_f32_16x16x32_bf16 v[78:81], v[150:153], v[220:223], v[78:81]
	v_mfma_f32_16x16x32_bf16 v[74:77], v[160:163], v[220:223], v[74:77]
	v_mfma_f32_16x16x32_bf16 v[126:129], v[156:159], v[200:203], v[126:129]
	v_mfma_f32_16x16x32_bf16 v[122:125], v[176:179], v[200:203], v[122:125]
	v_mfma_f32_16x16x32_bf16 v[110:113], v[156:159], v[208:211], v[110:113]
	v_mfma_f32_16x16x32_bf16 v[106:109], v[176:179], v[208:211], v[106:109]
	v_mfma_f32_16x16x32_bf16 v[94:97], v[156:159], v[216:219], v[94:97]
	v_mfma_f32_16x16x32_bf16 v[90:93], v[176:179], v[216:219], v[90:93]
	v_mfma_f32_16x16x32_bf16 v[78:81], v[156:159], v[224:227], v[78:81]
	v_mfma_f32_16x16x32_bf16 v[74:77], v[176:179], v[224:227], v[74:77]
	s_setprio 0
	s_setprio 1
	v_mfma_f32_16x16x32_bf16 v[118:121], v[180:183], v[196:199], v[118:121]
	v_mfma_f32_16x16x32_bf16 v[114:117], v[188:191], v[196:199], v[114:117]
	v_mfma_f32_16x16x32_bf16 v[102:105], v[180:183], v[204:207], v[102:105]
	v_mfma_f32_16x16x32_bf16 v[98:101], v[188:191], v[204:207], v[98:101]
	v_mfma_f32_16x16x32_bf16 v[86:89], v[180:183], v[212:215], v[86:89]
	v_mfma_f32_16x16x32_bf16 v[82:85], v[188:191], v[212:215], v[82:85]
	v_mfma_f32_16x16x32_bf16 v[70:73], v[180:183], v[220:223], v[70:73]
	v_mfma_f32_16x16x32_bf16 v[66:69], v[188:191], v[220:223], v[66:69]
	v_mfma_f32_16x16x32_bf16 v[118:121], v[184:187], v[200:203], v[118:121]
	v_mfma_f32_16x16x32_bf16 v[114:117], v[192:195], v[200:203], v[114:117]
	v_mfma_f32_16x16x32_bf16 v[102:105], v[184:187], v[208:211], v[102:105]
	v_mfma_f32_16x16x32_bf16 v[98:101], v[192:195], v[208:211], v[98:101]
	v_mfma_f32_16x16x32_bf16 v[86:89], v[184:187], v[216:219], v[86:89]
	v_mfma_f32_16x16x32_bf16 v[82:85], v[192:195], v[216:219], v[82:85]
	v_mfma_f32_16x16x32_bf16 v[70:73], v[184:187], v[224:227], v[70:73]
	v_mfma_f32_16x16x32_bf16 v[66:69], v[192:195], v[224:227], v[66:69]
	s_setprio 0
	s_barrier
; #define PG8_STAGE(bufoff, gbase, voff) do { _Pragma("unroll") for (int _i = 0; _i < 2; ++_i) \
;         __builtin_amdgcn_global_load_lds((const unsigned*)((const char*)(gbase) + (voff)[_i]), (PG8_LAS unsigned*)(lds + (bufoff) + ldsw + _i * 8192), 16, 0, 0); } while (0)
; #define PG8_LDA(dst, b, h) do { _Pragma("unroll") for (int m = 0; m < 4; ++m) _Pragma("unroll") for (int k = 0; k < 2; ++k) dst[m][k] = *(const PG8_LAS bf16x8*)(lds + PG8_SA(b, h) + aoff + m * 2048 + k * 1024); } while (0)
; #define PG8_MMA(ai, bj, At, Bt) do { __builtin_amdgcn_s_setprio(1); _Pragma("unroll") for (int m = 0; m < 4; ++m) _Pragma("unroll") for (int n = 0; n < 2; ++n) _Pragma("unroll") for (int k = 0; k < 2; ++k) \
;         acc[ai][bj][m][n] = __builtin_amdgcn_mfma_f32_16x16x32_bf16(Bt[n][k], At[m][k], acc[ai][bj][m][n], 0, 0, 0); __builtin_amdgcn_s_setprio(0); } while (0)
; #define PG8_WAIT_V(n) asm volatile("s_waitcnt vmcnt(" #n ")" ::: "memory")
; #define PG8_WAIT_L(n) asm volatile("s_waitcnt lgkmcnt(" #n ")" ::: "memory")
; #define PG8_BAR __builtin_amdgcn_s_barrier()
; #define PG8_SCHED __builtin_amdgcn_sched_barrier(0)
; template <class Epi, class Sched, bool ALIGN_EPI = false, bool SP2 = false, bool AGM = false  >
; __device__ __forceinline__ void gemm_phase(PG8_LAS unsigned char* lds, const Gemm g, const Sched& S, const Epi& E) {
;     ...
;             PG8_LDA(At, 1, 1); PG8_STAGE(PG8_SB(1, 0), b3, voffB); PG8_STAGE(PG8_SB(1, 1), b3 + hstep, voffB); PG8_STAGE(PG8_SA(1, 0), a3, voffA);
;             PG8_WAIT_V(8); PG8_WAIT_L(0); PG8_BAR; PG8_MMA(1, 0, At, B0); PG8_MMA(1, 1, At, B1); PG8_BAR; PG8_SCHED;
;     ...
;         if constexpr (ALIGN_EPI) { if (wr == 0) PG8_BAR; }
	s_add_i32 s36, s66, s38
	v_lshl_add_u64 v[164:165], v[164:165], 0, s[24:25]
	s_mov_b32 m0, s36
	ds_read_b128 v[196:199], v169 offset:49152
	ds_read_b128 v[200:203], v169 offset:50176
	ds_read_b128 v[204:207], v169 offset:51200
	ds_read_b128 v[208:211], v169 offset:52224
	ds_read_b128 v[212:215], v169 offset:53248
	ds_read_b128 v[216:219], v169 offset:54272
	ds_read_b128 v[220:223], v169 offset:55296
	ds_read_b128 v[224:227], v169 offset:56320
	global_load_lds_dwordx4 v[164:165], off
	s_add_i32 m0, s36, 0x2000
	s_add_u32 s34, s34, 0xb0080
	v_lshl_add_u64 v[164:165], v[228:229], 0, s[24:25]
	s_addc_u32 s35, s35, 0
	s_add_i32 s36, s67, s38
	global_load_lds_dwordx4 v[164:165], off
	v_lshl_add_u64 v[164:165], s[34:35], 0, v[132:133]
	s_mov_b32 m0, s36
	s_nop 0
	global_load_lds_dwordx4 v[164:165], off
	v_lshl_add_u64 v[164:165], s[34:35], 0, v[136:137]
	s_add_i32 m0, s36, 0x2000
	s_nop 0
	global_load_lds_dwordx4 v[164:165], off
	v_lshl_add_u64 v[164:165], v[230:231], 0, s[24:25]
	s_mov_b32 m0, s55
	s_nop 0
	global_load_lds_dwordx4 v[164:165], off
	v_lshl_add_u64 v[164:165], v[232:233], 0, s[24:25]
	s_mov_b32 m0, s58
	s_nop 0
	global_load_lds_dwordx4 v[164:165], off
	s_waitcnt vmcnt(8)
	s_waitcnt lgkmcnt(0)
	s_barrier
	s_setprio 1
	s_waitcnt lgkmcnt(0)
	v_mfma_f32_16x16x32_bf16 v[62:65], v[150:153], v[196:199], v[62:65]
	v_mfma_f32_16x16x32_bf16 v[58:61], v[160:163], v[196:199], v[58:61]
	v_mfma_f32_16x16x32_bf16 v[46:49], v[150:153], v[204:207], v[46:49]
	v_mfma_f32_16x16x32_bf16 v[42:45], v[160:163], v[204:207], v[42:45]
	v_mfma_f32_16x16x32_bf16 v[30:33], v[150:153], v[212:215], v[30:33]
	v_mfma_f32_16x16x32_bf16 v[26:29], v[160:163], v[212:215], v[26:29]
	v_mfma_f32_16x16x32_bf16 v[14:17], v[150:153], v[220:223], v[14:17]
	v_mfma_f32_16x16x32_bf16 v[10:13], v[160:163], v[220:223], v[10:13]
	v_mfma_f32_16x16x32_bf16 v[62:65], v[156:159], v[200:203], v[62:65]
	v_mfma_f32_16x16x32_bf16 v[58:61], v[176:179], v[200:203], v[58:61]
	v_mfma_f32_16x16x32_bf16 v[46:49], v[156:159], v[208:211], v[46:49]
	v_mfma_f32_16x16x32_bf16 v[42:45], v[176:179], v[208:211], v[42:45]
	v_mfma_f32_16x16x32_bf16 v[30:33], v[156:159], v[216:219], v[30:33]
	v_mfma_f32_16x16x32_bf16 v[26:29], v[176:179], v[216:219], v[26:29]
	v_mfma_f32_16x16x32_bf16 v[14:17], v[156:159], v[224:227], v[14:17]
	v_mfma_f32_16x16x32_bf16 v[10:13], v[176:179], v[224:227], v[10:13]
	s_setprio 0
	s_setprio 1
	v_mfma_f32_16x16x32_bf16 v[54:57], v[180:183], v[196:199], v[54:57]
	v_mfma_f32_16x16x32_bf16 v[50:53], v[188:191], v[196:199], v[50:53]
	v_mfma_f32_16x16x32_bf16 v[38:41], v[180:183], v[204:207], v[38:41]
	v_mfma_f32_16x16x32_bf16 v[34:37], v[188:191], v[204:207], v[34:37]
	v_mfma_f32_16x16x32_bf16 v[22:25], v[180:183], v[212:215], v[22:25]
	v_mfma_f32_16x16x32_bf16 v[18:21], v[188:191], v[212:215], v[18:21]
	v_mfma_f32_16x16x32_bf16 v[6:9], v[180:183], v[220:223], v[6:9]
	v_mfma_f32_16x16x32_bf16 v[2:5], v[188:191], v[220:223], v[2:5]
	v_mfma_f32_16x16x32_bf16 v[54:57], v[184:187], v[200:203], v[54:57]
	v_mfma_f32_16x16x32_bf16 v[50:53], v[192:195], v[200:203], v[50:53]
	v_mfma_f32_16x16x32_bf16 v[38:41], v[184:187], v[208:211], v[38:41]
	v_mfma_f32_16x16x32_bf16 v[34:37], v[192:195], v[208:211], v[34:37]
	v_mfma_f32_16x16x32_bf16 v[22:25], v[184:187], v[216:219], v[22:25]
	v_mfma_f32_16x16x32_bf16 v[18:21], v[192:195], v[216:219], v[18:21]
	v_mfma_f32_16x16x32_bf16 v[6:9], v[184:187], v[224:227], v[6:9]
	v_mfma_f32_16x16x32_bf16 v[2:5], v[192:195], v[224:227], v[2:5]
	s_add_i32 s65, s65, 2
	s_add_u32 s30, s30, 0x100
	s_addc_u32 s31, s31, 0
	s_add_u32 s5, s5, 0x100
	s_addc_u32 s33, s33, 0
	s_cmp_gt_u32 s65, 41
	s_setprio 0
	s_barrier
	s_cbranch_scc0 .LBB0_1068
	s_and_b64 vcc, exec, s[26:27]
	s_cbranch_vccz .LBB0_1071
	s_barrier
